# K-loop SP1 load segments: the two LDS-DMA loads issued first (sgpr-base form), before the 16 ds_reads
# baseline (speedup 1.0000x reference)
; #define PG8_STAGE(bufoff, gbase, voff) do { _Pragma("unroll") for (int _i = 0; _i < 2; ++_i) \
;         __builtin_amdgcn_global_load_lds((const unsigned*)((const char*)(gbase) + (voff)[_i]), (LAS unsigned*)(lds + (bufoff) + ldsw + _i * 8192), 16, 0, 0); } while (0)
; #define PG8_LDA(dst, b, h) do { _Pragma("unroll") for (int m = 0; m < 4; ++m) _Pragma("unroll") for (int k = 0; k < 2; ++k) dst[m][k] = *(const LAS bf16x8*)(lds + PG8_SA(b, h) + aoff + m * 2048 + k * 1024); } while (0)
; #define PG8_LDB(dst, b, h) do { _Pragma("unroll") for (int n = 0; n < 2; ++n) _Pragma("unroll") for (int k = 0; k < 2; ++k) dst[n][k] = *(const LAS bf16x8*)(lds + PG8_SB(b, h) + boff + n * 2048 + k * 1024); } while (0)
; #define PG8_MMA(ai, bj, At, Bt) do { __builtin_amdgcn_s_setprio(1); _Pragma("unroll") for (int m = 0; m < 4; ++m) _Pragma("unroll") for (int n = 0; n < 2; ++n) _Pragma("unroll") for (int k = 0; k < 2; ++k) \
;         acc[ai][bj][m][n] = __builtin_amdgcn_mfma_f32_16x16x32_bf16(Bt[n][k], At[m][k], acc[ai][bj][m][n], 0, 0, 0); __builtin_amdgcn_s_setprio(0); } while (0)
; #define PG8_WAIT_V(n) asm volatile("s_waitcnt vmcnt(" #n ")" ::: "memory")
; #define PG8_WAIT_L(n) asm volatile("s_waitcnt lgkmcnt(" #n ")" ::: "memory")
; #define PG8_BAR __builtin_amdgcn_s_barrier()
; #define PG8_SCHED __builtin_amdgcn_sched_barrier(0)
; template <class Epi>
; __device__ __forceinline__ void gemm_phase(LAS unsigned char* lds, const Gemm g, const StaticOrder& S, const Epi& E, const int tid) {
;     ...
;             PG8_LDB(B0, 0, 0); PG8_LDB(B1, 0, 1); PG8_SCHED; PG8_LDA(At, 0, 0); PG8_STAGE(PG8_SA(1, 1), a1 + hstep, voffA);
;             PG8_WAIT_V(8); PG8_WAIT_L(0); PG8_BAR; PG8_MMA(0, 0, At, B0); PG8_MMA(0, 1, At, B1); PG8_BAR; PG8_SCHED;
;             PG8_LDA(At, 0, 1); PG8_STAGE(PG8_SB(0, 0), b2, voffB); PG8_STAGE(PG8_SB(0, 1), b2 + bhs, voffB); PG8_STAGE(PG8_SA(0, 0), a2, voffA);
;             PG8_WAIT_V(8); PG8_WAIT_L(0); PG8_BAR; PG8_MMA(1, 0, At, B0); PG8_MMA(1, 1, At, B1); PG8_BAR; PG8_SCHED;
.LBB0_126:
	s_add_i32 m0, s37, 0xc000
	s_nop 0
	global_load_lds_dwordx4 v180, s[28:29]
	s_add_i32 m0, s37, 0xe000
	s_nop 0
	global_load_lds_dwordx4 v178, s[28:29]
	s_add_u32 s30, s28, 0xffe00080
	s_addc_u32 s31, s29, -1
	s_add_i32 s52, 0, 0x10000
	s_cmpk_eq_i32 s51, 0x7c
	s_cselect_b32 s35, s17, s31
	s_cselect_b32 s34, s27, s30
	s_cselect_b32 s31, s15, s50
	s_cselect_b32 s30, s33, s49
	s_add_i32 s54, 0, 0x14000
	v_add_u32_e32 v30, s52, v193
	v_add_u32_e32 v54, s54, v193
	ds_read_b128 v[18:21], v30
	ds_read_b128 v[22:25], v30 offset:1024
	ds_read_b128 v[26:29], v30 offset:2048
	ds_read_b128 v[30:33], v30 offset:3072
	ds_read_b128 v[42:45], v54
	ds_read_b128 v[46:49], v54 offset:1024
	ds_read_b128 v[50:53], v54 offset:2048
	ds_read_b128 v[54:57], v54 offset:3072
	ds_read_b128 v[182:185], v199
	ds_read_b128 v[186:189], v199 offset:1024
	ds_read_b128 v[212:215], v199 offset:2048
	ds_read_b128 v[216:219], v199 offset:3072
	ds_read_b128 v[220:223], v199 offset:4096
	ds_read_b128 v[224:227], v199 offset:5120
	ds_read_b128 v[228:231], v199 offset:6144
	ds_read_b128 v[232:235], v199 offset:7168
	s_waitcnt vmcnt(8)
	s_waitcnt lgkmcnt(0)
	s_barrier
	s_setprio 1
	s_waitcnt lgkmcnt(0)
	v_mfma_f32_16x16x32_bf16 v[158:161], v[18:21], v[182:185], v[158:161]
	v_mfma_f32_16x16x32_bf16 v[154:157], v[26:29], v[182:185], v[154:157]
	v_mfma_f32_16x16x32_bf16 v[142:145], v[18:21], v[212:215], v[142:145]
	v_mfma_f32_16x16x32_bf16 v[138:141], v[26:29], v[212:215], v[138:141]
	v_mfma_f32_16x16x32_bf16 v[126:129], v[18:21], v[220:223], v[126:129]
	v_mfma_f32_16x16x32_bf16 v[122:125], v[26:29], v[220:223], v[122:125]
	v_mfma_f32_16x16x32_bf16 v[110:113], v[18:21], v[228:231], v[110:113]
	v_mfma_f32_16x16x32_bf16 v[106:109], v[26:29], v[228:231], v[106:109]
	v_mfma_f32_16x16x32_bf16 v[158:161], v[22:25], v[186:189], v[158:161]
	v_mfma_f32_16x16x32_bf16 v[154:157], v[30:33], v[186:189], v[154:157]
	v_mfma_f32_16x16x32_bf16 v[142:145], v[22:25], v[216:219], v[142:145]
	v_mfma_f32_16x16x32_bf16 v[138:141], v[30:33], v[216:219], v[138:141]
	v_mfma_f32_16x16x32_bf16 v[126:129], v[22:25], v[224:227], v[126:129]
	v_mfma_f32_16x16x32_bf16 v[122:125], v[30:33], v[224:227], v[122:125]
	v_mfma_f32_16x16x32_bf16 v[110:113], v[22:25], v[232:235], v[110:113]
	v_mfma_f32_16x16x32_bf16 v[106:109], v[30:33], v[232:235], v[106:109]
	s_setprio 0
	s_setprio 1
	v_mfma_f32_16x16x32_bf16 v[150:153], v[42:45], v[182:185], v[150:153]
	v_mfma_f32_16x16x32_bf16 v[146:149], v[50:53], v[182:185], v[146:149]
	v_mfma_f32_16x16x32_bf16 v[134:137], v[42:45], v[212:215], v[134:137]
	v_mfma_f32_16x16x32_bf16 v[130:133], v[50:53], v[212:215], v[130:133]
	v_mfma_f32_16x16x32_bf16 v[118:121], v[42:45], v[220:223], v[118:121]
	v_mfma_f32_16x16x32_bf16 v[114:117], v[50:53], v[220:223], v[114:117]
	v_mfma_f32_16x16x32_bf16 v[102:105], v[42:45], v[228:231], v[102:105]
	v_mfma_f32_16x16x32_bf16 v[98:101], v[50:53], v[228:231], v[98:101]
	v_mfma_f32_16x16x32_bf16 v[150:153], v[46:49], v[186:189], v[150:153]
	v_mfma_f32_16x16x32_bf16 v[146:149], v[54:57], v[186:189], v[146:149]
	v_mfma_f32_16x16x32_bf16 v[134:137], v[46:49], v[216:219], v[134:137]
	v_mfma_f32_16x16x32_bf16 v[130:133], v[54:57], v[216:219], v[130:133]
	v_mfma_f32_16x16x32_bf16 v[118:121], v[46:49], v[224:227], v[118:121]
	v_mfma_f32_16x16x32_bf16 v[114:117], v[54:57], v[224:227], v[114:117]
	v_mfma_f32_16x16x32_bf16 v[102:105], v[46:49], v[232:235], v[102:105]
	v_mfma_f32_16x16x32_bf16 v[98:101], v[54:57], v[232:235], v[98:101]
	s_setprio 0
	s_barrier
	s_add_i32 s52, s52, s36
	v_lshl_add_u64 v[172:173], s[30:31], 0, v[0:1]
	s_mov_b32 m0, s52
	ds_read_b128 v[182:185], v199 offset:16384
	global_load_lds_dwordx4 v[172:173], off
	ds_read_b128 v[186:189], v199 offset:17408
	ds_read_b128 v[212:215], v199 offset:18432
	s_add_i32 m0, s52, 0x2000
	s_add_u32 s52, s30, 0x20000
	v_lshl_add_u64 v[174:175], s[30:31], 0, v[166:167]
	s_addc_u32 s53, s31, 0
	s_add_i32 s54, s54, s36
	global_load_lds_dwordx4 v[174:175], off
	ds_read_b128 v[216:219], v199 offset:19456
	ds_read_b128 v[220:223], v199 offset:20480
	v_lshl_add_u64 v[176:177], s[52:53], 0, v[0:1]
	s_mov_b32 m0, s54
	v_lshl_add_u64 v[200:201], s[34:35], 0, v[164:165]
	global_load_lds_dwordx4 v[176:177], off
	ds_read_b128 v[224:227], v199 offset:21504
	ds_read_b128 v[228:231], v199 offset:22528
	v_lshl_add_u64 v[176:177], s[52:53], 0, v[166:167]
	s_add_i32 m0, s54, 0x2000
	s_nop 0
	global_load_lds_dwordx4 v[176:177], off
	ds_read_b128 v[232:235], v199 offset:23552
	v_lshl_add_u64 v[176:177], s[34:35], 0, v[162:163]
	s_mov_b32 m0, s37
	s_nop 0
	global_load_lds_dwordx4 v[176:177], off
	s_mov_b32 m0, s38
	s_nop 0
	global_load_lds_dwordx4 v[200:201], off
	s_waitcnt vmcnt(8)
	s_waitcnt lgkmcnt(0)
	s_barrier
; #define PG8_STAGE(bufoff, gbase, voff) do { _Pragma("unroll") for (int _i = 0; _i < 2; ++_i) \
;         __builtin_amdgcn_global_load_lds((const unsigned*)((const char*)(gbase) + (voff)[_i]), (LAS unsigned*)(lds + (bufoff) + ldsw + _i * 8192), 16, 0, 0); } while (0)
; #define PG8_LDA(dst, b, h) do { _Pragma("unroll") for (int m = 0; m < 4; ++m) _Pragma("unroll") for (int k = 0; k < 2; ++k) dst[m][k] = *(const LAS bf16x8*)(lds + PG8_SA(b, h) + aoff + m * 2048 + k * 1024); } while (0)
; #define PG8_LDB(dst, b, h) do { _Pragma("unroll") for (int n = 0; n < 2; ++n) _Pragma("unroll") for (int k = 0; k < 2; ++k) dst[n][k] = *(const LAS bf16x8*)(lds + PG8_SB(b, h) + boff + n * 2048 + k * 1024); } while (0)
; #define PG8_MMA(ai, bj, At, Bt) do { __builtin_amdgcn_s_setprio(1); _Pragma("unroll") for (int m = 0; m < 4; ++m) _Pragma("unroll") for (int n = 0; n < 2; ++n) _Pragma("unroll") for (int k = 0; k < 2; ++k) \
;         acc[ai][bj][m][n] = __builtin_amdgcn_mfma_f32_16x16x32_bf16(Bt[n][k], At[m][k], acc[ai][bj][m][n], 0, 0, 0); __builtin_amdgcn_s_setprio(0); } while (0)
; #define PG8_WAIT_V(n) asm volatile("s_waitcnt vmcnt(" #n ")" ::: "memory")
; #define PG8_WAIT_L(n) asm volatile("s_waitcnt lgkmcnt(" #n ")" ::: "memory")
; #define PG8_BAR __builtin_amdgcn_s_barrier()
; #define PG8_SCHED __builtin_amdgcn_sched_barrier(0)
; template <class Epi>
; __device__ __forceinline__ void gemm_phase(LAS unsigned char* lds, const Gemm g, const StaticOrder& S, const Epi& E, const int tid) {
;     ...
;             PG8_WAIT_V(8); PG8_WAIT_L(0); PG8_BAR; PG8_MMA(1, 0, At, B0); PG8_MMA(1, 1, At, B1); PG8_BAR; PG8_SCHED;
;             PG8_LDB(B0, 1, 0); PG8_LDB(B1, 1, 1); PG8_SCHED; PG8_LDA(At, 1, 0); PG8_STAGE(PG8_SA(0, 1), a2 + hstep, voffA);
;             PG8_WAIT_V(8); PG8_WAIT_L(0); PG8_BAR; PG8_MMA(0, 0, At, B0); PG8_MMA(0, 1, At, B1); PG8_BAR; PG8_SCHED;
	s_setprio 1
	s_waitcnt lgkmcnt(0)
	v_mfma_f32_16x16x32_bf16 v[94:97], v[18:21], v[182:185], v[94:97]
	v_mfma_f32_16x16x32_bf16 v[90:93], v[26:29], v[182:185], v[90:93]
	v_mfma_f32_16x16x32_bf16 v[78:81], v[18:21], v[212:215], v[78:81]
	v_mfma_f32_16x16x32_bf16 v[74:77], v[26:29], v[212:215], v[74:77]
	v_mfma_f32_16x16x32_bf16 v[62:65], v[18:21], v[220:223], v[62:65]
	v_mfma_f32_16x16x32_bf16 v[58:61], v[26:29], v[220:223], v[58:61]
	v_mfma_f32_16x16x32_bf16 v[14:17], v[18:21], v[228:231], v[14:17]
	v_mfma_f32_16x16x32_bf16 v[10:13], v[26:29], v[228:231], v[10:13]
	v_mfma_f32_16x16x32_bf16 v[94:97], v[22:25], v[186:189], v[94:97]
	v_mfma_f32_16x16x32_bf16 v[90:93], v[30:33], v[186:189], v[90:93]
	v_mfma_f32_16x16x32_bf16 v[78:81], v[22:25], v[216:219], v[78:81]
	v_mfma_f32_16x16x32_bf16 v[74:77], v[30:33], v[216:219], v[74:77]
	v_mfma_f32_16x16x32_bf16 v[62:65], v[22:25], v[224:227], v[62:65]
	v_mfma_f32_16x16x32_bf16 v[58:61], v[30:33], v[224:227], v[58:61]
	v_mfma_f32_16x16x32_bf16 v[14:17], v[22:25], v[232:235], v[14:17]
	v_mfma_f32_16x16x32_bf16 v[10:13], v[30:33], v[232:235], v[10:13]
	s_setprio 0
	s_setprio 1
	v_mfma_f32_16x16x32_bf16 v[38:41], v[42:45], v[220:223], v[38:41]
	v_mfma_f32_16x16x32_bf16 v[34:37], v[50:53], v[220:223], v[34:37]
	v_mfma_f32_16x16x32_bf16 v[6:9], v[42:45], v[228:231], v[6:9]
	v_mfma_f32_16x16x32_bf16 v[2:5], v[50:53], v[228:231], v[2:5]
	v_mfma_f32_16x16x32_bf16 v[18:21], v[42:45], v[182:185], v[86:89]
	v_mfma_f32_16x16x32_bf16 v[22:25], v[50:53], v[182:185], v[82:85]
	v_mfma_f32_16x16x32_bf16 v[26:29], v[42:45], v[212:215], v[70:73]
	v_mfma_f32_16x16x32_bf16 v[30:33], v[50:53], v[212:215], v[66:69]
	v_mfma_f32_16x16x32_bf16 v[38:41], v[46:49], v[224:227], v[38:41]
	v_mfma_f32_16x16x32_bf16 v[34:37], v[54:57], v[224:227], v[34:37]
	v_mfma_f32_16x16x32_bf16 v[6:9], v[46:49], v[232:235], v[6:9]
	v_mfma_f32_16x16x32_bf16 v[2:5], v[54:57], v[232:235], v[2:5]
	v_mfma_f32_16x16x32_bf16 v[18:21], v[46:49], v[186:189], v[18:21]
	v_mfma_f32_16x16x32_bf16 v[22:25], v[54:57], v[186:189], v[22:25]
	v_mfma_f32_16x16x32_bf16 v[26:29], v[46:49], v[216:219], v[26:29]
	v_mfma_f32_16x16x32_bf16 v[30:33], v[54:57], v[216:219], v[30:33]
	s_setprio 0
	s_barrier
	s_add_u32 s34, s34, 0x200000
	s_addc_u32 s35, s35, 0
	s_mov_b32 m0, s39
	s_nop 0
	global_load_lds_dwordx4 v162, s[34:35]
	s_mov_b32 m0, s44
	s_nop 0
	global_load_lds_dwordx4 v164, s[34:35]
	s_add_i32 s52, 0, 0x18000
	s_add_i32 s53, 0, 0x1c000
	v_add_u32_e32 v54, s52, v193
	v_add_u32_e32 v66, s53, v193
	ds_read_b128 v[42:45], v54
	ds_read_b128 v[46:49], v54 offset:1024
	ds_read_b128 v[50:53], v54 offset:2048
	ds_read_b128 v[54:57], v54 offset:3072
	ds_read_b128 v[182:185], v66
	ds_read_b128 v[186:189], v66 offset:1024
	ds_read_b128 v[212:215], v66 offset:2048
	ds_read_b128 v[216:219], v66 offset:3072
	ds_read_b128 v[66:69], v199 offset:32768
	ds_read_b128 v[70:73], v199 offset:33792
	ds_read_b128 v[82:85], v199 offset:34816
	ds_read_b128 v[86:89], v199 offset:35840
	ds_read_b128 v[220:223], v199 offset:36864
	ds_read_b128 v[224:227], v199 offset:37888
	ds_read_b128 v[228:231], v199 offset:38912
	ds_read_b128 v[232:235], v199 offset:39936
	s_waitcnt vmcnt(8)
	s_waitcnt lgkmcnt(0)
	s_barrier
	s_setprio 1
	s_waitcnt lgkmcnt(0)
	v_mfma_f32_16x16x32_bf16 v[158:161], v[42:45], v[66:69], v[158:161]
	v_mfma_f32_16x16x32_bf16 v[154:157], v[50:53], v[66:69], v[154:157]
	v_mfma_f32_16x16x32_bf16 v[142:145], v[42:45], v[82:85], v[142:145]
	v_mfma_f32_16x16x32_bf16 v[138:141], v[50:53], v[82:85], v[138:141]
	v_mfma_f32_16x16x32_bf16 v[126:129], v[42:45], v[220:223], v[126:129]
	v_mfma_f32_16x16x32_bf16 v[122:125], v[50:53], v[220:223], v[122:125]
	v_mfma_f32_16x16x32_bf16 v[110:113], v[42:45], v[228:231], v[110:113]
	v_mfma_f32_16x16x32_bf16 v[106:109], v[50:53], v[228:231], v[106:109]
	v_mfma_f32_16x16x32_bf16 v[158:161], v[46:49], v[70:73], v[158:161]
	v_mfma_f32_16x16x32_bf16 v[154:157], v[54:57], v[70:73], v[154:157]
	v_mfma_f32_16x16x32_bf16 v[142:145], v[46:49], v[86:89], v[142:145]
	v_mfma_f32_16x16x32_bf16 v[138:141], v[54:57], v[86:89], v[138:141]
	v_mfma_f32_16x16x32_bf16 v[126:129], v[46:49], v[224:227], v[126:129]
	v_mfma_f32_16x16x32_bf16 v[122:125], v[54:57], v[224:227], v[122:125]
	v_mfma_f32_16x16x32_bf16 v[110:113], v[46:49], v[232:235], v[110:113]
	v_mfma_f32_16x16x32_bf16 v[106:109], v[54:57], v[232:235], v[106:109]
	s_setprio 0
	s_setprio 1
	v_mfma_f32_16x16x32_bf16 v[150:153], v[182:185], v[66:69], v[150:153]
	v_mfma_f32_16x16x32_bf16 v[66:69], v[212:215], v[66:69], v[146:149]
	v_mfma_f32_16x16x32_bf16 v[146:149], v[216:219], v[70:73], v[66:69]
	v_mfma_f32_16x16x32_bf16 v[66:69], v[182:185], v[82:85], v[134:137]
	v_mfma_f32_16x16x32_bf16 v[134:137], v[186:189], v[86:89], v[66:69]
	v_mfma_f32_16x16x32_bf16 v[66:69], v[212:215], v[82:85], v[130:133]
	v_mfma_f32_16x16x32_bf16 v[130:133], v[216:219], v[86:89], v[66:69]
	v_mfma_f32_16x16x32_bf16 v[66:69], v[182:185], v[220:223], v[118:121]
	v_mfma_f32_16x16x32_bf16 v[118:121], v[186:189], v[224:227], v[66:69]
	v_mfma_f32_16x16x32_bf16 v[66:69], v[212:215], v[220:223], v[114:117]
	v_mfma_f32_16x16x32_bf16 v[114:117], v[216:219], v[224:227], v[66:69]
	v_mfma_f32_16x16x32_bf16 v[66:69], v[182:185], v[228:231], v[102:105]
	v_mfma_f32_16x16x32_bf16 v[102:105], v[186:189], v[232:235], v[66:69]
	v_mfma_f32_16x16x32_bf16 v[66:69], v[212:215], v[228:231], v[98:101]
	v_mfma_f32_16x16x32_bf16 v[150:153], v[186:189], v[70:73], v[150:153]
	v_mfma_f32_16x16x32_bf16 v[98:101], v[216:219], v[232:235], v[66:69]
	s_setprio 0
	s_barrier
; #define PG8_STAGE(bufoff, gbase, voff) do { _Pragma("unroll") for (int _i = 0; _i < 2; ++_i) \
;         __builtin_amdgcn_global_load_lds((const unsigned*)((const char*)(gbase) + (voff)[_i]), (LAS unsigned*)(lds + (bufoff) + ldsw + _i * 8192), 16, 0, 0); } while (0)
; #define PG8_LDA(dst, b, h) do { _Pragma("unroll") for (int m = 0; m < 4; ++m) _Pragma("unroll") for (int k = 0; k < 2; ++k) dst[m][k] = *(const LAS bf16x8*)(lds + PG8_SA(b, h) + aoff + m * 2048 + k * 1024); } while (0)
; #define PG8_MMA(ai, bj, At, Bt) do { __builtin_amdgcn_s_setprio(1); _Pragma("unroll") for (int m = 0; m < 4; ++m) _Pragma("unroll") for (int n = 0; n < 2; ++n) _Pragma("unroll") for (int k = 0; k < 2; ++k) \
;         acc[ai][bj][m][n] = __builtin_amdgcn_mfma_f32_16x16x32_bf16(Bt[n][k], At[m][k], acc[ai][bj][m][n], 0, 0, 0); __builtin_amdgcn_s_setprio(0); } while (0)
; #define PG8_WAIT_V(n) asm volatile("s_waitcnt vmcnt(" #n ")" ::: "memory")
; #define PG8_WAIT_L(n) asm volatile("s_waitcnt lgkmcnt(" #n ")" ::: "memory")
; #define PG8_BAR __builtin_amdgcn_s_barrier()
; #define PG8_SCHED __builtin_amdgcn_sched_barrier(0)
; template <class Epi>
; __device__ __forceinline__ void gemm_phase(LAS unsigned char* lds, const Gemm g, const StaticOrder& S, const Epi& E, const int tid) {
;     ...
;             const char* a1 = (s1 ? cA2 + (size_t)(t - nt + 1) * kstep : cA + (size_t)(t + 1) * kstep);
;             const char* a2 = last ? nA : (s2 ? cA2 + (size_t)(t + 2 - nt) * kstep : cA + (size_t)(t + 2) * kstep);
;             const char* b2 = last ? nB : (s2 ? cB2 + (size_t)(t + 2 - nt) * kstep : cB + (size_t)(t + 2) * kstep);
;             const char* a3 = a2 + kstep; const char* b3 = b2 + kstep;
;     ...
;             PG8_LDA(At, 1, 1); PG8_STAGE(PG8_SB(1, 0), b3, voffB); PG8_STAGE(PG8_SB(1, 1), b3 + bhs, voffB); PG8_STAGE(PG8_SA(1, 0), a3, voffA);
;             PG8_WAIT_V(8); PG8_WAIT_L(0); PG8_BAR; PG8_MMA(1, 0, At, B0); PG8_MMA(1, 1, At, B1); PG8_BAR; PG8_SCHED;
	s_add_i32 s34, s52, s36
	v_lshl_add_u64 v[82:83], v[172:173], 0, s[70:71]
	s_mov_b32 m0, s34
	s_nop 0
	ds_read_b128 v[66:69], v199 offset:49152
	global_load_lds_dwordx4 v[82:83], off
	ds_read_b128 v[70:73], v199 offset:50176
	ds_read_b128 v[220:223], v199 offset:51200
	s_add_i32 m0, s34, 0x2000
	s_add_u32 s30, s30, 0x20080
	v_lshl_add_u64 v[82:83], v[174:175], 0, s[70:71]
	s_addc_u32 s31, s31, 0
	s_add_i32 s34, s53, s36
	global_load_lds_dwordx4 v[82:83], off
	ds_read_b128 v[224:227], v199 offset:52224
	ds_read_b128 v[228:231], v199 offset:53248
	v_lshl_add_u64 v[82:83], s[30:31], 0, v[0:1]
	s_mov_b32 m0, s34
	s_nop 0
	global_load_lds_dwordx4 v[82:83], off
	ds_read_b128 v[232:235], v199 offset:54272
	ds_read_b128 v[236:239], v199 offset:55296
	v_lshl_add_u64 v[82:83], s[30:31], 0, v[166:167]
	s_add_i32 m0, s34, 0x2000
	s_nop 0
	global_load_lds_dwordx4 v[82:83], off
	ds_read_b128 v[240:243], v199 offset:56320
	v_lshl_add_u64 v[82:83], v[176:177], 0, s[70:71]
	s_mov_b32 m0, s45
	s_nop 0
	global_load_lds_dwordx4 v[82:83], off
	v_lshl_add_u64 v[82:83], v[200:201], 0, s[70:71]
	s_mov_b32 m0, s46
	s_nop 0
	global_load_lds_dwordx4 v[82:83], off
	s_waitcnt vmcnt(8)
	s_waitcnt lgkmcnt(0)
	s_barrier
	s_setprio 1
	s_waitcnt lgkmcnt(0)
	v_mfma_f32_16x16x32_bf16 v[82:85], v[42:45], v[66:69], v[94:97]
	v_mfma_f32_16x16x32_bf16 v[94:97], v[46:49], v[70:73], v[82:85]
	v_mfma_f32_16x16x32_bf16 v[82:85], v[50:53], v[66:69], v[90:93]
	v_mfma_f32_16x16x32_bf16 v[78:81], v[42:45], v[220:223], v[78:81]
	v_mfma_f32_16x16x32_bf16 v[74:77], v[50:53], v[220:223], v[74:77]
	v_mfma_f32_16x16x32_bf16 v[62:65], v[42:45], v[228:231], v[62:65]
	v_mfma_f32_16x16x32_bf16 v[58:61], v[50:53], v[228:231], v[58:61]
	v_mfma_f32_16x16x32_bf16 v[14:17], v[42:45], v[236:239], v[14:17]
	v_mfma_f32_16x16x32_bf16 v[10:13], v[50:53], v[236:239], v[10:13]
	v_mfma_f32_16x16x32_bf16 v[90:93], v[54:57], v[70:73], v[82:85]
	v_mfma_f32_16x16x32_bf16 v[78:81], v[46:49], v[224:227], v[78:81]
	v_mfma_f32_16x16x32_bf16 v[74:77], v[54:57], v[224:227], v[74:77]
	v_mfma_f32_16x16x32_bf16 v[62:65], v[46:49], v[232:235], v[62:65]
	v_mfma_f32_16x16x32_bf16 v[58:61], v[54:57], v[232:235], v[58:61]
	v_mfma_f32_16x16x32_bf16 v[14:17], v[46:49], v[240:243], v[14:17]
	v_mfma_f32_16x16x32_bf16 v[10:13], v[54:57], v[240:243], v[10:13]
	s_setprio 0
	s_setprio 1
	v_mfma_f32_16x16x32_bf16 v[18:21], v[182:185], v[66:69], v[18:21]
	v_mfma_f32_16x16x32_bf16 v[86:89], v[186:189], v[70:73], v[18:21]
	v_mfma_f32_16x16x32_bf16 v[18:21], v[212:215], v[66:69], v[22:25]
	v_mfma_f32_16x16x32_bf16 v[82:85], v[216:219], v[70:73], v[18:21]
	v_mfma_f32_16x16x32_bf16 v[18:21], v[182:185], v[220:223], v[26:29]
	v_mfma_f32_16x16x32_bf16 v[70:73], v[186:189], v[224:227], v[18:21]
	v_mfma_f32_16x16x32_bf16 v[18:21], v[212:215], v[220:223], v[30:33]
	v_mfma_f32_16x16x32_bf16 v[66:69], v[216:219], v[224:227], v[18:21]
	v_mfma_f32_16x16x32_bf16 v[18:21], v[182:185], v[228:231], v[38:41]
	v_mfma_f32_16x16x32_bf16 v[38:41], v[186:189], v[232:235], v[18:21]
	v_mfma_f32_16x16x32_bf16 v[18:21], v[212:215], v[228:231], v[34:37]
	v_mfma_f32_16x16x32_bf16 v[6:9], v[182:185], v[236:239], v[6:9]
	v_mfma_f32_16x16x32_bf16 v[2:5], v[212:215], v[236:239], v[2:5]
	v_mfma_f32_16x16x32_bf16 v[34:37], v[216:219], v[232:235], v[18:21]
	v_mfma_f32_16x16x32_bf16 v[6:9], v[186:189], v[240:243], v[6:9]
	v_mfma_f32_16x16x32_bf16 v[2:5], v[216:219], v[240:243], v[2:5]
	s_setprio 0
	s_barrier
	s_add_i32 s51, s51, 2
	s_add_u32 s49, s49, 0x100
	s_addc_u32 s50, s50, 0
	s_add_u32 s28, s28, 0x100
	s_addc_u32 s29, s29, 0
	s_cmpk_gt_u32 s51, 0x7d
	s_cbranch_scc0 .LBB0_126
	s_and_b64 vcc, exec, s[12:13]
	s_cbranch_vccz .LBB0_129
	s_barrier

; #define PG8_STAGE(bufoff, gbase, voff) do { _Pragma("unroll") for (int _i = 0; _i < 2; ++_i) \
;         __builtin_amdgcn_global_load_lds((const unsigned*)((const char*)(gbase) + (voff)[_i]), (LAS unsigned*)(lds + (bufoff) + ldsw + _i * 8192), 16, 0, 0); } while (0)
; #define PG8_LDA(dst, b, h) do { _Pragma("unroll") for (int m = 0; m < 4; ++m) _Pragma("unroll") for (int k = 0; k < 2; ++k) dst[m][k] = *(const LAS bf16x8*)(lds + PG8_SA(b, h) + aoff + m * 2048 + k * 1024); } while (0)
; #define PG8_LDB(dst, b, h) do { _Pragma("unroll") for (int n = 0; n < 2; ++n) _Pragma("unroll") for (int k = 0; k < 2; ++k) dst[n][k] = *(const LAS bf16x8*)(lds + PG8_SB(b, h) + boff + n * 2048 + k * 1024); } while (0)
; #define PG8_MMA(ai, bj, At, Bt) do { __builtin_amdgcn_s_setprio(1); _Pragma("unroll") for (int m = 0; m < 4; ++m) _Pragma("unroll") for (int n = 0; n < 2; ++n) _Pragma("unroll") for (int k = 0; k < 2; ++k) \
;         acc[ai][bj][m][n] = __builtin_amdgcn_mfma_f32_16x16x32_bf16(Bt[n][k], At[m][k], acc[ai][bj][m][n], 0, 0, 0); __builtin_amdgcn_s_setprio(0); } while (0)
; #define PG8_WAIT_V(n) asm volatile("s_waitcnt vmcnt(" #n ")" ::: "memory")
; #define PG8_WAIT_L(n) asm volatile("s_waitcnt lgkmcnt(" #n ")" ::: "memory")
; #define PG8_BAR __builtin_amdgcn_s_barrier()
; #define PG8_SCHED __builtin_amdgcn_sched_barrier(0)
; template <class Epi>
; __device__ __forceinline__ void gemm_phase(LAS unsigned char* lds, const Gemm g, const StaticOrder& S, const Epi& E, const int tid) {
;     ...
;             PG8_LDB(B0, 0, 0); PG8_LDB(B1, 0, 1); PG8_SCHED; PG8_LDA(At, 0, 0); PG8_STAGE(PG8_SA(1, 1), a1 + hstep, voffA);
;             PG8_WAIT_V(8); PG8_WAIT_L(0); PG8_BAR; PG8_MMA(0, 0, At, B0); PG8_MMA(0, 1, At, B1); PG8_BAR; PG8_SCHED;
;             PG8_LDA(At, 0, 1); PG8_STAGE(PG8_SB(0, 0), b2, voffB); PG8_STAGE(PG8_SB(0, 1), b2 + bhs, voffB); PG8_STAGE(PG8_SA(0, 0), a2, voffA);
;             PG8_WAIT_V(8); PG8_WAIT_L(0); PG8_BAR; PG8_MMA(1, 0, At, B0); PG8_MMA(1, 1, At, B1); PG8_BAR; PG8_SCHED;
.LBB0_173:
	s_add_i32 m0, s2, 0xc000
	s_nop 0
	global_load_lds_dwordx4 v140, s[26:27]
	s_add_i32 m0, s2, 0xe000
	s_nop 0
	global_load_lds_dwordx4 v138, s[26:27]
	s_add_u32 s28, s26, 0xfff80080
	s_addc_u32 s29, s27, -1
	s_add_i32 s47, 0, 0x10000
	s_cmp_eq_u32 s46, 28
	s_cselect_b32 s31, s17, s29
	s_cselect_b32 s30, s42, s28
	v_add_u32_e32 v142, s47, v149
	s_cselect_b32 s29, s15, s45
	s_cselect_b32 s28, s43, s44
	s_add_i32 s50, 0, 0x14000
	ds_read_b128 v[156:159], v142
	ds_read_b128 v[160:163], v142 offset:1024
	ds_read_b128 v[164:167], v142 offset:2048
	ds_read_b128 v[178:181], v142 offset:3072
	v_add_u32_e32 v142, s50, v149
	ds_read_b128 v[182:185], v142
	ds_read_b128 v[186:189], v142 offset:1024
	ds_read_b128 v[190:193], v142 offset:2048
	ds_read_b128 v[194:197], v142 offset:3072
	ds_read_b128 v[198:201], v154
	ds_read_b128 v[212:215], v154 offset:1024
	ds_read_b128 v[216:219], v154 offset:2048
	ds_read_b128 v[220:223], v154 offset:3072
	ds_read_b128 v[224:227], v154 offset:4096
	ds_read_b128 v[228:231], v154 offset:5120
	ds_read_b128 v[232:235], v154 offset:6144
	ds_read_b128 v[236:239], v154 offset:7168
	s_waitcnt vmcnt(8)
	s_waitcnt lgkmcnt(0)
	s_barrier
	s_setprio 1
	s_waitcnt lgkmcnt(0)
	v_mfma_f32_16x16x32_bf16 v[126:129], v[156:159], v[198:201], v[126:129]
	v_mfma_f32_16x16x32_bf16 v[122:125], v[164:167], v[198:201], v[122:125]
	v_mfma_f32_16x16x32_bf16 v[110:113], v[156:159], v[216:219], v[110:113]
	v_mfma_f32_16x16x32_bf16 v[106:109], v[164:167], v[216:219], v[106:109]
	v_mfma_f32_16x16x32_bf16 v[94:97], v[156:159], v[224:227], v[94:97]
	v_mfma_f32_16x16x32_bf16 v[90:93], v[164:167], v[224:227], v[90:93]
	v_mfma_f32_16x16x32_bf16 v[78:81], v[156:159], v[232:235], v[78:81]
	v_mfma_f32_16x16x32_bf16 v[74:77], v[164:167], v[232:235], v[74:77]
	v_mfma_f32_16x16x32_bf16 v[126:129], v[160:163], v[212:215], v[126:129]
	v_mfma_f32_16x16x32_bf16 v[122:125], v[178:181], v[212:215], v[122:125]
	v_mfma_f32_16x16x32_bf16 v[110:113], v[160:163], v[220:223], v[110:113]
	v_mfma_f32_16x16x32_bf16 v[106:109], v[178:181], v[220:223], v[106:109]
	v_mfma_f32_16x16x32_bf16 v[94:97], v[160:163], v[228:231], v[94:97]
	v_mfma_f32_16x16x32_bf16 v[90:93], v[178:181], v[228:231], v[90:93]
	v_mfma_f32_16x16x32_bf16 v[78:81], v[160:163], v[236:239], v[78:81]
	v_mfma_f32_16x16x32_bf16 v[74:77], v[178:181], v[236:239], v[74:77]
	s_setprio 0
	s_setprio 1
	v_mfma_f32_16x16x32_bf16 v[118:121], v[182:185], v[198:201], v[118:121]
	v_mfma_f32_16x16x32_bf16 v[114:117], v[190:193], v[198:201], v[114:117]
	v_mfma_f32_16x16x32_bf16 v[102:105], v[182:185], v[216:219], v[102:105]
	v_mfma_f32_16x16x32_bf16 v[98:101], v[190:193], v[216:219], v[98:101]
	v_mfma_f32_16x16x32_bf16 v[86:89], v[182:185], v[224:227], v[86:89]
	v_mfma_f32_16x16x32_bf16 v[82:85], v[190:193], v[224:227], v[82:85]
	v_mfma_f32_16x16x32_bf16 v[70:73], v[182:185], v[232:235], v[70:73]
	v_mfma_f32_16x16x32_bf16 v[66:69], v[190:193], v[232:235], v[66:69]
	v_mfma_f32_16x16x32_bf16 v[118:121], v[186:189], v[212:215], v[118:121]
	v_mfma_f32_16x16x32_bf16 v[114:117], v[194:197], v[212:215], v[114:117]
	v_mfma_f32_16x16x32_bf16 v[102:105], v[186:189], v[220:223], v[102:105]
	v_mfma_f32_16x16x32_bf16 v[98:101], v[194:197], v[220:223], v[98:101]
	v_mfma_f32_16x16x32_bf16 v[86:89], v[186:189], v[228:231], v[86:89]
	v_mfma_f32_16x16x32_bf16 v[82:85], v[194:197], v[228:231], v[82:85]
	v_mfma_f32_16x16x32_bf16 v[70:73], v[186:189], v[236:239], v[70:73]
	v_mfma_f32_16x16x32_bf16 v[66:69], v[194:197], v[236:239], v[66:69]
	s_setprio 0
	s_barrier
	s_add_i32 s47, s47, s34
	v_lshl_add_u64 v[142:143], s[28:29], 0, v[0:1]
	s_mov_b32 m0, s47
	ds_read_b128 v[198:201], v154 offset:16384
	global_load_lds_dwordx4 v[142:143], off
	ds_read_b128 v[212:215], v154 offset:17408
	ds_read_b128 v[216:219], v154 offset:18432
	s_add_i32 m0, s47, 0x2000
	s_add_u32 s48, s28, 0x8000
	v_lshl_add_u64 v[168:169], s[28:29], 0, v[134:135]
	s_addc_u32 s49, s29, 0
	s_add_i32 s47, s50, s34
	global_load_lds_dwordx4 v[168:169], off
	ds_read_b128 v[220:223], v154 offset:19456
	ds_read_b128 v[224:227], v154 offset:20480
	v_lshl_add_u64 v[172:173], s[48:49], 0, v[0:1]
	s_mov_b32 m0, s47
	v_lshl_add_u64 v[174:175], s[30:31], 0, v[132:133]
	global_load_lds_dwordx4 v[172:173], off
	ds_read_b128 v[228:231], v154 offset:21504
	ds_read_b128 v[232:235], v154 offset:22528
	v_lshl_add_u64 v[172:173], s[48:49], 0, v[134:135]
	s_add_i32 m0, s47, 0x2000
	s_nop 0
	global_load_lds_dwordx4 v[172:173], off
	ds_read_b128 v[236:239], v154 offset:23552
	v_lshl_add_u64 v[172:173], s[30:31], 0, v[130:131]
	s_mov_b32 m0, s2
	s_nop 0
	global_load_lds_dwordx4 v[172:173], off
	s_mov_b32 m0, s25
	s_nop 0
	global_load_lds_dwordx4 v[174:175], off
	s_waitcnt vmcnt(8)
	s_waitcnt lgkmcnt(0)
	s_barrier
; #define PG8_STAGE(bufoff, gbase, voff) do { _Pragma("unroll") for (int _i = 0; _i < 2; ++_i) \
;         __builtin_amdgcn_global_load_lds((const unsigned*)((const char*)(gbase) + (voff)[_i]), (LAS unsigned*)(lds + (bufoff) + ldsw + _i * 8192), 16, 0, 0); } while (0)
; #define PG8_LDA(dst, b, h) do { _Pragma("unroll") for (int m = 0; m < 4; ++m) _Pragma("unroll") for (int k = 0; k < 2; ++k) dst[m][k] = *(const LAS bf16x8*)(lds + PG8_SA(b, h) + aoff + m * 2048 + k * 1024); } while (0)
; #define PG8_LDB(dst, b, h) do { _Pragma("unroll") for (int n = 0; n < 2; ++n) _Pragma("unroll") for (int k = 0; k < 2; ++k) dst[n][k] = *(const LAS bf16x8*)(lds + PG8_SB(b, h) + boff + n * 2048 + k * 1024); } while (0)
; #define PG8_MMA(ai, bj, At, Bt) do { __builtin_amdgcn_s_setprio(1); _Pragma("unroll") for (int m = 0; m < 4; ++m) _Pragma("unroll") for (int n = 0; n < 2; ++n) _Pragma("unroll") for (int k = 0; k < 2; ++k) \
;         acc[ai][bj][m][n] = __builtin_amdgcn_mfma_f32_16x16x32_bf16(Bt[n][k], At[m][k], acc[ai][bj][m][n], 0, 0, 0); __builtin_amdgcn_s_setprio(0); } while (0)
; #define PG8_WAIT_V(n) asm volatile("s_waitcnt vmcnt(" #n ")" ::: "memory")
; #define PG8_WAIT_L(n) asm volatile("s_waitcnt lgkmcnt(" #n ")" ::: "memory")
; #define PG8_BAR __builtin_amdgcn_s_barrier()
; #define PG8_SCHED __builtin_amdgcn_sched_barrier(0)
; template <class Epi>
; __device__ __forceinline__ void gemm_phase(LAS unsigned char* lds, const Gemm g, const StaticOrder& S, const Epi& E, const int tid) {
;     ...
;             PG8_WAIT_V(8); PG8_WAIT_L(0); PG8_BAR; PG8_MMA(1, 0, At, B0); PG8_MMA(1, 1, At, B1); PG8_BAR; PG8_SCHED;
;             PG8_LDB(B0, 1, 0); PG8_LDB(B1, 1, 1); PG8_SCHED; PG8_LDA(At, 1, 0); PG8_STAGE(PG8_SA(0, 1), a2 + hstep, voffA);
;             PG8_WAIT_V(8); PG8_WAIT_L(0); PG8_BAR; PG8_MMA(0, 0, At, B0); PG8_MMA(0, 1, At, B1); PG8_BAR; PG8_SCHED;
	s_setprio 1
	s_waitcnt lgkmcnt(0)
	v_mfma_f32_16x16x32_bf16 v[62:65], v[156:159], v[198:201], v[62:65]
	v_mfma_f32_16x16x32_bf16 v[58:61], v[164:167], v[198:201], v[58:61]
	v_mfma_f32_16x16x32_bf16 v[46:49], v[156:159], v[216:219], v[46:49]
	v_mfma_f32_16x16x32_bf16 v[42:45], v[164:167], v[216:219], v[42:45]
	v_mfma_f32_16x16x32_bf16 v[30:33], v[156:159], v[224:227], v[30:33]
	v_mfma_f32_16x16x32_bf16 v[26:29], v[164:167], v[224:227], v[26:29]
	v_mfma_f32_16x16x32_bf16 v[14:17], v[156:159], v[232:235], v[14:17]
	v_mfma_f32_16x16x32_bf16 v[10:13], v[164:167], v[232:235], v[10:13]
	v_mfma_f32_16x16x32_bf16 v[62:65], v[160:163], v[212:215], v[62:65]
	v_mfma_f32_16x16x32_bf16 v[58:61], v[178:181], v[212:215], v[58:61]
	v_mfma_f32_16x16x32_bf16 v[46:49], v[160:163], v[220:223], v[46:49]
	v_mfma_f32_16x16x32_bf16 v[42:45], v[178:181], v[220:223], v[42:45]
	v_mfma_f32_16x16x32_bf16 v[30:33], v[160:163], v[228:231], v[30:33]
	v_mfma_f32_16x16x32_bf16 v[26:29], v[178:181], v[228:231], v[26:29]
	v_mfma_f32_16x16x32_bf16 v[14:17], v[160:163], v[236:239], v[14:17]
	v_mfma_f32_16x16x32_bf16 v[10:13], v[178:181], v[236:239], v[10:13]
	s_setprio 0
	s_setprio 1
	v_mfma_f32_16x16x32_bf16 v[54:57], v[182:185], v[198:201], v[54:57]
	v_mfma_f32_16x16x32_bf16 v[50:53], v[190:193], v[198:201], v[50:53]
	v_mfma_f32_16x16x32_bf16 v[38:41], v[182:185], v[216:219], v[38:41]
	v_mfma_f32_16x16x32_bf16 v[34:37], v[190:193], v[216:219], v[34:37]
	v_mfma_f32_16x16x32_bf16 v[22:25], v[182:185], v[224:227], v[22:25]
	v_mfma_f32_16x16x32_bf16 v[18:21], v[190:193], v[224:227], v[18:21]
	v_mfma_f32_16x16x32_bf16 v[6:9], v[182:185], v[232:235], v[6:9]
	v_mfma_f32_16x16x32_bf16 v[2:5], v[190:193], v[232:235], v[2:5]
	v_mfma_f32_16x16x32_bf16 v[54:57], v[186:189], v[212:215], v[54:57]
	v_mfma_f32_16x16x32_bf16 v[50:53], v[194:197], v[212:215], v[50:53]
	v_mfma_f32_16x16x32_bf16 v[38:41], v[186:189], v[220:223], v[38:41]
	v_mfma_f32_16x16x32_bf16 v[34:37], v[194:197], v[220:223], v[34:37]
	v_mfma_f32_16x16x32_bf16 v[22:25], v[186:189], v[228:231], v[22:25]
	v_mfma_f32_16x16x32_bf16 v[18:21], v[194:197], v[228:231], v[18:21]
	v_mfma_f32_16x16x32_bf16 v[6:9], v[186:189], v[236:239], v[6:9]
	v_mfma_f32_16x16x32_bf16 v[2:5], v[194:197], v[236:239], v[2:5]
	s_setprio 0
	s_barrier
	s_add_u32 s30, s30, 0x80000
	s_addc_u32 s31, s31, 0
	s_mov_b32 m0, s35
	s_nop 0
	global_load_lds_dwordx4 v130, s[30:31]
	s_mov_b32 m0, s36
	s_nop 0
	global_load_lds_dwordx4 v132, s[30:31]
	s_add_i32 s47, 0, 0x18000
	v_add_u32_e32 v155, s47, v149
	s_add_i32 s48, 0, 0x1c000
	ds_read_b128 v[156:159], v155
	ds_read_b128 v[160:163], v155 offset:1024
	ds_read_b128 v[164:167], v155 offset:2048
	ds_read_b128 v[178:181], v155 offset:3072
	v_add_u32_e32 v155, s48, v149
	ds_read_b128 v[182:185], v155
	ds_read_b128 v[186:189], v155 offset:1024
	ds_read_b128 v[190:193], v155 offset:2048
	ds_read_b128 v[194:197], v155 offset:3072
	ds_read_b128 v[198:201], v154 offset:32768
	ds_read_b128 v[212:215], v154 offset:33792
	ds_read_b128 v[216:219], v154 offset:34816
	ds_read_b128 v[220:223], v154 offset:35840
	ds_read_b128 v[224:227], v154 offset:36864
	ds_read_b128 v[228:231], v154 offset:37888
	ds_read_b128 v[232:235], v154 offset:38912
	ds_read_b128 v[236:239], v154 offset:39936
	s_waitcnt vmcnt(8)
	s_waitcnt lgkmcnt(0)
	s_barrier
	s_setprio 1
	s_waitcnt lgkmcnt(0)
	v_mfma_f32_16x16x32_bf16 v[126:129], v[156:159], v[198:201], v[126:129]
	v_mfma_f32_16x16x32_bf16 v[122:125], v[164:167], v[198:201], v[122:125]
	v_mfma_f32_16x16x32_bf16 v[110:113], v[156:159], v[216:219], v[110:113]
	v_mfma_f32_16x16x32_bf16 v[106:109], v[164:167], v[216:219], v[106:109]
	v_mfma_f32_16x16x32_bf16 v[94:97], v[156:159], v[224:227], v[94:97]
	v_mfma_f32_16x16x32_bf16 v[90:93], v[164:167], v[224:227], v[90:93]
	v_mfma_f32_16x16x32_bf16 v[78:81], v[156:159], v[232:235], v[78:81]
	v_mfma_f32_16x16x32_bf16 v[74:77], v[164:167], v[232:235], v[74:77]
	v_mfma_f32_16x16x32_bf16 v[126:129], v[160:163], v[212:215], v[126:129]
	v_mfma_f32_16x16x32_bf16 v[122:125], v[178:181], v[212:215], v[122:125]
	v_mfma_f32_16x16x32_bf16 v[110:113], v[160:163], v[220:223], v[110:113]
	v_mfma_f32_16x16x32_bf16 v[106:109], v[178:181], v[220:223], v[106:109]
	v_mfma_f32_16x16x32_bf16 v[94:97], v[160:163], v[228:231], v[94:97]
	v_mfma_f32_16x16x32_bf16 v[90:93], v[178:181], v[228:231], v[90:93]
	v_mfma_f32_16x16x32_bf16 v[78:81], v[160:163], v[236:239], v[78:81]
	v_mfma_f32_16x16x32_bf16 v[74:77], v[178:181], v[236:239], v[74:77]
	s_setprio 0
	s_setprio 1
	v_mfma_f32_16x16x32_bf16 v[118:121], v[182:185], v[198:201], v[118:121]
	v_mfma_f32_16x16x32_bf16 v[114:117], v[190:193], v[198:201], v[114:117]
	v_mfma_f32_16x16x32_bf16 v[102:105], v[182:185], v[216:219], v[102:105]
	v_mfma_f32_16x16x32_bf16 v[98:101], v[190:193], v[216:219], v[98:101]
	v_mfma_f32_16x16x32_bf16 v[86:89], v[182:185], v[224:227], v[86:89]
	v_mfma_f32_16x16x32_bf16 v[82:85], v[190:193], v[224:227], v[82:85]
	v_mfma_f32_16x16x32_bf16 v[70:73], v[182:185], v[232:235], v[70:73]
	v_mfma_f32_16x16x32_bf16 v[66:69], v[190:193], v[232:235], v[66:69]
	v_mfma_f32_16x16x32_bf16 v[118:121], v[186:189], v[212:215], v[118:121]
	v_mfma_f32_16x16x32_bf16 v[114:117], v[194:197], v[212:215], v[114:117]
	v_mfma_f32_16x16x32_bf16 v[102:105], v[186:189], v[220:223], v[102:105]
	v_mfma_f32_16x16x32_bf16 v[98:101], v[194:197], v[220:223], v[98:101]
	v_mfma_f32_16x16x32_bf16 v[86:89], v[186:189], v[228:231], v[86:89]
	v_mfma_f32_16x16x32_bf16 v[82:85], v[194:197], v[228:231], v[82:85]
	v_mfma_f32_16x16x32_bf16 v[70:73], v[186:189], v[236:239], v[70:73]
	v_mfma_f32_16x16x32_bf16 v[66:69], v[194:197], v[236:239], v[66:69]
	s_setprio 0
	s_barrier
; #define PG8_STAGE(bufoff, gbase, voff) do { _Pragma("unroll") for (int _i = 0; _i < 2; ++_i) \
;         __builtin_amdgcn_global_load_lds((const unsigned*)((const char*)(gbase) + (voff)[_i]), (LAS unsigned*)(lds + (bufoff) + ldsw + _i * 8192), 16, 0, 0); } while (0)
; #define PG8_LDA(dst, b, h) do { _Pragma("unroll") for (int m = 0; m < 4; ++m) _Pragma("unroll") for (int k = 0; k < 2; ++k) dst[m][k] = *(const LAS bf16x8*)(lds + PG8_SA(b, h) + aoff + m * 2048 + k * 1024); } while (0)
; #define PG8_MMA(ai, bj, At, Bt) do { __builtin_amdgcn_s_setprio(1); _Pragma("unroll") for (int m = 0; m < 4; ++m) _Pragma("unroll") for (int n = 0; n < 2; ++n) _Pragma("unroll") for (int k = 0; k < 2; ++k) \
;         acc[ai][bj][m][n] = __builtin_amdgcn_mfma_f32_16x16x32_bf16(Bt[n][k], At[m][k], acc[ai][bj][m][n], 0, 0, 0); __builtin_amdgcn_s_setprio(0); } while (0)
; #define PG8_WAIT_V(n) asm volatile("s_waitcnt vmcnt(" #n ")" ::: "memory")
; #define PG8_WAIT_L(n) asm volatile("s_waitcnt lgkmcnt(" #n ")" ::: "memory")
; #define PG8_BAR __builtin_amdgcn_s_barrier()
; #define PG8_SCHED __builtin_amdgcn_sched_barrier(0)
; template <class Epi>
; __device__ __forceinline__ void gemm_phase(LAS unsigned char* lds, const Gemm g, const StaticOrder& S, const Epi& E, const int tid) {
;     ...
;             const char* a1 = (s1 ? cA2 + (size_t)(t - nt + 1) * kstep : cA + (size_t)(t + 1) * kstep);
;             const char* a2 = last ? nA : (s2 ? cA2 + (size_t)(t + 2 - nt) * kstep : cA + (size_t)(t + 2) * kstep);
;             const char* b2 = last ? nB : (s2 ? cB2 + (size_t)(t + 2 - nt) * kstep : cB + (size_t)(t + 2) * kstep);
;             const char* a3 = a2 + kstep; const char* b3 = b2 + kstep;
;     ...
;             PG8_LDA(At, 1, 1); PG8_STAGE(PG8_SB(1, 0), b3, voffB); PG8_STAGE(PG8_SB(1, 1), b3 + bhs, voffB); PG8_STAGE(PG8_SA(1, 0), a3, voffA);
;             PG8_WAIT_V(8); PG8_WAIT_L(0); PG8_BAR; PG8_MMA(1, 0, At, B0); PG8_MMA(1, 1, At, B1); PG8_BAR; PG8_SCHED;
	s_add_i32 s30, s47, s34
	v_lshl_add_u64 v[142:143], v[142:143], 0, s[70:71]
	s_mov_b32 m0, s30
	ds_read_b128 v[198:201], v154 offset:49152
	global_load_lds_dwordx4 v[142:143], off
	ds_read_b128 v[212:215], v154 offset:50176
	ds_read_b128 v[216:219], v154 offset:51200
	s_add_i32 m0, s30, 0x2000
	s_add_u32 s28, s28, 0x8080
	v_lshl_add_u64 v[142:143], v[168:169], 0, s[70:71]
	s_addc_u32 s29, s29, 0
	s_add_i32 s30, s48, s34
	global_load_lds_dwordx4 v[142:143], off
	ds_read_b128 v[220:223], v154 offset:52224
	ds_read_b128 v[224:227], v154 offset:53248
	v_lshl_add_u64 v[142:143], s[28:29], 0, v[0:1]
	s_mov_b32 m0, s30
	s_nop 0
	global_load_lds_dwordx4 v[142:143], off
	ds_read_b128 v[228:231], v154 offset:54272
	ds_read_b128 v[232:235], v154 offset:55296
	v_lshl_add_u64 v[142:143], s[28:29], 0, v[134:135]
	s_add_i32 m0, s30, 0x2000
	s_nop 0
	global_load_lds_dwordx4 v[142:143], off
	ds_read_b128 v[236:239], v154 offset:56320
	v_lshl_add_u64 v[142:143], v[172:173], 0, s[70:71]
	s_mov_b32 m0, s37
	s_nop 0
	global_load_lds_dwordx4 v[142:143], off
	v_lshl_add_u64 v[142:143], v[174:175], 0, s[70:71]
	s_mov_b32 m0, s38
	s_nop 0
	global_load_lds_dwordx4 v[142:143], off
	s_waitcnt vmcnt(8)
	s_waitcnt lgkmcnt(0)
	s_barrier
	s_setprio 1
	s_waitcnt lgkmcnt(0)
	v_mfma_f32_16x16x32_bf16 v[62:65], v[156:159], v[198:201], v[62:65]
	v_mfma_f32_16x16x32_bf16 v[58:61], v[164:167], v[198:201], v[58:61]
	v_mfma_f32_16x16x32_bf16 v[46:49], v[156:159], v[216:219], v[46:49]
	v_mfma_f32_16x16x32_bf16 v[42:45], v[164:167], v[216:219], v[42:45]
	v_mfma_f32_16x16x32_bf16 v[30:33], v[156:159], v[224:227], v[30:33]
	v_mfma_f32_16x16x32_bf16 v[26:29], v[164:167], v[224:227], v[26:29]
	v_mfma_f32_16x16x32_bf16 v[14:17], v[156:159], v[232:235], v[14:17]
	v_mfma_f32_16x16x32_bf16 v[10:13], v[164:167], v[232:235], v[10:13]
	v_mfma_f32_16x16x32_bf16 v[62:65], v[160:163], v[212:215], v[62:65]
	v_mfma_f32_16x16x32_bf16 v[58:61], v[178:181], v[212:215], v[58:61]
	v_mfma_f32_16x16x32_bf16 v[46:49], v[160:163], v[220:223], v[46:49]
	v_mfma_f32_16x16x32_bf16 v[42:45], v[178:181], v[220:223], v[42:45]
	v_mfma_f32_16x16x32_bf16 v[30:33], v[160:163], v[228:231], v[30:33]
	v_mfma_f32_16x16x32_bf16 v[26:29], v[178:181], v[228:231], v[26:29]
	v_mfma_f32_16x16x32_bf16 v[14:17], v[160:163], v[236:239], v[14:17]
	v_mfma_f32_16x16x32_bf16 v[10:13], v[178:181], v[236:239], v[10:13]
	s_setprio 0
	s_setprio 1
	v_mfma_f32_16x16x32_bf16 v[54:57], v[182:185], v[198:201], v[54:57]
	v_mfma_f32_16x16x32_bf16 v[50:53], v[190:193], v[198:201], v[50:53]
	v_mfma_f32_16x16x32_bf16 v[38:41], v[182:185], v[216:219], v[38:41]
	v_mfma_f32_16x16x32_bf16 v[34:37], v[190:193], v[216:219], v[34:37]
	v_mfma_f32_16x16x32_bf16 v[22:25], v[182:185], v[224:227], v[22:25]
	v_mfma_f32_16x16x32_bf16 v[18:21], v[190:193], v[224:227], v[18:21]
	v_mfma_f32_16x16x32_bf16 v[6:9], v[182:185], v[232:235], v[6:9]
	v_mfma_f32_16x16x32_bf16 v[2:5], v[190:193], v[232:235], v[2:5]
	v_mfma_f32_16x16x32_bf16 v[54:57], v[186:189], v[212:215], v[54:57]
	v_mfma_f32_16x16x32_bf16 v[50:53], v[194:197], v[212:215], v[50:53]
	v_mfma_f32_16x16x32_bf16 v[38:41], v[186:189], v[220:223], v[38:41]
	v_mfma_f32_16x16x32_bf16 v[34:37], v[194:197], v[220:223], v[34:37]
	v_mfma_f32_16x16x32_bf16 v[22:25], v[186:189], v[228:231], v[22:25]
	v_mfma_f32_16x16x32_bf16 v[18:21], v[194:197], v[228:231], v[18:21]
	v_mfma_f32_16x16x32_bf16 v[6:9], v[186:189], v[236:239], v[6:9]
	v_mfma_f32_16x16x32_bf16 v[2:5], v[194:197], v[236:239], v[2:5]
	s_setprio 0
	s_barrier
	s_add_i32 s46, s46, 2
	s_add_u32 s44, s44, 0x100
	s_addc_u32 s45, s45, 0
	s_add_u32 s26, s26, 0x100
	s_addc_u32 s27, s27, 0
	s_cmp_gt_u32 s46, 29
	s_cbranch_scc0 .LBB0_173
	v_readlane_b32 s42, v251, 53
	s_and_b64 vcc, exec, s[12:13]
	v_readlane_b32 s43, v251, 54
	s_cbranch_vccz .LBB0_176
	s_barrier

; #define PG8_STAGE(bufoff, gbase, voff) do { _Pragma("unroll") for (int _i = 0; _i < 2; ++_i) \
;         __builtin_amdgcn_global_load_lds((const unsigned*)((const char*)(gbase) + (voff)[_i]), (LAS unsigned*)(lds + (bufoff) + ldsw + _i * 8192), 16, 0, 0); } while (0)
; #define PG8_LDA(dst, b, h) do { _Pragma("unroll") for (int m = 0; m < 4; ++m) _Pragma("unroll") for (int k = 0; k < 2; ++k) dst[m][k] = *(const LAS bf16x8*)(lds + PG8_SA(b, h) + aoff + m * 2048 + k * 1024); } while (0)
; #define PG8_LDB(dst, b, h) do { _Pragma("unroll") for (int n = 0; n < 2; ++n) _Pragma("unroll") for (int k = 0; k < 2; ++k) dst[n][k] = *(const LAS bf16x8*)(lds + PG8_SB(b, h) + boff + n * 2048 + k * 1024); } while (0)
; #define PG8_MMA(ai, bj, At, Bt) do { __builtin_amdgcn_s_setprio(1); _Pragma("unroll") for (int m = 0; m < 4; ++m) _Pragma("unroll") for (int n = 0; n < 2; ++n) _Pragma("unroll") for (int k = 0; k < 2; ++k) \
;         acc[ai][bj][m][n] = __builtin_amdgcn_mfma_f32_16x16x32_bf16(Bt[n][k], At[m][k], acc[ai][bj][m][n], 0, 0, 0); __builtin_amdgcn_s_setprio(0); } while (0)
; #define PG8_WAIT_V(n) asm volatile("s_waitcnt vmcnt(" #n ")" ::: "memory")
; #define PG8_WAIT_L(n) asm volatile("s_waitcnt lgkmcnt(" #n ")" ::: "memory")
; #define PG8_BAR __builtin_amdgcn_s_barrier()
; #define PG8_SCHED __builtin_amdgcn_sched_barrier(0)
; template <class Epi>
; __device__ __forceinline__ void gemm_phase(LAS unsigned char* lds, const Gemm g, const StaticOrder& S, const Epi& E, const int tid) {
;     ...
;             PG8_LDB(B0, 0, 0); PG8_LDB(B1, 0, 1); PG8_SCHED; PG8_LDA(At, 0, 0); PG8_STAGE(PG8_SA(1, 1), a1 + hstep, voffA);
;             PG8_WAIT_V(8); PG8_WAIT_L(0); PG8_BAR; PG8_MMA(0, 0, At, B0); PG8_MMA(0, 1, At, B1); PG8_BAR; PG8_SCHED;
;             PG8_LDA(At, 0, 1); PG8_STAGE(PG8_SB(0, 0), b2, voffB); PG8_STAGE(PG8_SB(0, 1), b2 + bhs, voffB); PG8_STAGE(PG8_SA(0, 0), a2, voffA);
;             PG8_WAIT_V(8); PG8_WAIT_L(0); PG8_BAR; PG8_MMA(1, 0, At, B0); PG8_MMA(1, 1, At, B1); PG8_BAR; PG8_SCHED;
.LBB0_206:
	s_add_i32 m0, s37, 0xc000
	s_nop 0
	global_load_lds_dwordx4 v180, s[28:29]
	s_add_i32 m0, s37, 0xe000
	s_nop 0
	global_load_lds_dwordx4 v178, s[28:29]
	s_add_u32 s30, s28, 0xfffe0080
	s_addc_u32 s31, s29, -1
	s_add_i32 s52, 0, 0x10000
	s_cmp_eq_u32 s51, 4
	s_cselect_b32 s35, s17, s31
	s_cselect_b32 s34, s27, s30
	s_cselect_b32 s31, s15, s50
	s_cselect_b32 s30, s33, s49
	s_add_i32 s54, 0, 0x14000
	v_add_u32_e32 v30, s52, v193
	v_add_u32_e32 v54, s54, v193
	ds_read_b128 v[18:21], v30
	ds_read_b128 v[22:25], v30 offset:1024
	ds_read_b128 v[26:29], v30 offset:2048
	ds_read_b128 v[30:33], v30 offset:3072
	ds_read_b128 v[42:45], v54
	ds_read_b128 v[46:49], v54 offset:1024
	ds_read_b128 v[50:53], v54 offset:2048
	ds_read_b128 v[54:57], v54 offset:3072
	ds_read_b128 v[182:185], v199
	ds_read_b128 v[186:189], v199 offset:1024
	ds_read_b128 v[212:215], v199 offset:2048
	ds_read_b128 v[216:219], v199 offset:3072
	ds_read_b128 v[220:223], v199 offset:4096
	ds_read_b128 v[224:227], v199 offset:5120
	ds_read_b128 v[228:231], v199 offset:6144
	ds_read_b128 v[232:235], v199 offset:7168
	s_waitcnt vmcnt(8)
	s_waitcnt lgkmcnt(0)
	s_barrier
	s_setprio 1
	s_waitcnt lgkmcnt(0)
	v_mfma_f32_16x16x32_bf16 v[158:161], v[18:21], v[182:185], v[158:161]
	v_mfma_f32_16x16x32_bf16 v[154:157], v[26:29], v[182:185], v[154:157]
	v_mfma_f32_16x16x32_bf16 v[142:145], v[18:21], v[212:215], v[142:145]
	v_mfma_f32_16x16x32_bf16 v[138:141], v[26:29], v[212:215], v[138:141]
	v_mfma_f32_16x16x32_bf16 v[126:129], v[18:21], v[220:223], v[126:129]
	v_mfma_f32_16x16x32_bf16 v[122:125], v[26:29], v[220:223], v[122:125]
	v_mfma_f32_16x16x32_bf16 v[110:113], v[18:21], v[228:231], v[110:113]
	v_mfma_f32_16x16x32_bf16 v[106:109], v[26:29], v[228:231], v[106:109]
	v_mfma_f32_16x16x32_bf16 v[158:161], v[22:25], v[186:189], v[158:161]
	v_mfma_f32_16x16x32_bf16 v[154:157], v[30:33], v[186:189], v[154:157]
	v_mfma_f32_16x16x32_bf16 v[142:145], v[22:25], v[216:219], v[142:145]
	v_mfma_f32_16x16x32_bf16 v[138:141], v[30:33], v[216:219], v[138:141]
	v_mfma_f32_16x16x32_bf16 v[126:129], v[22:25], v[224:227], v[126:129]
	v_mfma_f32_16x16x32_bf16 v[122:125], v[30:33], v[224:227], v[122:125]
	v_mfma_f32_16x16x32_bf16 v[110:113], v[22:25], v[232:235], v[110:113]
	v_mfma_f32_16x16x32_bf16 v[106:109], v[30:33], v[232:235], v[106:109]
	s_setprio 0
	s_setprio 1
	v_mfma_f32_16x16x32_bf16 v[150:153], v[42:45], v[182:185], v[150:153]
	v_mfma_f32_16x16x32_bf16 v[146:149], v[50:53], v[182:185], v[146:149]
	v_mfma_f32_16x16x32_bf16 v[134:137], v[42:45], v[212:215], v[134:137]
	v_mfma_f32_16x16x32_bf16 v[130:133], v[50:53], v[212:215], v[130:133]
	v_mfma_f32_16x16x32_bf16 v[118:121], v[42:45], v[220:223], v[118:121]
	v_mfma_f32_16x16x32_bf16 v[114:117], v[50:53], v[220:223], v[114:117]
	v_mfma_f32_16x16x32_bf16 v[102:105], v[42:45], v[228:231], v[102:105]
	v_mfma_f32_16x16x32_bf16 v[98:101], v[50:53], v[228:231], v[98:101]
	v_mfma_f32_16x16x32_bf16 v[150:153], v[46:49], v[186:189], v[150:153]
	v_mfma_f32_16x16x32_bf16 v[146:149], v[54:57], v[186:189], v[146:149]
	v_mfma_f32_16x16x32_bf16 v[134:137], v[46:49], v[216:219], v[134:137]
	v_mfma_f32_16x16x32_bf16 v[130:133], v[54:57], v[216:219], v[130:133]
	v_mfma_f32_16x16x32_bf16 v[118:121], v[46:49], v[224:227], v[118:121]
	v_mfma_f32_16x16x32_bf16 v[114:117], v[54:57], v[224:227], v[114:117]
	v_mfma_f32_16x16x32_bf16 v[102:105], v[46:49], v[232:235], v[102:105]
	v_mfma_f32_16x16x32_bf16 v[98:101], v[54:57], v[232:235], v[98:101]
	s_setprio 0
	s_barrier
	s_add_i32 s52, s52, s36
	v_lshl_add_u64 v[172:173], s[30:31], 0, v[0:1]
	s_mov_b32 m0, s52
	ds_read_b128 v[182:185], v199 offset:16384
	global_load_lds_dwordx4 v[172:173], off
	ds_read_b128 v[186:189], v199 offset:17408
	ds_read_b128 v[212:215], v199 offset:18432
	s_add_i32 m0, s52, 0x2000
	s_add_u32 s52, s30, 0x2000
	v_lshl_add_u64 v[174:175], s[30:31], 0, v[166:167]
	s_addc_u32 s53, s31, 0
	s_add_i32 s54, s54, s36
	global_load_lds_dwordx4 v[174:175], off
	ds_read_b128 v[216:219], v199 offset:19456
	ds_read_b128 v[220:223], v199 offset:20480
	v_lshl_add_u64 v[176:177], s[52:53], 0, v[0:1]
	s_mov_b32 m0, s54
	v_lshl_add_u64 v[200:201], s[34:35], 0, v[164:165]
	global_load_lds_dwordx4 v[176:177], off
	ds_read_b128 v[224:227], v199 offset:21504
	ds_read_b128 v[228:231], v199 offset:22528
	v_lshl_add_u64 v[176:177], s[52:53], 0, v[166:167]
	s_add_i32 m0, s54, 0x2000
	s_nop 0
	global_load_lds_dwordx4 v[176:177], off
	ds_read_b128 v[232:235], v199 offset:23552
	v_lshl_add_u64 v[176:177], s[34:35], 0, v[162:163]
	s_mov_b32 m0, s37
	s_nop 0
	global_load_lds_dwordx4 v[176:177], off
	s_mov_b32 m0, s38
	s_nop 0
	global_load_lds_dwordx4 v[200:201], off
	s_waitcnt vmcnt(8)
	s_waitcnt lgkmcnt(0)
	s_barrier
; #define PG8_STAGE(bufoff, gbase, voff) do { _Pragma("unroll") for (int _i = 0; _i < 2; ++_i) \
;         __builtin_amdgcn_global_load_lds((const unsigned*)((const char*)(gbase) + (voff)[_i]), (LAS unsigned*)(lds + (bufoff) + ldsw + _i * 8192), 16, 0, 0); } while (0)
; #define PG8_LDA(dst, b, h) do { _Pragma("unroll") for (int m = 0; m < 4; ++m) _Pragma("unroll") for (int k = 0; k < 2; ++k) dst[m][k] = *(const LAS bf16x8*)(lds + PG8_SA(b, h) + aoff + m * 2048 + k * 1024); } while (0)
; #define PG8_LDB(dst, b, h) do { _Pragma("unroll") for (int n = 0; n < 2; ++n) _Pragma("unroll") for (int k = 0; k < 2; ++k) dst[n][k] = *(const LAS bf16x8*)(lds + PG8_SB(b, h) + boff + n * 2048 + k * 1024); } while (0)
; #define PG8_MMA(ai, bj, At, Bt) do { __builtin_amdgcn_s_setprio(1); _Pragma("unroll") for (int m = 0; m < 4; ++m) _Pragma("unroll") for (int n = 0; n < 2; ++n) _Pragma("unroll") for (int k = 0; k < 2; ++k) \
;         acc[ai][bj][m][n] = __builtin_amdgcn_mfma_f32_16x16x32_bf16(Bt[n][k], At[m][k], acc[ai][bj][m][n], 0, 0, 0); __builtin_amdgcn_s_setprio(0); } while (0)
; #define PG8_WAIT_V(n) asm volatile("s_waitcnt vmcnt(" #n ")" ::: "memory")
; #define PG8_WAIT_L(n) asm volatile("s_waitcnt lgkmcnt(" #n ")" ::: "memory")
; #define PG8_BAR __builtin_amdgcn_s_barrier()
; #define PG8_SCHED __builtin_amdgcn_sched_barrier(0)
; template <class Epi>
; __device__ __forceinline__ void gemm_phase(LAS unsigned char* lds, const Gemm g, const StaticOrder& S, const Epi& E, const int tid) {
;     ...
;             PG8_WAIT_V(8); PG8_WAIT_L(0); PG8_BAR; PG8_MMA(1, 0, At, B0); PG8_MMA(1, 1, At, B1); PG8_BAR; PG8_SCHED;
;             PG8_LDB(B0, 1, 0); PG8_LDB(B1, 1, 1); PG8_SCHED; PG8_LDA(At, 1, 0); PG8_STAGE(PG8_SA(0, 1), a2 + hstep, voffA);
;             PG8_WAIT_V(8); PG8_WAIT_L(0); PG8_BAR; PG8_MMA(0, 0, At, B0); PG8_MMA(0, 1, At, B1); PG8_BAR; PG8_SCHED;
	s_setprio 1
	s_waitcnt lgkmcnt(0)
	v_mfma_f32_16x16x32_bf16 v[94:97], v[18:21], v[182:185], v[94:97]
	v_mfma_f32_16x16x32_bf16 v[90:93], v[26:29], v[182:185], v[90:93]
	v_mfma_f32_16x16x32_bf16 v[78:81], v[18:21], v[212:215], v[78:81]
	v_mfma_f32_16x16x32_bf16 v[74:77], v[26:29], v[212:215], v[74:77]
	v_mfma_f32_16x16x32_bf16 v[62:65], v[18:21], v[220:223], v[62:65]
	v_mfma_f32_16x16x32_bf16 v[58:61], v[26:29], v[220:223], v[58:61]
	v_mfma_f32_16x16x32_bf16 v[14:17], v[18:21], v[228:231], v[14:17]
	v_mfma_f32_16x16x32_bf16 v[10:13], v[26:29], v[228:231], v[10:13]
	v_mfma_f32_16x16x32_bf16 v[94:97], v[22:25], v[186:189], v[94:97]
	v_mfma_f32_16x16x32_bf16 v[90:93], v[30:33], v[186:189], v[90:93]
	v_mfma_f32_16x16x32_bf16 v[78:81], v[22:25], v[216:219], v[78:81]
	v_mfma_f32_16x16x32_bf16 v[74:77], v[30:33], v[216:219], v[74:77]
	v_mfma_f32_16x16x32_bf16 v[62:65], v[22:25], v[224:227], v[62:65]
	v_mfma_f32_16x16x32_bf16 v[58:61], v[30:33], v[224:227], v[58:61]
	v_mfma_f32_16x16x32_bf16 v[14:17], v[22:25], v[232:235], v[14:17]
	v_mfma_f32_16x16x32_bf16 v[10:13], v[30:33], v[232:235], v[10:13]
	s_setprio 0
	s_setprio 1
	v_mfma_f32_16x16x32_bf16 v[38:41], v[42:45], v[220:223], v[38:41]
	v_mfma_f32_16x16x32_bf16 v[34:37], v[50:53], v[220:223], v[34:37]
	v_mfma_f32_16x16x32_bf16 v[6:9], v[42:45], v[228:231], v[6:9]
	v_mfma_f32_16x16x32_bf16 v[2:5], v[50:53], v[228:231], v[2:5]
	v_mfma_f32_16x16x32_bf16 v[18:21], v[42:45], v[182:185], v[86:89]
	v_mfma_f32_16x16x32_bf16 v[22:25], v[50:53], v[182:185], v[82:85]
	v_mfma_f32_16x16x32_bf16 v[26:29], v[42:45], v[212:215], v[70:73]
	v_mfma_f32_16x16x32_bf16 v[30:33], v[50:53], v[212:215], v[66:69]
	v_mfma_f32_16x16x32_bf16 v[38:41], v[46:49], v[224:227], v[38:41]
	v_mfma_f32_16x16x32_bf16 v[34:37], v[54:57], v[224:227], v[34:37]
	v_mfma_f32_16x16x32_bf16 v[6:9], v[46:49], v[232:235], v[6:9]
	v_mfma_f32_16x16x32_bf16 v[2:5], v[54:57], v[232:235], v[2:5]
	v_mfma_f32_16x16x32_bf16 v[18:21], v[46:49], v[186:189], v[18:21]
	v_mfma_f32_16x16x32_bf16 v[22:25], v[54:57], v[186:189], v[22:25]
	v_mfma_f32_16x16x32_bf16 v[26:29], v[46:49], v[216:219], v[26:29]
	v_mfma_f32_16x16x32_bf16 v[30:33], v[54:57], v[216:219], v[30:33]
	s_setprio 0
	s_barrier
	s_add_u32 s34, s34, 0x20000
	s_addc_u32 s35, s35, 0
	s_mov_b32 m0, s39
	s_nop 0
	global_load_lds_dwordx4 v162, s[34:35]
	s_mov_b32 m0, s44
	s_nop 0
	global_load_lds_dwordx4 v164, s[34:35]
	s_add_i32 s52, 0, 0x18000
	s_add_i32 s53, 0, 0x1c000
	v_add_u32_e32 v54, s52, v193
	v_add_u32_e32 v66, s53, v193
	ds_read_b128 v[42:45], v54
	ds_read_b128 v[46:49], v54 offset:1024
	ds_read_b128 v[50:53], v54 offset:2048
	ds_read_b128 v[54:57], v54 offset:3072
	ds_read_b128 v[182:185], v66
	ds_read_b128 v[186:189], v66 offset:1024
	ds_read_b128 v[212:215], v66 offset:2048
	ds_read_b128 v[216:219], v66 offset:3072
	ds_read_b128 v[66:69], v199 offset:32768
	ds_read_b128 v[70:73], v199 offset:33792
	ds_read_b128 v[82:85], v199 offset:34816
	ds_read_b128 v[86:89], v199 offset:35840
	ds_read_b128 v[220:223], v199 offset:36864
	ds_read_b128 v[224:227], v199 offset:37888
	ds_read_b128 v[228:231], v199 offset:38912
	ds_read_b128 v[232:235], v199 offset:39936
	s_waitcnt vmcnt(8)
	s_waitcnt lgkmcnt(0)
	s_barrier
	s_setprio 1
	s_waitcnt lgkmcnt(0)
	v_mfma_f32_16x16x32_bf16 v[158:161], v[42:45], v[66:69], v[158:161]
	v_mfma_f32_16x16x32_bf16 v[154:157], v[50:53], v[66:69], v[154:157]
	v_mfma_f32_16x16x32_bf16 v[142:145], v[42:45], v[82:85], v[142:145]
	v_mfma_f32_16x16x32_bf16 v[138:141], v[50:53], v[82:85], v[138:141]
	v_mfma_f32_16x16x32_bf16 v[126:129], v[42:45], v[220:223], v[126:129]
	v_mfma_f32_16x16x32_bf16 v[122:125], v[50:53], v[220:223], v[122:125]
	v_mfma_f32_16x16x32_bf16 v[110:113], v[42:45], v[228:231], v[110:113]
	v_mfma_f32_16x16x32_bf16 v[106:109], v[50:53], v[228:231], v[106:109]
	v_mfma_f32_16x16x32_bf16 v[158:161], v[46:49], v[70:73], v[158:161]
	v_mfma_f32_16x16x32_bf16 v[154:157], v[54:57], v[70:73], v[154:157]
	v_mfma_f32_16x16x32_bf16 v[142:145], v[46:49], v[86:89], v[142:145]
	v_mfma_f32_16x16x32_bf16 v[138:141], v[54:57], v[86:89], v[138:141]
	v_mfma_f32_16x16x32_bf16 v[126:129], v[46:49], v[224:227], v[126:129]
	v_mfma_f32_16x16x32_bf16 v[122:125], v[54:57], v[224:227], v[122:125]
	v_mfma_f32_16x16x32_bf16 v[110:113], v[46:49], v[232:235], v[110:113]
	v_mfma_f32_16x16x32_bf16 v[106:109], v[54:57], v[232:235], v[106:109]
	s_setprio 0
	s_setprio 1
	v_mfma_f32_16x16x32_bf16 v[150:153], v[182:185], v[66:69], v[150:153]
	v_mfma_f32_16x16x32_bf16 v[66:69], v[212:215], v[66:69], v[146:149]
	v_mfma_f32_16x16x32_bf16 v[146:149], v[216:219], v[70:73], v[66:69]
	v_mfma_f32_16x16x32_bf16 v[66:69], v[182:185], v[82:85], v[134:137]
	v_mfma_f32_16x16x32_bf16 v[134:137], v[186:189], v[86:89], v[66:69]
	v_mfma_f32_16x16x32_bf16 v[66:69], v[212:215], v[82:85], v[130:133]
	v_mfma_f32_16x16x32_bf16 v[130:133], v[216:219], v[86:89], v[66:69]
	v_mfma_f32_16x16x32_bf16 v[66:69], v[182:185], v[220:223], v[118:121]
	v_mfma_f32_16x16x32_bf16 v[118:121], v[186:189], v[224:227], v[66:69]
	v_mfma_f32_16x16x32_bf16 v[66:69], v[212:215], v[220:223], v[114:117]
	v_mfma_f32_16x16x32_bf16 v[114:117], v[216:219], v[224:227], v[66:69]
	v_mfma_f32_16x16x32_bf16 v[66:69], v[182:185], v[228:231], v[102:105]
	v_mfma_f32_16x16x32_bf16 v[102:105], v[186:189], v[232:235], v[66:69]
	v_mfma_f32_16x16x32_bf16 v[66:69], v[212:215], v[228:231], v[98:101]
	v_mfma_f32_16x16x32_bf16 v[150:153], v[186:189], v[70:73], v[150:153]
	v_mfma_f32_16x16x32_bf16 v[98:101], v[216:219], v[232:235], v[66:69]
	s_setprio 0
	s_barrier
; #define PG8_STAGE(bufoff, gbase, voff) do { _Pragma("unroll") for (int _i = 0; _i < 2; ++_i) \
;         __builtin_amdgcn_global_load_lds((const unsigned*)((const char*)(gbase) + (voff)[_i]), (LAS unsigned*)(lds + (bufoff) + ldsw + _i * 8192), 16, 0, 0); } while (0)
; #define PG8_LDA(dst, b, h) do { _Pragma("unroll") for (int m = 0; m < 4; ++m) _Pragma("unroll") for (int k = 0; k < 2; ++k) dst[m][k] = *(const LAS bf16x8*)(lds + PG8_SA(b, h) + aoff + m * 2048 + k * 1024); } while (0)
; #define PG8_MMA(ai, bj, At, Bt) do { __builtin_amdgcn_s_setprio(1); _Pragma("unroll") for (int m = 0; m < 4; ++m) _Pragma("unroll") for (int n = 0; n < 2; ++n) _Pragma("unroll") for (int k = 0; k < 2; ++k) \
;         acc[ai][bj][m][n] = __builtin_amdgcn_mfma_f32_16x16x32_bf16(Bt[n][k], At[m][k], acc[ai][bj][m][n], 0, 0, 0); __builtin_amdgcn_s_setprio(0); } while (0)
; #define PG8_WAIT_V(n) asm volatile("s_waitcnt vmcnt(" #n ")" ::: "memory")
; #define PG8_WAIT_L(n) asm volatile("s_waitcnt lgkmcnt(" #n ")" ::: "memory")
; #define PG8_BAR __builtin_amdgcn_s_barrier()
; #define PG8_SCHED __builtin_amdgcn_sched_barrier(0)
; template <class Epi>
; __device__ __forceinline__ void gemm_phase(LAS unsigned char* lds, const Gemm g, const StaticOrder& S, const Epi& E, const int tid) {
;     ...
;             const char* a1 = (s1 ? cA2 + (size_t)(t - nt + 1) * kstep : cA + (size_t)(t + 1) * kstep);
;             const char* a2 = last ? nA : (s2 ? cA2 + (size_t)(t + 2 - nt) * kstep : cA + (size_t)(t + 2) * kstep);
;             const char* b2 = last ? nB : (s2 ? cB2 + (size_t)(t + 2 - nt) * kstep : cB + (size_t)(t + 2) * kstep);
;             const char* a3 = a2 + kstep; const char* b3 = b2 + kstep;
;     ...
;             PG8_LDA(At, 1, 1); PG8_STAGE(PG8_SB(1, 0), b3, voffB); PG8_STAGE(PG8_SB(1, 1), b3 + bhs, voffB); PG8_STAGE(PG8_SA(1, 0), a3, voffA);
;             PG8_WAIT_V(8); PG8_WAIT_L(0); PG8_BAR; PG8_MMA(1, 0, At, B0); PG8_MMA(1, 1, At, B1); PG8_BAR; PG8_SCHED;
	s_add_i32 s34, s52, s36
	v_lshl_add_u64 v[82:83], v[172:173], 0, s[70:71]
	s_mov_b32 m0, s34
	s_nop 0
	ds_read_b128 v[66:69], v199 offset:49152
	global_load_lds_dwordx4 v[82:83], off
	ds_read_b128 v[70:73], v199 offset:50176
	ds_read_b128 v[220:223], v199 offset:51200
	s_add_i32 m0, s34, 0x2000
	s_add_u32 s30, s30, 0x2080
	v_lshl_add_u64 v[82:83], v[174:175], 0, s[70:71]
	s_addc_u32 s31, s31, 0
	s_add_i32 s34, s53, s36
	global_load_lds_dwordx4 v[82:83], off
	ds_read_b128 v[224:227], v199 offset:52224
	ds_read_b128 v[228:231], v199 offset:53248
	v_lshl_add_u64 v[82:83], s[30:31], 0, v[0:1]
	s_mov_b32 m0, s34
	s_nop 0
	global_load_lds_dwordx4 v[82:83], off
	ds_read_b128 v[232:235], v199 offset:54272
	ds_read_b128 v[236:239], v199 offset:55296
	v_lshl_add_u64 v[82:83], s[30:31], 0, v[166:167]
	s_add_i32 m0, s34, 0x2000
	s_nop 0
	global_load_lds_dwordx4 v[82:83], off
	ds_read_b128 v[240:243], v199 offset:56320
	v_lshl_add_u64 v[82:83], v[176:177], 0, s[70:71]
	s_mov_b32 m0, s45
	s_nop 0
	global_load_lds_dwordx4 v[82:83], off
	v_lshl_add_u64 v[82:83], v[200:201], 0, s[70:71]
	s_mov_b32 m0, s46
	s_nop 0
	global_load_lds_dwordx4 v[82:83], off
	s_waitcnt vmcnt(8)
	s_waitcnt lgkmcnt(0)
	s_barrier
	s_setprio 1
	s_waitcnt lgkmcnt(0)
	v_mfma_f32_16x16x32_bf16 v[82:85], v[42:45], v[66:69], v[94:97]
	v_mfma_f32_16x16x32_bf16 v[94:97], v[46:49], v[70:73], v[82:85]
	v_mfma_f32_16x16x32_bf16 v[82:85], v[50:53], v[66:69], v[90:93]
	v_mfma_f32_16x16x32_bf16 v[78:81], v[42:45], v[220:223], v[78:81]
	v_mfma_f32_16x16x32_bf16 v[74:77], v[50:53], v[220:223], v[74:77]
	v_mfma_f32_16x16x32_bf16 v[62:65], v[42:45], v[228:231], v[62:65]
	v_mfma_f32_16x16x32_bf16 v[58:61], v[50:53], v[228:231], v[58:61]
	v_mfma_f32_16x16x32_bf16 v[14:17], v[42:45], v[236:239], v[14:17]
	v_mfma_f32_16x16x32_bf16 v[10:13], v[50:53], v[236:239], v[10:13]
	v_mfma_f32_16x16x32_bf16 v[90:93], v[54:57], v[70:73], v[82:85]
	v_mfma_f32_16x16x32_bf16 v[78:81], v[46:49], v[224:227], v[78:81]
	v_mfma_f32_16x16x32_bf16 v[74:77], v[54:57], v[224:227], v[74:77]
	v_mfma_f32_16x16x32_bf16 v[62:65], v[46:49], v[232:235], v[62:65]
	v_mfma_f32_16x16x32_bf16 v[58:61], v[54:57], v[232:235], v[58:61]
	v_mfma_f32_16x16x32_bf16 v[14:17], v[46:49], v[240:243], v[14:17]
	v_mfma_f32_16x16x32_bf16 v[10:13], v[54:57], v[240:243], v[10:13]
	s_setprio 0
	s_setprio 1
	v_mfma_f32_16x16x32_bf16 v[18:21], v[182:185], v[66:69], v[18:21]
	v_mfma_f32_16x16x32_bf16 v[86:89], v[186:189], v[70:73], v[18:21]
	v_mfma_f32_16x16x32_bf16 v[18:21], v[212:215], v[66:69], v[22:25]
	v_mfma_f32_16x16x32_bf16 v[82:85], v[216:219], v[70:73], v[18:21]
	v_mfma_f32_16x16x32_bf16 v[18:21], v[182:185], v[220:223], v[26:29]
	v_mfma_f32_16x16x32_bf16 v[70:73], v[186:189], v[224:227], v[18:21]
	v_mfma_f32_16x16x32_bf16 v[18:21], v[212:215], v[220:223], v[30:33]
	v_mfma_f32_16x16x32_bf16 v[66:69], v[216:219], v[224:227], v[18:21]
	v_mfma_f32_16x16x32_bf16 v[18:21], v[182:185], v[228:231], v[38:41]
	v_mfma_f32_16x16x32_bf16 v[38:41], v[186:189], v[232:235], v[18:21]
	v_mfma_f32_16x16x32_bf16 v[18:21], v[212:215], v[228:231], v[34:37]
	v_mfma_f32_16x16x32_bf16 v[6:9], v[182:185], v[236:239], v[6:9]
	v_mfma_f32_16x16x32_bf16 v[2:5], v[212:215], v[236:239], v[2:5]
	v_mfma_f32_16x16x32_bf16 v[34:37], v[216:219], v[232:235], v[18:21]
	v_mfma_f32_16x16x32_bf16 v[6:9], v[186:189], v[240:243], v[6:9]
	v_mfma_f32_16x16x32_bf16 v[2:5], v[216:219], v[240:243], v[2:5]
	s_setprio 0
	s_barrier
	s_add_i32 s51, s51, 2
	s_add_u32 s49, s49, 0x100
	s_addc_u32 s50, s50, 0
	s_add_u32 s28, s28, 0x100
	s_addc_u32 s29, s29, 0
	s_cmp_gt_u32 s51, 5
	s_cbranch_scc0 .LBB0_206
	s_and_b64 vcc, exec, s[12:13]
	s_cbranch_vccz .LBB0_209
	s_barrier

; #define PG8_STAGE(bufoff, gbase, voff) do { _Pragma("unroll") for (int _i = 0; _i < 2; ++_i) \
;         __builtin_amdgcn_global_load_lds((const unsigned*)((const char*)(gbase) + (voff)[_i]), (LAS unsigned*)(lds + (bufoff) + ldsw + _i * 8192), 16, 0, 0); } while (0)
; #define PG8_LDA(dst, b, h) do { _Pragma("unroll") for (int m = 0; m < 4; ++m) _Pragma("unroll") for (int k = 0; k < 2; ++k) dst[m][k] = *(const LAS bf16x8*)(lds + PG8_SA(b, h) + aoff + m * 2048 + k * 1024); } while (0)
; #define PG8_LDB(dst, b, h) do { _Pragma("unroll") for (int n = 0; n < 2; ++n) _Pragma("unroll") for (int k = 0; k < 2; ++k) dst[n][k] = *(const LAS bf16x8*)(lds + PG8_SB(b, h) + boff + n * 2048 + k * 1024); } while (0)
; #define PG8_MMA(ai, bj, At, Bt) do { __builtin_amdgcn_s_setprio(1); _Pragma("unroll") for (int m = 0; m < 4; ++m) _Pragma("unroll") for (int n = 0; n < 2; ++n) _Pragma("unroll") for (int k = 0; k < 2; ++k) \
;         acc[ai][bj][m][n] = __builtin_amdgcn_mfma_f32_16x16x32_bf16(Bt[n][k], At[m][k], acc[ai][bj][m][n], 0, 0, 0); __builtin_amdgcn_s_setprio(0); } while (0)
; #define PG8_WAIT_V(n) asm volatile("s_waitcnt vmcnt(" #n ")" ::: "memory")
; #define PG8_WAIT_L(n) asm volatile("s_waitcnt lgkmcnt(" #n ")" ::: "memory")
; #define PG8_BAR __builtin_amdgcn_s_barrier()
; #define PG8_SCHED __builtin_amdgcn_sched_barrier(0)
; template <class Epi>
; __device__ __forceinline__ void gemm_phase(LAS unsigned char* lds, const Gemm g, const StaticOrder& S, const Epi& E, const int tid) {
;     ...
;             PG8_LDB(B0, 0, 0); PG8_LDB(B1, 0, 1); PG8_SCHED; PG8_LDA(At, 0, 0); PG8_STAGE(PG8_SA(1, 1), a1 + hstep, voffA);
;             PG8_WAIT_V(8); PG8_WAIT_L(0); PG8_BAR; PG8_MMA(0, 0, At, B0); PG8_MMA(0, 1, At, B1); PG8_BAR; PG8_SCHED;
;             PG8_LDA(At, 0, 1); PG8_STAGE(PG8_SB(0, 0), b2, voffB); PG8_STAGE(PG8_SB(0, 1), b2 + bhs, voffB); PG8_STAGE(PG8_SA(0, 0), a2, voffA);
;             PG8_WAIT_V(8); PG8_WAIT_L(0); PG8_BAR; PG8_MMA(1, 0, At, B0); PG8_MMA(1, 1, At, B1); PG8_BAR; PG8_SCHED;
.LBB0_261:
	s_add_i32 m0, s2, 0xc000
	s_nop 0
	global_load_lds_dwordx4 v140, s[28:29]
	s_add_i32 m0, s2, 0xe000
	s_nop 0
	global_load_lds_dwordx4 v138, s[28:29]
	s_add_u32 s30, s28, 0xfff80080
	s_addc_u32 s31, s29, -1
	s_add_i32 s49, 0, 0x10000
	s_cmp_eq_u32 s48, 28
	s_cselect_b32 s35, s19, s31
	s_cselect_b32 s34, s44, s30
	v_add_u32_e32 v142, s49, v149
	s_cselect_b32 s31, s17, s47
	s_cselect_b32 s30, s45, s46
	s_add_i32 s52, 0, 0x14000
	ds_read_b128 v[156:159], v142
	ds_read_b128 v[160:163], v142 offset:1024
	ds_read_b128 v[164:167], v142 offset:2048
	ds_read_b128 v[178:181], v142 offset:3072
	v_add_u32_e32 v142, s52, v149
	ds_read_b128 v[182:185], v142
	ds_read_b128 v[186:189], v142 offset:1024
	ds_read_b128 v[190:193], v142 offset:2048
	ds_read_b128 v[194:197], v142 offset:3072
	ds_read_b128 v[198:201], v154
	ds_read_b128 v[212:215], v154 offset:1024
	ds_read_b128 v[216:219], v154 offset:2048
	ds_read_b128 v[220:223], v154 offset:3072
	ds_read_b128 v[224:227], v154 offset:4096
	ds_read_b128 v[228:231], v154 offset:5120
	ds_read_b128 v[232:235], v154 offset:6144
	ds_read_b128 v[236:239], v154 offset:7168
	s_waitcnt vmcnt(8)
	s_waitcnt lgkmcnt(0)
	s_barrier
	s_setprio 1
	s_waitcnt lgkmcnt(0)
	v_mfma_f32_16x16x32_bf16 v[126:129], v[156:159], v[198:201], v[126:129]
	v_mfma_f32_16x16x32_bf16 v[122:125], v[164:167], v[198:201], v[122:125]
	v_mfma_f32_16x16x32_bf16 v[110:113], v[156:159], v[216:219], v[110:113]
	v_mfma_f32_16x16x32_bf16 v[106:109], v[164:167], v[216:219], v[106:109]
	v_mfma_f32_16x16x32_bf16 v[94:97], v[156:159], v[224:227], v[94:97]
	v_mfma_f32_16x16x32_bf16 v[90:93], v[164:167], v[224:227], v[90:93]
	v_mfma_f32_16x16x32_bf16 v[78:81], v[156:159], v[232:235], v[78:81]
	v_mfma_f32_16x16x32_bf16 v[74:77], v[164:167], v[232:235], v[74:77]
	v_mfma_f32_16x16x32_bf16 v[126:129], v[160:163], v[212:215], v[126:129]
	v_mfma_f32_16x16x32_bf16 v[122:125], v[178:181], v[212:215], v[122:125]
	v_mfma_f32_16x16x32_bf16 v[110:113], v[160:163], v[220:223], v[110:113]
	v_mfma_f32_16x16x32_bf16 v[106:109], v[178:181], v[220:223], v[106:109]
	v_mfma_f32_16x16x32_bf16 v[94:97], v[160:163], v[228:231], v[94:97]
	v_mfma_f32_16x16x32_bf16 v[90:93], v[178:181], v[228:231], v[90:93]
	v_mfma_f32_16x16x32_bf16 v[78:81], v[160:163], v[236:239], v[78:81]
	v_mfma_f32_16x16x32_bf16 v[74:77], v[178:181], v[236:239], v[74:77]
	s_setprio 0
	s_setprio 1
	v_mfma_f32_16x16x32_bf16 v[118:121], v[182:185], v[198:201], v[118:121]
	v_mfma_f32_16x16x32_bf16 v[114:117], v[190:193], v[198:201], v[114:117]
	v_mfma_f32_16x16x32_bf16 v[102:105], v[182:185], v[216:219], v[102:105]
	v_mfma_f32_16x16x32_bf16 v[98:101], v[190:193], v[216:219], v[98:101]
	v_mfma_f32_16x16x32_bf16 v[86:89], v[182:185], v[224:227], v[86:89]
	v_mfma_f32_16x16x32_bf16 v[82:85], v[190:193], v[224:227], v[82:85]
	v_mfma_f32_16x16x32_bf16 v[70:73], v[182:185], v[232:235], v[70:73]
	v_mfma_f32_16x16x32_bf16 v[66:69], v[190:193], v[232:235], v[66:69]
	v_mfma_f32_16x16x32_bf16 v[118:121], v[186:189], v[212:215], v[118:121]
	v_mfma_f32_16x16x32_bf16 v[114:117], v[194:197], v[212:215], v[114:117]
	v_mfma_f32_16x16x32_bf16 v[102:105], v[186:189], v[220:223], v[102:105]
	v_mfma_f32_16x16x32_bf16 v[98:101], v[194:197], v[220:223], v[98:101]
	v_mfma_f32_16x16x32_bf16 v[86:89], v[186:189], v[228:231], v[86:89]
	v_mfma_f32_16x16x32_bf16 v[82:85], v[194:197], v[228:231], v[82:85]
	v_mfma_f32_16x16x32_bf16 v[70:73], v[186:189], v[236:239], v[70:73]
	v_mfma_f32_16x16x32_bf16 v[66:69], v[194:197], v[236:239], v[66:69]
	s_setprio 0
	s_barrier
	s_add_i32 s49, s49, s36
	v_lshl_add_u64 v[142:143], s[30:31], 0, v[0:1]
	s_mov_b32 m0, s49
	ds_read_b128 v[198:201], v154 offset:16384
	global_load_lds_dwordx4 v[142:143], off
	ds_read_b128 v[212:215], v154 offset:17408
	ds_read_b128 v[216:219], v154 offset:18432
	s_add_i32 m0, s49, 0x2000
	s_add_u32 s50, s30, 0x8000
	v_lshl_add_u64 v[168:169], s[30:31], 0, v[134:135]
	s_addc_u32 s51, s31, 0
	s_add_i32 s49, s52, s36
	global_load_lds_dwordx4 v[168:169], off
	ds_read_b128 v[220:223], v154 offset:19456
	ds_read_b128 v[224:227], v154 offset:20480
	v_lshl_add_u64 v[172:173], s[50:51], 0, v[0:1]
	s_mov_b32 m0, s49
	v_lshl_add_u64 v[174:175], s[34:35], 0, v[132:133]
	global_load_lds_dwordx4 v[172:173], off
	ds_read_b128 v[228:231], v154 offset:21504
	ds_read_b128 v[232:235], v154 offset:22528
	v_lshl_add_u64 v[172:173], s[50:51], 0, v[134:135]
	s_add_i32 m0, s49, 0x2000
	s_nop 0
	global_load_lds_dwordx4 v[172:173], off
	ds_read_b128 v[236:239], v154 offset:23552
	v_lshl_add_u64 v[172:173], s[34:35], 0, v[130:131]
	s_mov_b32 m0, s2
	s_nop 0
	global_load_lds_dwordx4 v[172:173], off
	s_mov_b32 m0, s27
	s_nop 0
	global_load_lds_dwordx4 v[174:175], off
	s_waitcnt vmcnt(8)
	s_waitcnt lgkmcnt(0)
	s_barrier
; #define PG8_STAGE(bufoff, gbase, voff) do { _Pragma("unroll") for (int _i = 0; _i < 2; ++_i) \
;         __builtin_amdgcn_global_load_lds((const unsigned*)((const char*)(gbase) + (voff)[_i]), (LAS unsigned*)(lds + (bufoff) + ldsw + _i * 8192), 16, 0, 0); } while (0)
; #define PG8_LDA(dst, b, h) do { _Pragma("unroll") for (int m = 0; m < 4; ++m) _Pragma("unroll") for (int k = 0; k < 2; ++k) dst[m][k] = *(const LAS bf16x8*)(lds + PG8_SA(b, h) + aoff + m * 2048 + k * 1024); } while (0)
; #define PG8_LDB(dst, b, h) do { _Pragma("unroll") for (int n = 0; n < 2; ++n) _Pragma("unroll") for (int k = 0; k < 2; ++k) dst[n][k] = *(const LAS bf16x8*)(lds + PG8_SB(b, h) + boff + n * 2048 + k * 1024); } while (0)
; #define PG8_MMA(ai, bj, At, Bt) do { __builtin_amdgcn_s_setprio(1); _Pragma("unroll") for (int m = 0; m < 4; ++m) _Pragma("unroll") for (int n = 0; n < 2; ++n) _Pragma("unroll") for (int k = 0; k < 2; ++k) \
;         acc[ai][bj][m][n] = __builtin_amdgcn_mfma_f32_16x16x32_bf16(Bt[n][k], At[m][k], acc[ai][bj][m][n], 0, 0, 0); __builtin_amdgcn_s_setprio(0); } while (0)
; #define PG8_WAIT_V(n) asm volatile("s_waitcnt vmcnt(" #n ")" ::: "memory")
; #define PG8_WAIT_L(n) asm volatile("s_waitcnt lgkmcnt(" #n ")" ::: "memory")
; #define PG8_BAR __builtin_amdgcn_s_barrier()
; #define PG8_SCHED __builtin_amdgcn_sched_barrier(0)
; template <class Epi>
; __device__ __forceinline__ void gemm_phase(LAS unsigned char* lds, const Gemm g, const StaticOrder& S, const Epi& E, const int tid) {
;     ...
;             PG8_WAIT_V(8); PG8_WAIT_L(0); PG8_BAR; PG8_MMA(1, 0, At, B0); PG8_MMA(1, 1, At, B1); PG8_BAR; PG8_SCHED;
;             PG8_LDB(B0, 1, 0); PG8_LDB(B1, 1, 1); PG8_SCHED; PG8_LDA(At, 1, 0); PG8_STAGE(PG8_SA(0, 1), a2 + hstep, voffA);
;             PG8_WAIT_V(8); PG8_WAIT_L(0); PG8_BAR; PG8_MMA(0, 0, At, B0); PG8_MMA(0, 1, At, B1); PG8_BAR; PG8_SCHED;
	s_setprio 1
	s_waitcnt lgkmcnt(0)
	v_mfma_f32_16x16x32_bf16 v[62:65], v[156:159], v[198:201], v[62:65]
	v_mfma_f32_16x16x32_bf16 v[58:61], v[164:167], v[198:201], v[58:61]
	v_mfma_f32_16x16x32_bf16 v[46:49], v[156:159], v[216:219], v[46:49]
	v_mfma_f32_16x16x32_bf16 v[42:45], v[164:167], v[216:219], v[42:45]
	v_mfma_f32_16x16x32_bf16 v[30:33], v[156:159], v[224:227], v[30:33]
	v_mfma_f32_16x16x32_bf16 v[26:29], v[164:167], v[224:227], v[26:29]
	v_mfma_f32_16x16x32_bf16 v[14:17], v[156:159], v[232:235], v[14:17]
	v_mfma_f32_16x16x32_bf16 v[10:13], v[164:167], v[232:235], v[10:13]
	v_mfma_f32_16x16x32_bf16 v[62:65], v[160:163], v[212:215], v[62:65]
	v_mfma_f32_16x16x32_bf16 v[58:61], v[178:181], v[212:215], v[58:61]
	v_mfma_f32_16x16x32_bf16 v[46:49], v[160:163], v[220:223], v[46:49]
	v_mfma_f32_16x16x32_bf16 v[42:45], v[178:181], v[220:223], v[42:45]
	v_mfma_f32_16x16x32_bf16 v[30:33], v[160:163], v[228:231], v[30:33]
	v_mfma_f32_16x16x32_bf16 v[26:29], v[178:181], v[228:231], v[26:29]
	v_mfma_f32_16x16x32_bf16 v[14:17], v[160:163], v[236:239], v[14:17]
	v_mfma_f32_16x16x32_bf16 v[10:13], v[178:181], v[236:239], v[10:13]
	s_setprio 0
	s_setprio 1
	v_mfma_f32_16x16x32_bf16 v[54:57], v[182:185], v[198:201], v[54:57]
	v_mfma_f32_16x16x32_bf16 v[50:53], v[190:193], v[198:201], v[50:53]
	v_mfma_f32_16x16x32_bf16 v[38:41], v[182:185], v[216:219], v[38:41]
	v_mfma_f32_16x16x32_bf16 v[34:37], v[190:193], v[216:219], v[34:37]
	v_mfma_f32_16x16x32_bf16 v[22:25], v[182:185], v[224:227], v[22:25]
	v_mfma_f32_16x16x32_bf16 v[18:21], v[190:193], v[224:227], v[18:21]
	v_mfma_f32_16x16x32_bf16 v[6:9], v[182:185], v[232:235], v[6:9]
	v_mfma_f32_16x16x32_bf16 v[2:5], v[190:193], v[232:235], v[2:5]
	v_mfma_f32_16x16x32_bf16 v[54:57], v[186:189], v[212:215], v[54:57]
	v_mfma_f32_16x16x32_bf16 v[50:53], v[194:197], v[212:215], v[50:53]
	v_mfma_f32_16x16x32_bf16 v[38:41], v[186:189], v[220:223], v[38:41]
	v_mfma_f32_16x16x32_bf16 v[34:37], v[194:197], v[220:223], v[34:37]
	v_mfma_f32_16x16x32_bf16 v[22:25], v[186:189], v[228:231], v[22:25]
	v_mfma_f32_16x16x32_bf16 v[18:21], v[194:197], v[228:231], v[18:21]
	v_mfma_f32_16x16x32_bf16 v[6:9], v[186:189], v[236:239], v[6:9]
	v_mfma_f32_16x16x32_bf16 v[2:5], v[194:197], v[236:239], v[2:5]
	s_setprio 0
	s_barrier
	s_add_u32 s34, s34, 0x80000
	s_addc_u32 s35, s35, 0
	s_mov_b32 m0, s37
	s_nop 0
	global_load_lds_dwordx4 v130, s[34:35]
	s_mov_b32 m0, s38
	s_nop 0
	global_load_lds_dwordx4 v132, s[34:35]
	s_add_i32 s49, 0, 0x18000
	v_add_u32_e32 v155, s49, v149
	s_add_i32 s50, 0, 0x1c000
	ds_read_b128 v[156:159], v155
	ds_read_b128 v[160:163], v155 offset:1024
	ds_read_b128 v[164:167], v155 offset:2048
	ds_read_b128 v[178:181], v155 offset:3072
	v_add_u32_e32 v155, s50, v149
	ds_read_b128 v[182:185], v155
	ds_read_b128 v[186:189], v155 offset:1024
	ds_read_b128 v[190:193], v155 offset:2048
	ds_read_b128 v[194:197], v155 offset:3072
	ds_read_b128 v[198:201], v154 offset:32768
	ds_read_b128 v[212:215], v154 offset:33792
	ds_read_b128 v[216:219], v154 offset:34816
	ds_read_b128 v[220:223], v154 offset:35840
	ds_read_b128 v[224:227], v154 offset:36864
	ds_read_b128 v[228:231], v154 offset:37888
	ds_read_b128 v[232:235], v154 offset:38912
	ds_read_b128 v[236:239], v154 offset:39936
	s_waitcnt vmcnt(8)
	s_waitcnt lgkmcnt(0)
	s_barrier
	s_setprio 1
	s_waitcnt lgkmcnt(0)
	v_mfma_f32_16x16x32_bf16 v[126:129], v[156:159], v[198:201], v[126:129]
	v_mfma_f32_16x16x32_bf16 v[122:125], v[164:167], v[198:201], v[122:125]
	v_mfma_f32_16x16x32_bf16 v[110:113], v[156:159], v[216:219], v[110:113]
	v_mfma_f32_16x16x32_bf16 v[106:109], v[164:167], v[216:219], v[106:109]
	v_mfma_f32_16x16x32_bf16 v[94:97], v[156:159], v[224:227], v[94:97]
	v_mfma_f32_16x16x32_bf16 v[90:93], v[164:167], v[224:227], v[90:93]
	v_mfma_f32_16x16x32_bf16 v[78:81], v[156:159], v[232:235], v[78:81]
	v_mfma_f32_16x16x32_bf16 v[74:77], v[164:167], v[232:235], v[74:77]
	v_mfma_f32_16x16x32_bf16 v[126:129], v[160:163], v[212:215], v[126:129]
	v_mfma_f32_16x16x32_bf16 v[122:125], v[178:181], v[212:215], v[122:125]
	v_mfma_f32_16x16x32_bf16 v[110:113], v[160:163], v[220:223], v[110:113]
	v_mfma_f32_16x16x32_bf16 v[106:109], v[178:181], v[220:223], v[106:109]
	v_mfma_f32_16x16x32_bf16 v[94:97], v[160:163], v[228:231], v[94:97]
	v_mfma_f32_16x16x32_bf16 v[90:93], v[178:181], v[228:231], v[90:93]
	v_mfma_f32_16x16x32_bf16 v[78:81], v[160:163], v[236:239], v[78:81]
	v_mfma_f32_16x16x32_bf16 v[74:77], v[178:181], v[236:239], v[74:77]
	s_setprio 0
	s_setprio 1
	v_mfma_f32_16x16x32_bf16 v[118:121], v[182:185], v[198:201], v[118:121]
	v_mfma_f32_16x16x32_bf16 v[114:117], v[190:193], v[198:201], v[114:117]
	v_mfma_f32_16x16x32_bf16 v[102:105], v[182:185], v[216:219], v[102:105]
	v_mfma_f32_16x16x32_bf16 v[98:101], v[190:193], v[216:219], v[98:101]
	v_mfma_f32_16x16x32_bf16 v[86:89], v[182:185], v[224:227], v[86:89]
	v_mfma_f32_16x16x32_bf16 v[82:85], v[190:193], v[224:227], v[82:85]
	v_mfma_f32_16x16x32_bf16 v[70:73], v[182:185], v[232:235], v[70:73]
	v_mfma_f32_16x16x32_bf16 v[66:69], v[190:193], v[232:235], v[66:69]
	v_mfma_f32_16x16x32_bf16 v[118:121], v[186:189], v[212:215], v[118:121]
	v_mfma_f32_16x16x32_bf16 v[114:117], v[194:197], v[212:215], v[114:117]
	v_mfma_f32_16x16x32_bf16 v[102:105], v[186:189], v[220:223], v[102:105]
	v_mfma_f32_16x16x32_bf16 v[98:101], v[194:197], v[220:223], v[98:101]
	v_mfma_f32_16x16x32_bf16 v[86:89], v[186:189], v[228:231], v[86:89]
	v_mfma_f32_16x16x32_bf16 v[82:85], v[194:197], v[228:231], v[82:85]
	v_mfma_f32_16x16x32_bf16 v[70:73], v[186:189], v[236:239], v[70:73]
	v_mfma_f32_16x16x32_bf16 v[66:69], v[194:197], v[236:239], v[66:69]
	s_setprio 0
	s_barrier
; #define PG8_STAGE(bufoff, gbase, voff) do { _Pragma("unroll") for (int _i = 0; _i < 2; ++_i) \
;         __builtin_amdgcn_global_load_lds((const unsigned*)((const char*)(gbase) + (voff)[_i]), (LAS unsigned*)(lds + (bufoff) + ldsw + _i * 8192), 16, 0, 0); } while (0)
; #define PG8_LDA(dst, b, h) do { _Pragma("unroll") for (int m = 0; m < 4; ++m) _Pragma("unroll") for (int k = 0; k < 2; ++k) dst[m][k] = *(const LAS bf16x8*)(lds + PG8_SA(b, h) + aoff + m * 2048 + k * 1024); } while (0)
; #define PG8_MMA(ai, bj, At, Bt) do { __builtin_amdgcn_s_setprio(1); _Pragma("unroll") for (int m = 0; m < 4; ++m) _Pragma("unroll") for (int n = 0; n < 2; ++n) _Pragma("unroll") for (int k = 0; k < 2; ++k) \
;         acc[ai][bj][m][n] = __builtin_amdgcn_mfma_f32_16x16x32_bf16(Bt[n][k], At[m][k], acc[ai][bj][m][n], 0, 0, 0); __builtin_amdgcn_s_setprio(0); } while (0)
; #define PG8_WAIT_V(n) asm volatile("s_waitcnt vmcnt(" #n ")" ::: "memory")
; #define PG8_WAIT_L(n) asm volatile("s_waitcnt lgkmcnt(" #n ")" ::: "memory")
; #define PG8_BAR __builtin_amdgcn_s_barrier()
; #define PG8_SCHED __builtin_amdgcn_sched_barrier(0)
; template <class Epi>
; __device__ __forceinline__ void gemm_phase(LAS unsigned char* lds, const Gemm g, const StaticOrder& S, const Epi& E, const int tid) {
;     ...
;             const char* a1 = (s1 ? cA2 + (size_t)(t - nt + 1) * kstep : cA + (size_t)(t + 1) * kstep);
;             const char* a2 = last ? nA : (s2 ? cA2 + (size_t)(t + 2 - nt) * kstep : cA + (size_t)(t + 2) * kstep);
;             const char* b2 = last ? nB : (s2 ? cB2 + (size_t)(t + 2 - nt) * kstep : cB + (size_t)(t + 2) * kstep);
;             const char* a3 = a2 + kstep; const char* b3 = b2 + kstep;
;     ...
;             PG8_LDA(At, 1, 1); PG8_STAGE(PG8_SB(1, 0), b3, voffB); PG8_STAGE(PG8_SB(1, 1), b3 + bhs, voffB); PG8_STAGE(PG8_SA(1, 0), a3, voffA);
;             PG8_WAIT_V(8); PG8_WAIT_L(0); PG8_BAR; PG8_MMA(1, 0, At, B0); PG8_MMA(1, 1, At, B1); PG8_BAR; PG8_SCHED;
	s_add_i32 s34, s49, s36
	v_lshl_add_u64 v[142:143], v[142:143], 0, s[70:71]
	s_mov_b32 m0, s34
	ds_read_b128 v[198:201], v154 offset:49152
	global_load_lds_dwordx4 v[142:143], off
	ds_read_b128 v[212:215], v154 offset:50176
	ds_read_b128 v[216:219], v154 offset:51200
	s_add_i32 m0, s34, 0x2000
	s_add_u32 s30, s30, 0x8080
	v_lshl_add_u64 v[142:143], v[168:169], 0, s[70:71]
	s_addc_u32 s31, s31, 0
	s_add_i32 s34, s50, s36
	global_load_lds_dwordx4 v[142:143], off
	ds_read_b128 v[220:223], v154 offset:52224
	ds_read_b128 v[224:227], v154 offset:53248
	v_lshl_add_u64 v[142:143], s[30:31], 0, v[0:1]
	s_mov_b32 m0, s34
	s_nop 0
	global_load_lds_dwordx4 v[142:143], off
	ds_read_b128 v[228:231], v154 offset:54272
	ds_read_b128 v[232:235], v154 offset:55296
	v_lshl_add_u64 v[142:143], s[30:31], 0, v[134:135]
	s_add_i32 m0, s34, 0x2000
	s_nop 0
	global_load_lds_dwordx4 v[142:143], off
	ds_read_b128 v[236:239], v154 offset:56320
	v_lshl_add_u64 v[142:143], v[172:173], 0, s[70:71]
	s_mov_b32 m0, s39
	s_nop 0
	global_load_lds_dwordx4 v[142:143], off
	v_lshl_add_u64 v[142:143], v[174:175], 0, s[70:71]
	s_mov_b32 m0, s40
	s_nop 0
	global_load_lds_dwordx4 v[142:143], off
	s_waitcnt vmcnt(8)
	s_waitcnt lgkmcnt(0)
	s_barrier
	s_setprio 1
	s_waitcnt lgkmcnt(0)
	v_mfma_f32_16x16x32_bf16 v[62:65], v[156:159], v[198:201], v[62:65]
	v_mfma_f32_16x16x32_bf16 v[58:61], v[164:167], v[198:201], v[58:61]
	v_mfma_f32_16x16x32_bf16 v[46:49], v[156:159], v[216:219], v[46:49]
	v_mfma_f32_16x16x32_bf16 v[42:45], v[164:167], v[216:219], v[42:45]
	v_mfma_f32_16x16x32_bf16 v[30:33], v[156:159], v[224:227], v[30:33]
	v_mfma_f32_16x16x32_bf16 v[26:29], v[164:167], v[224:227], v[26:29]
	v_mfma_f32_16x16x32_bf16 v[14:17], v[156:159], v[232:235], v[14:17]
	v_mfma_f32_16x16x32_bf16 v[10:13], v[164:167], v[232:235], v[10:13]
	v_mfma_f32_16x16x32_bf16 v[62:65], v[160:163], v[212:215], v[62:65]
	v_mfma_f32_16x16x32_bf16 v[58:61], v[178:181], v[212:215], v[58:61]
	v_mfma_f32_16x16x32_bf16 v[46:49], v[160:163], v[220:223], v[46:49]
	v_mfma_f32_16x16x32_bf16 v[42:45], v[178:181], v[220:223], v[42:45]
	v_mfma_f32_16x16x32_bf16 v[30:33], v[160:163], v[228:231], v[30:33]
	v_mfma_f32_16x16x32_bf16 v[26:29], v[178:181], v[228:231], v[26:29]
	v_mfma_f32_16x16x32_bf16 v[14:17], v[160:163], v[236:239], v[14:17]
	v_mfma_f32_16x16x32_bf16 v[10:13], v[178:181], v[236:239], v[10:13]
	s_setprio 0
	s_setprio 1
	v_mfma_f32_16x16x32_bf16 v[54:57], v[182:185], v[198:201], v[54:57]
	v_mfma_f32_16x16x32_bf16 v[50:53], v[190:193], v[198:201], v[50:53]
	v_mfma_f32_16x16x32_bf16 v[38:41], v[182:185], v[216:219], v[38:41]
	v_mfma_f32_16x16x32_bf16 v[34:37], v[190:193], v[216:219], v[34:37]
	v_mfma_f32_16x16x32_bf16 v[22:25], v[182:185], v[224:227], v[22:25]
	v_mfma_f32_16x16x32_bf16 v[18:21], v[190:193], v[224:227], v[18:21]
	v_mfma_f32_16x16x32_bf16 v[6:9], v[182:185], v[232:235], v[6:9]
	v_mfma_f32_16x16x32_bf16 v[2:5], v[190:193], v[232:235], v[2:5]
	v_mfma_f32_16x16x32_bf16 v[54:57], v[186:189], v[212:215], v[54:57]
	v_mfma_f32_16x16x32_bf16 v[50:53], v[194:197], v[212:215], v[50:53]
	v_mfma_f32_16x16x32_bf16 v[38:41], v[186:189], v[220:223], v[38:41]
	v_mfma_f32_16x16x32_bf16 v[34:37], v[194:197], v[220:223], v[34:37]
	v_mfma_f32_16x16x32_bf16 v[22:25], v[186:189], v[228:231], v[22:25]
	v_mfma_f32_16x16x32_bf16 v[18:21], v[194:197], v[228:231], v[18:21]
	v_mfma_f32_16x16x32_bf16 v[6:9], v[186:189], v[236:239], v[6:9]
	v_mfma_f32_16x16x32_bf16 v[2:5], v[194:197], v[236:239], v[2:5]
	s_setprio 0
	s_barrier
	s_add_i32 s48, s48, 2
	s_add_u32 s46, s46, 0x100
	s_addc_u32 s47, s47, 0
	s_add_u32 s28, s28, 0x100
	s_addc_u32 s29, s29, 0
	s_cmp_gt_u32 s48, 29
	s_cbranch_scc0 .LBB0_261
	s_and_b64 vcc, exec, s[14:15]
	s_cbranch_vccz .LBB0_264
	s_barrier

; #define PG8_STAGE(bufoff, gbase, voff) do { _Pragma("unroll") for (int _i = 0; _i < 2; ++_i) \
;         __builtin_amdgcn_global_load_lds((const unsigned*)((const char*)(gbase) + (voff)[_i]), (LAS unsigned*)(lds + (bufoff) + ldsw + _i * 8192), 16, 0, 0); } while (0)
; #define PG8_LDA(dst, b, h) do { _Pragma("unroll") for (int m = 0; m < 4; ++m) _Pragma("unroll") for (int k = 0; k < 2; ++k) dst[m][k] = *(const LAS bf16x8*)(lds + PG8_SA(b, h) + aoff + m * 2048 + k * 1024); } while (0)
; #define PG8_LDB(dst, b, h) do { _Pragma("unroll") for (int n = 0; n < 2; ++n) _Pragma("unroll") for (int k = 0; k < 2; ++k) dst[n][k] = *(const LAS bf16x8*)(lds + PG8_SB(b, h) + boff + n * 2048 + k * 1024); } while (0)
; #define PG8_MMA(ai, bj, At, Bt) do { __builtin_amdgcn_s_setprio(1); _Pragma("unroll") for (int m = 0; m < 4; ++m) _Pragma("unroll") for (int n = 0; n < 2; ++n) _Pragma("unroll") for (int k = 0; k < 2; ++k) \
;         acc[ai][bj][m][n] = __builtin_amdgcn_mfma_f32_16x16x32_bf16(Bt[n][k], At[m][k], acc[ai][bj][m][n], 0, 0, 0); __builtin_amdgcn_s_setprio(0); } while (0)
; #define PG8_WAIT_V(n) asm volatile("s_waitcnt vmcnt(" #n ")" ::: "memory")
; #define PG8_WAIT_L(n) asm volatile("s_waitcnt lgkmcnt(" #n ")" ::: "memory")
; #define PG8_BAR __builtin_amdgcn_s_barrier()
; #define PG8_SCHED __builtin_amdgcn_sched_barrier(0)
; template <class Epi>
; __device__ __forceinline__ void gemm_phase(LAS unsigned char* lds, const Gemm g, const StaticOrder& S, const Epi& E, const int tid) {
;     ...
;             PG8_LDB(B0, 0, 0); PG8_LDB(B1, 0, 1); PG8_SCHED; PG8_LDA(At, 0, 0); PG8_STAGE(PG8_SA(1, 1), a1 + hstep, voffA);
;             PG8_WAIT_V(8); PG8_WAIT_L(0); PG8_BAR; PG8_MMA(0, 0, At, B0); PG8_MMA(0, 1, At, B1); PG8_BAR; PG8_SCHED;
;             PG8_LDA(At, 0, 1); PG8_STAGE(PG8_SB(0, 0), b2, voffB); PG8_STAGE(PG8_SB(0, 1), b2 + bhs, voffB); PG8_STAGE(PG8_SA(0, 0), a2, voffA);
;             PG8_WAIT_V(8); PG8_WAIT_L(0); PG8_BAR; PG8_MMA(1, 0, At, B0); PG8_MMA(1, 1, At, B1); PG8_BAR; PG8_SCHED;
.LBB0_314:
	s_add_i32 m0, s44, 0xc000
	s_nop 0
	global_load_lds_dwordx4 v188, s[6:7]
	s_add_i32 m0, s44, 0xe000
	s_nop 0
	global_load_lds_dwordx4 v186, s[6:7]
	s_add_u32 s40, s6, 0xfff80080
	s_addc_u32 s41, s7, -1
	s_add_i32 s56, 0, 0x10000
	s_cmp_eq_u32 s55, 28
	s_cselect_b32 s43, s27, s41
	s_cselect_b32 s42, s39, s40
	s_cselect_b32 s41, s25, s54
	s_cselect_b32 s40, s52, s53
	s_add_i32 s58, 0, 0x14000
	v_add_u32_e32 v46, s56, v212
	v_add_u32_e32 v70, s58, v212
	ds_read_b128 v[34:37], v46
	ds_read_b128 v[38:41], v46 offset:1024
	ds_read_b128 v[42:45], v46 offset:2048
	ds_read_b128 v[46:49], v46 offset:3072
	ds_read_b128 v[58:61], v70
	ds_read_b128 v[62:65], v70 offset:1024
	ds_read_b128 v[66:69], v70 offset:2048
	ds_read_b128 v[70:73], v70 offset:3072
	ds_read_b128 v[162:165], v220
	ds_read_b128 v[166:169], v220 offset:1024
	ds_read_b128 v[190:193], v220 offset:2048
	ds_read_b128 v[194:197], v220 offset:3072
	ds_read_b128 v[198:201], v220 offset:4096
	ds_read_b128 v[222:225], v220 offset:5120
	ds_read_b128 v[226:229], v220 offset:6144
	ds_read_b128 v[230:233], v220 offset:7168
	s_waitcnt vmcnt(8)
	s_waitcnt lgkmcnt(0)
	s_barrier
	s_setprio 1
	s_waitcnt lgkmcnt(0)
	v_mfma_f32_16x16x32_bf16 v[158:161], v[34:37], v[162:165], v[158:161]
	v_mfma_f32_16x16x32_bf16 v[154:157], v[42:45], v[162:165], v[154:157]
	v_mfma_f32_16x16x32_bf16 v[142:145], v[34:37], v[190:193], v[142:145]
	v_mfma_f32_16x16x32_bf16 v[138:141], v[42:45], v[190:193], v[138:141]
	v_mfma_f32_16x16x32_bf16 v[126:129], v[34:37], v[198:201], v[126:129]
	v_mfma_f32_16x16x32_bf16 v[122:125], v[42:45], v[198:201], v[122:125]
	v_mfma_f32_16x16x32_bf16 v[110:113], v[34:37], v[226:229], v[110:113]
	v_mfma_f32_16x16x32_bf16 v[106:109], v[42:45], v[226:229], v[106:109]
	v_mfma_f32_16x16x32_bf16 v[158:161], v[38:41], v[166:169], v[158:161]
	v_mfma_f32_16x16x32_bf16 v[154:157], v[46:49], v[166:169], v[154:157]
	v_mfma_f32_16x16x32_bf16 v[142:145], v[38:41], v[194:197], v[142:145]
	v_mfma_f32_16x16x32_bf16 v[138:141], v[46:49], v[194:197], v[138:141]
	v_mfma_f32_16x16x32_bf16 v[126:129], v[38:41], v[222:225], v[126:129]
	v_mfma_f32_16x16x32_bf16 v[122:125], v[46:49], v[222:225], v[122:125]
	v_mfma_f32_16x16x32_bf16 v[110:113], v[38:41], v[230:233], v[110:113]
	v_mfma_f32_16x16x32_bf16 v[106:109], v[46:49], v[230:233], v[106:109]
	s_setprio 0
	s_setprio 1
	v_mfma_f32_16x16x32_bf16 v[150:153], v[58:61], v[162:165], v[150:153]
	v_mfma_f32_16x16x32_bf16 v[146:149], v[66:69], v[162:165], v[146:149]
	v_mfma_f32_16x16x32_bf16 v[134:137], v[58:61], v[190:193], v[134:137]
	v_mfma_f32_16x16x32_bf16 v[130:133], v[66:69], v[190:193], v[130:133]
	v_mfma_f32_16x16x32_bf16 v[118:121], v[58:61], v[198:201], v[118:121]
	v_mfma_f32_16x16x32_bf16 v[114:117], v[66:69], v[198:201], v[114:117]
	v_mfma_f32_16x16x32_bf16 v[102:105], v[58:61], v[226:229], v[102:105]
	v_mfma_f32_16x16x32_bf16 v[98:101], v[66:69], v[226:229], v[98:101]
	v_mfma_f32_16x16x32_bf16 v[150:153], v[62:65], v[166:169], v[150:153]
	v_mfma_f32_16x16x32_bf16 v[146:149], v[70:73], v[166:169], v[146:149]
	v_mfma_f32_16x16x32_bf16 v[134:137], v[62:65], v[194:197], v[134:137]
	v_mfma_f32_16x16x32_bf16 v[130:133], v[70:73], v[194:197], v[130:133]
	v_mfma_f32_16x16x32_bf16 v[118:121], v[62:65], v[222:225], v[118:121]
	v_mfma_f32_16x16x32_bf16 v[114:117], v[70:73], v[222:225], v[114:117]
	v_mfma_f32_16x16x32_bf16 v[102:105], v[62:65], v[230:233], v[102:105]
	v_mfma_f32_16x16x32_bf16 v[98:101], v[70:73], v[230:233], v[98:101]
	s_setprio 0
	s_barrier
	s_add_i32 s56, s56, s33
	v_lshl_add_u64 v[172:173], s[40:41], 0, v[0:1]
	s_mov_b32 m0, s56
	ds_read_b128 v[162:165], v220 offset:16384
	global_load_lds_dwordx4 v[172:173], off
	ds_read_b128 v[166:169], v220 offset:17408
	ds_read_b128 v[190:193], v220 offset:18432
	s_add_i32 m0, s56, 0x2000
	s_add_u32 s56, s40, 0x8000
	v_lshl_add_u64 v[174:175], s[40:41], 0, v[182:183]
	s_addc_u32 s57, s41, 0
	s_add_i32 s58, s58, s33
	global_load_lds_dwordx4 v[174:175], off
	ds_read_b128 v[194:197], v220 offset:19456
	ds_read_b128 v[198:201], v220 offset:20480
	v_lshl_add_u64 v[176:177], s[56:57], 0, v[0:1]
	s_mov_b32 m0, s58
	v_lshl_add_u64 v[238:239], s[42:43], 0, v[180:181]
	global_load_lds_dwordx4 v[176:177], off
	ds_read_b128 v[222:225], v220 offset:21504
	ds_read_b128 v[226:229], v220 offset:22528
	v_lshl_add_u64 v[176:177], s[56:57], 0, v[182:183]
	s_add_i32 m0, s58, 0x2000
	s_nop 0
	global_load_lds_dwordx4 v[176:177], off
	ds_read_b128 v[230:233], v220 offset:23552
	v_lshl_add_u64 v[176:177], s[42:43], 0, v[178:179]
	s_mov_b32 m0, s44
	s_nop 0
	global_load_lds_dwordx4 v[176:177], off
	s_mov_b32 m0, s45
	s_nop 0
	global_load_lds_dwordx4 v[238:239], off
	s_waitcnt vmcnt(8)
	s_waitcnt lgkmcnt(0)
	s_barrier
; #define PG8_STAGE(bufoff, gbase, voff) do { _Pragma("unroll") for (int _i = 0; _i < 2; ++_i) \
;         __builtin_amdgcn_global_load_lds((const unsigned*)((const char*)(gbase) + (voff)[_i]), (LAS unsigned*)(lds + (bufoff) + ldsw + _i * 8192), 16, 0, 0); } while (0)
; #define PG8_LDA(dst, b, h) do { _Pragma("unroll") for (int m = 0; m < 4; ++m) _Pragma("unroll") for (int k = 0; k < 2; ++k) dst[m][k] = *(const LAS bf16x8*)(lds + PG8_SA(b, h) + aoff + m * 2048 + k * 1024); } while (0)
; #define PG8_LDB(dst, b, h) do { _Pragma("unroll") for (int n = 0; n < 2; ++n) _Pragma("unroll") for (int k = 0; k < 2; ++k) dst[n][k] = *(const LAS bf16x8*)(lds + PG8_SB(b, h) + boff + n * 2048 + k * 1024); } while (0)
; #define PG8_MMA(ai, bj, At, Bt) do { __builtin_amdgcn_s_setprio(1); _Pragma("unroll") for (int m = 0; m < 4; ++m) _Pragma("unroll") for (int n = 0; n < 2; ++n) _Pragma("unroll") for (int k = 0; k < 2; ++k) \
;         acc[ai][bj][m][n] = __builtin_amdgcn_mfma_f32_16x16x32_bf16(Bt[n][k], At[m][k], acc[ai][bj][m][n], 0, 0, 0); __builtin_amdgcn_s_setprio(0); } while (0)
; #define PG8_WAIT_V(n) asm volatile("s_waitcnt vmcnt(" #n ")" ::: "memory")
; #define PG8_WAIT_L(n) asm volatile("s_waitcnt lgkmcnt(" #n ")" ::: "memory")
; #define PG8_BAR __builtin_amdgcn_s_barrier()
; #define PG8_SCHED __builtin_amdgcn_sched_barrier(0)
; template <class Epi>
; __device__ __forceinline__ void gemm_phase(LAS unsigned char* lds, const Gemm g, const StaticOrder& S, const Epi& E, const int tid) {
;     ...
;             PG8_WAIT_V(8); PG8_WAIT_L(0); PG8_BAR; PG8_MMA(1, 0, At, B0); PG8_MMA(1, 1, At, B1); PG8_BAR; PG8_SCHED;
;             PG8_LDB(B0, 1, 0); PG8_LDB(B1, 1, 1); PG8_SCHED; PG8_LDA(At, 1, 0); PG8_STAGE(PG8_SA(0, 1), a2 + hstep, voffA);
;             PG8_WAIT_V(8); PG8_WAIT_L(0); PG8_BAR; PG8_MMA(0, 0, At, B0); PG8_MMA(0, 1, At, B1); PG8_BAR; PG8_SCHED;
	s_setprio 1
	s_waitcnt lgkmcnt(0)
	v_mfma_f32_16x16x32_bf16 v[94:97], v[34:37], v[162:165], v[94:97]
	v_mfma_f32_16x16x32_bf16 v[90:93], v[42:45], v[162:165], v[90:93]
	v_mfma_f32_16x16x32_bf16 v[78:81], v[34:37], v[190:193], v[78:81]
	v_mfma_f32_16x16x32_bf16 v[74:77], v[42:45], v[190:193], v[74:77]
	v_mfma_f32_16x16x32_bf16 v[30:33], v[34:37], v[198:201], v[30:33]
	v_mfma_f32_16x16x32_bf16 v[26:29], v[42:45], v[198:201], v[26:29]
	v_mfma_f32_16x16x32_bf16 v[14:17], v[34:37], v[226:229], v[14:17]
	v_mfma_f32_16x16x32_bf16 v[10:13], v[42:45], v[226:229], v[10:13]
	v_mfma_f32_16x16x32_bf16 v[94:97], v[38:41], v[166:169], v[94:97]
	v_mfma_f32_16x16x32_bf16 v[90:93], v[46:49], v[166:169], v[90:93]
	v_mfma_f32_16x16x32_bf16 v[78:81], v[38:41], v[194:197], v[78:81]
	v_mfma_f32_16x16x32_bf16 v[74:77], v[46:49], v[194:197], v[74:77]
	v_mfma_f32_16x16x32_bf16 v[30:33], v[38:41], v[222:225], v[30:33]
	v_mfma_f32_16x16x32_bf16 v[26:29], v[46:49], v[222:225], v[26:29]
	v_mfma_f32_16x16x32_bf16 v[14:17], v[38:41], v[230:233], v[14:17]
	v_mfma_f32_16x16x32_bf16 v[10:13], v[46:49], v[230:233], v[10:13]
	s_setprio 0
	s_setprio 1
	v_mfma_f32_16x16x32_bf16 v[22:25], v[58:61], v[198:201], v[22:25]
	v_mfma_f32_16x16x32_bf16 v[18:21], v[66:69], v[198:201], v[18:21]
	v_mfma_f32_16x16x32_bf16 v[6:9], v[58:61], v[226:229], v[6:9]
	v_mfma_f32_16x16x32_bf16 v[2:5], v[66:69], v[226:229], v[2:5]
	v_mfma_f32_16x16x32_bf16 v[34:37], v[58:61], v[162:165], v[86:89]
	v_mfma_f32_16x16x32_bf16 v[38:41], v[66:69], v[162:165], v[82:85]
	v_mfma_f32_16x16x32_bf16 v[42:45], v[58:61], v[190:193], v[54:57]
	v_mfma_f32_16x16x32_bf16 v[46:49], v[66:69], v[190:193], v[50:53]
	v_mfma_f32_16x16x32_bf16 v[22:25], v[62:65], v[222:225], v[22:25]
	v_mfma_f32_16x16x32_bf16 v[18:21], v[70:73], v[222:225], v[18:21]
	v_mfma_f32_16x16x32_bf16 v[6:9], v[62:65], v[230:233], v[6:9]
	v_mfma_f32_16x16x32_bf16 v[2:5], v[70:73], v[230:233], v[2:5]
	v_mfma_f32_16x16x32_bf16 v[34:37], v[62:65], v[166:169], v[34:37]
	v_mfma_f32_16x16x32_bf16 v[38:41], v[70:73], v[166:169], v[38:41]
	v_mfma_f32_16x16x32_bf16 v[42:45], v[62:65], v[194:197], v[42:45]
	v_mfma_f32_16x16x32_bf16 v[46:49], v[70:73], v[194:197], v[46:49]
	s_setprio 0
	s_barrier
	s_add_u32 s42, s42, 0x80000
	s_addc_u32 s43, s43, 0
	s_mov_b32 m0, s46
	s_nop 0
	global_load_lds_dwordx4 v178, s[42:43]
	s_mov_b32 m0, s47
	s_nop 0
	global_load_lds_dwordx4 v180, s[42:43]
	s_add_i32 s56, 0, 0x18000
	s_add_i32 s57, 0, 0x1c000
	v_add_u32_e32 v62, s56, v212
	v_add_u32_e32 v82, s57, v212
	ds_read_b128 v[50:53], v62
	ds_read_b128 v[54:57], v62 offset:1024
	ds_read_b128 v[58:61], v62 offset:2048
	ds_read_b128 v[62:65], v62 offset:3072
	ds_read_b128 v[66:69], v82
	ds_read_b128 v[70:73], v82 offset:1024
	ds_read_b128 v[162:165], v82 offset:2048
	ds_read_b128 v[166:169], v82 offset:3072
	ds_read_b128 v[82:85], v220 offset:32768
	ds_read_b128 v[86:89], v220 offset:33792
	ds_read_b128 v[190:193], v220 offset:34816
	ds_read_b128 v[194:197], v220 offset:35840
	ds_read_b128 v[198:201], v220 offset:36864
	ds_read_b128 v[222:225], v220 offset:37888
	ds_read_b128 v[226:229], v220 offset:38912
	ds_read_b128 v[230:233], v220 offset:39936
	s_waitcnt vmcnt(8)
	s_waitcnt lgkmcnt(0)
	s_barrier
	s_setprio 1
	s_waitcnt lgkmcnt(0)
	v_mfma_f32_16x16x32_bf16 v[158:161], v[50:53], v[82:85], v[158:161]
	v_mfma_f32_16x16x32_bf16 v[154:157], v[58:61], v[82:85], v[154:157]
	v_mfma_f32_16x16x32_bf16 v[142:145], v[50:53], v[190:193], v[142:145]
	v_mfma_f32_16x16x32_bf16 v[138:141], v[58:61], v[190:193], v[138:141]
	v_mfma_f32_16x16x32_bf16 v[126:129], v[50:53], v[198:201], v[126:129]
	v_mfma_f32_16x16x32_bf16 v[122:125], v[58:61], v[198:201], v[122:125]
	v_mfma_f32_16x16x32_bf16 v[110:113], v[50:53], v[226:229], v[110:113]
	v_mfma_f32_16x16x32_bf16 v[106:109], v[58:61], v[226:229], v[106:109]
	v_mfma_f32_16x16x32_bf16 v[158:161], v[54:57], v[86:89], v[158:161]
	v_mfma_f32_16x16x32_bf16 v[154:157], v[62:65], v[86:89], v[154:157]
	v_mfma_f32_16x16x32_bf16 v[142:145], v[54:57], v[194:197], v[142:145]
	v_mfma_f32_16x16x32_bf16 v[138:141], v[62:65], v[194:197], v[138:141]
	v_mfma_f32_16x16x32_bf16 v[126:129], v[54:57], v[222:225], v[126:129]
	v_mfma_f32_16x16x32_bf16 v[122:125], v[62:65], v[222:225], v[122:125]
	v_mfma_f32_16x16x32_bf16 v[110:113], v[54:57], v[230:233], v[110:113]
	v_mfma_f32_16x16x32_bf16 v[106:109], v[62:65], v[230:233], v[106:109]
	s_setprio 0
	s_setprio 1
	v_mfma_f32_16x16x32_bf16 v[150:153], v[66:69], v[82:85], v[150:153]
	v_mfma_f32_16x16x32_bf16 v[82:85], v[162:165], v[82:85], v[146:149]
	v_mfma_f32_16x16x32_bf16 v[146:149], v[166:169], v[86:89], v[82:85]
	v_mfma_f32_16x16x32_bf16 v[82:85], v[66:69], v[190:193], v[134:137]
	v_mfma_f32_16x16x32_bf16 v[134:137], v[70:73], v[194:197], v[82:85]
	v_mfma_f32_16x16x32_bf16 v[82:85], v[162:165], v[190:193], v[130:133]
	v_mfma_f32_16x16x32_bf16 v[130:133], v[166:169], v[194:197], v[82:85]
	v_mfma_f32_16x16x32_bf16 v[82:85], v[66:69], v[198:201], v[118:121]
	v_mfma_f32_16x16x32_bf16 v[118:121], v[70:73], v[222:225], v[82:85]
	v_mfma_f32_16x16x32_bf16 v[82:85], v[162:165], v[198:201], v[114:117]
	v_mfma_f32_16x16x32_bf16 v[114:117], v[166:169], v[222:225], v[82:85]
	v_mfma_f32_16x16x32_bf16 v[82:85], v[66:69], v[226:229], v[102:105]
	v_mfma_f32_16x16x32_bf16 v[102:105], v[70:73], v[230:233], v[82:85]
	v_mfma_f32_16x16x32_bf16 v[82:85], v[162:165], v[226:229], v[98:101]
	v_mfma_f32_16x16x32_bf16 v[150:153], v[70:73], v[86:89], v[150:153]
	v_mfma_f32_16x16x32_bf16 v[98:101], v[166:169], v[230:233], v[82:85]
	s_setprio 0
	s_barrier
; #define PG8_STAGE(bufoff, gbase, voff) do { _Pragma("unroll") for (int _i = 0; _i < 2; ++_i) \
;         __builtin_amdgcn_global_load_lds((const unsigned*)((const char*)(gbase) + (voff)[_i]), (LAS unsigned*)(lds + (bufoff) + ldsw + _i * 8192), 16, 0, 0); } while (0)
; #define PG8_LDA(dst, b, h) do { _Pragma("unroll") for (int m = 0; m < 4; ++m) _Pragma("unroll") for (int k = 0; k < 2; ++k) dst[m][k] = *(const LAS bf16x8*)(lds + PG8_SA(b, h) + aoff + m * 2048 + k * 1024); } while (0)
; #define PG8_MMA(ai, bj, At, Bt) do { __builtin_amdgcn_s_setprio(1); _Pragma("unroll") for (int m = 0; m < 4; ++m) _Pragma("unroll") for (int n = 0; n < 2; ++n) _Pragma("unroll") for (int k = 0; k < 2; ++k) \
;         acc[ai][bj][m][n] = __builtin_amdgcn_mfma_f32_16x16x32_bf16(Bt[n][k], At[m][k], acc[ai][bj][m][n], 0, 0, 0); __builtin_amdgcn_s_setprio(0); } while (0)
; #define PG8_WAIT_V(n) asm volatile("s_waitcnt vmcnt(" #n ")" ::: "memory")
; #define PG8_WAIT_L(n) asm volatile("s_waitcnt lgkmcnt(" #n ")" ::: "memory")
; #define PG8_BAR __builtin_amdgcn_s_barrier()
; #define PG8_SCHED __builtin_amdgcn_sched_barrier(0)
; template <class Epi>
; __device__ __forceinline__ void gemm_phase(LAS unsigned char* lds, const Gemm g, const StaticOrder& S, const Epi& E, const int tid) {
;     ...
;             const char* a1 = (s1 ? cA2 + (size_t)(t - nt + 1) * kstep : cA + (size_t)(t + 1) * kstep);
;             const char* a2 = last ? nA : (s2 ? cA2 + (size_t)(t + 2 - nt) * kstep : cA + (size_t)(t + 2) * kstep);
;             const char* b2 = last ? nB : (s2 ? cB2 + (size_t)(t + 2 - nt) * kstep : cB + (size_t)(t + 2) * kstep);
;             const char* a3 = a2 + kstep; const char* b3 = b2 + kstep;
;     ...
;             PG8_LDA(At, 1, 1); PG8_STAGE(PG8_SB(1, 0), b3, voffB); PG8_STAGE(PG8_SB(1, 1), b3 + bhs, voffB); PG8_STAGE(PG8_SA(1, 0), a3, voffA);
;             PG8_WAIT_V(8); PG8_WAIT_L(0); PG8_BAR; PG8_MMA(1, 0, At, B0); PG8_MMA(1, 1, At, B1); PG8_BAR; PG8_SCHED;
	s_add_i32 s42, s56, s33
	v_lshl_add_u64 v[86:87], v[172:173], 0, s[70:71]
	s_mov_b32 m0, s42
	s_nop 0
	ds_read_b128 v[82:85], v220 offset:49152
	global_load_lds_dwordx4 v[86:87], off
	ds_read_b128 v[190:193], v220 offset:50176
	ds_read_b128 v[194:197], v220 offset:51200
	s_add_i32 m0, s42, 0x2000
	s_add_u32 s40, s40, 0x8080
	v_lshl_add_u64 v[86:87], v[174:175], 0, s[70:71]
	s_addc_u32 s41, s41, 0
	s_add_i32 s42, s57, s33
	global_load_lds_dwordx4 v[86:87], off
	ds_read_b128 v[198:201], v220 offset:52224
	ds_read_b128 v[222:225], v220 offset:53248
	v_lshl_add_u64 v[86:87], s[40:41], 0, v[0:1]
	s_mov_b32 m0, s42
	s_nop 0
	global_load_lds_dwordx4 v[86:87], off
	ds_read_b128 v[226:229], v220 offset:54272
	ds_read_b128 v[230:233], v220 offset:55296
	v_lshl_add_u64 v[86:87], s[40:41], 0, v[182:183]
	s_add_i32 m0, s42, 0x2000
	s_nop 0
	global_load_lds_dwordx4 v[86:87], off
	ds_read_b128 v[234:237], v220 offset:56320
	v_lshl_add_u64 v[86:87], v[176:177], 0, s[70:71]
	s_mov_b32 m0, s48
	s_nop 0
	global_load_lds_dwordx4 v[86:87], off
	v_lshl_add_u64 v[86:87], v[238:239], 0, s[70:71]
	s_mov_b32 m0, s49
	s_nop 0
	global_load_lds_dwordx4 v[86:87], off
	s_waitcnt vmcnt(8)
	s_waitcnt lgkmcnt(0)
	s_barrier
	s_setprio 1
	s_waitcnt lgkmcnt(0)
	v_mfma_f32_16x16x32_bf16 v[86:89], v[50:53], v[82:85], v[94:97]
	v_mfma_f32_16x16x32_bf16 v[94:97], v[54:57], v[190:193], v[86:89]
	v_mfma_f32_16x16x32_bf16 v[86:89], v[58:61], v[82:85], v[90:93]
	v_mfma_f32_16x16x32_bf16 v[78:81], v[50:53], v[194:197], v[78:81]
	v_mfma_f32_16x16x32_bf16 v[74:77], v[58:61], v[194:197], v[74:77]
	v_mfma_f32_16x16x32_bf16 v[30:33], v[50:53], v[222:225], v[30:33]
	v_mfma_f32_16x16x32_bf16 v[26:29], v[58:61], v[222:225], v[26:29]
	v_mfma_f32_16x16x32_bf16 v[14:17], v[50:53], v[230:233], v[14:17]
	v_mfma_f32_16x16x32_bf16 v[10:13], v[58:61], v[230:233], v[10:13]
	v_mfma_f32_16x16x32_bf16 v[90:93], v[62:65], v[190:193], v[86:89]
	v_mfma_f32_16x16x32_bf16 v[78:81], v[54:57], v[198:201], v[78:81]
	v_mfma_f32_16x16x32_bf16 v[74:77], v[62:65], v[198:201], v[74:77]
	v_mfma_f32_16x16x32_bf16 v[30:33], v[54:57], v[226:229], v[30:33]
	v_mfma_f32_16x16x32_bf16 v[26:29], v[62:65], v[226:229], v[26:29]
	v_mfma_f32_16x16x32_bf16 v[14:17], v[54:57], v[234:237], v[14:17]
	v_mfma_f32_16x16x32_bf16 v[10:13], v[62:65], v[234:237], v[10:13]
	s_setprio 0
	s_setprio 1
	v_mfma_f32_16x16x32_bf16 v[34:37], v[66:69], v[82:85], v[34:37]
	v_mfma_f32_16x16x32_bf16 v[86:89], v[70:73], v[190:193], v[34:37]
	v_mfma_f32_16x16x32_bf16 v[34:37], v[162:165], v[82:85], v[38:41]
	v_mfma_f32_16x16x32_bf16 v[82:85], v[166:169], v[190:193], v[34:37]
	v_mfma_f32_16x16x32_bf16 v[34:37], v[66:69], v[194:197], v[42:45]
	v_mfma_f32_16x16x32_bf16 v[54:57], v[70:73], v[198:201], v[34:37]
	v_mfma_f32_16x16x32_bf16 v[34:37], v[162:165], v[194:197], v[46:49]
	v_mfma_f32_16x16x32_bf16 v[22:25], v[66:69], v[222:225], v[22:25]
	v_mfma_f32_16x16x32_bf16 v[18:21], v[162:165], v[222:225], v[18:21]
	v_mfma_f32_16x16x32_bf16 v[6:9], v[66:69], v[230:233], v[6:9]
	v_mfma_f32_16x16x32_bf16 v[2:5], v[162:165], v[230:233], v[2:5]
	v_mfma_f32_16x16x32_bf16 v[50:53], v[166:169], v[198:201], v[34:37]
	v_mfma_f32_16x16x32_bf16 v[22:25], v[70:73], v[226:229], v[22:25]
	v_mfma_f32_16x16x32_bf16 v[18:21], v[166:169], v[226:229], v[18:21]
	v_mfma_f32_16x16x32_bf16 v[6:9], v[70:73], v[234:237], v[6:9]
	v_mfma_f32_16x16x32_bf16 v[2:5], v[166:169], v[234:237], v[2:5]
	s_setprio 0
	s_barrier
	s_add_i32 s55, s55, 2
	s_add_u32 s53, s53, 0x100
	s_addc_u32 s54, s54, 0
	s_add_u32 s6, s6, 0x100
	s_addc_u32 s7, s7, 0
	s_cmp_gt_u32 s55, 29
	s_cbranch_scc0 .LBB0_314
	s_and_b64 vcc, exec, s[22:23]
	s_cbranch_vccz .LBB0_317
	s_barrier

; #define PG8_STAGE(bufoff, gbase, voff) do { _Pragma("unroll") for (int _i = 0; _i < 2; ++_i) \
;         __builtin_amdgcn_global_load_lds((const unsigned*)((const char*)(gbase) + (voff)[_i]), (LAS unsigned*)(lds + (bufoff) + ldsw + _i * 8192), 16, 0, 0); } while (0)
; #define PG8_LDA(dst, b, h) do { _Pragma("unroll") for (int m = 0; m < 4; ++m) _Pragma("unroll") for (int k = 0; k < 2; ++k) dst[m][k] = *(const LAS bf16x8*)(lds + PG8_SA(b, h) + aoff + m * 2048 + k * 1024); } while (0)
; #define PG8_LDB(dst, b, h) do { _Pragma("unroll") for (int n = 0; n < 2; ++n) _Pragma("unroll") for (int k = 0; k < 2; ++k) dst[n][k] = *(const LAS bf16x8*)(lds + PG8_SB(b, h) + boff + n * 2048 + k * 1024); } while (0)
; #define PG8_MMA(ai, bj, At, Bt) do { __builtin_amdgcn_s_setprio(1); _Pragma("unroll") for (int m = 0; m < 4; ++m) _Pragma("unroll") for (int n = 0; n < 2; ++n) _Pragma("unroll") for (int k = 0; k < 2; ++k) \
;         acc[ai][bj][m][n] = __builtin_amdgcn_mfma_f32_16x16x32_bf16(Bt[n][k], At[m][k], acc[ai][bj][m][n], 0, 0, 0); __builtin_amdgcn_s_setprio(0); } while (0)
; #define PG8_WAIT_V(n) asm volatile("s_waitcnt vmcnt(" #n ")" ::: "memory")
; #define PG8_WAIT_L(n) asm volatile("s_waitcnt lgkmcnt(" #n ")" ::: "memory")
; #define PG8_BAR __builtin_amdgcn_s_barrier()
; #define PG8_SCHED __builtin_amdgcn_sched_barrier(0)
; template <class Epi>
; __device__ __forceinline__ void gemm_phase(LAS unsigned char* lds, const Gemm g, const StaticOrder& S, const Epi& E, const int tid) {
;     ...
;             PG8_LDB(B0, 0, 0); PG8_LDB(B1, 0, 1); PG8_SCHED; PG8_LDA(At, 0, 0); PG8_STAGE(PG8_SA(1, 1), a1 + hstep, voffA);
;             PG8_WAIT_V(8); PG8_WAIT_L(0); PG8_BAR; PG8_MMA(0, 0, At, B0); PG8_MMA(0, 1, At, B1); PG8_BAR; PG8_SCHED;
;             PG8_LDA(At, 0, 1); PG8_STAGE(PG8_SB(0, 0), b2, voffB); PG8_STAGE(PG8_SB(0, 1), b2 + bhs, voffB); PG8_STAGE(PG8_SA(0, 0), a2, voffA);
;             PG8_WAIT_V(8); PG8_WAIT_L(0); PG8_BAR; PG8_MMA(1, 0, At, B0); PG8_MMA(1, 1, At, B1); PG8_BAR; PG8_SCHED;
.LBB0_546:
	s_add_i32 m0, s57, 0xc000
	s_nop 0
	global_load_lds_dwordx4 v146, s[26:27]
	s_add_i32 m0, s57, 0xe000
	s_nop 0
	global_load_lds_dwordx4 v144, s[26:27]
	s_add_u32 s28, s26, 0xfff80080
	s_addc_u32 s29, s27, -1
	s_add_i32 s44, 0, 0x10000
	s_cmp_eq_u32 s39, 28
	s_cselect_b32 s35, s19, s29
	s_cselect_b32 s34, s31, s28
	v_add_u32_e32 v0, s44, v149
	s_cselect_b32 s29, s17, s38
	s_cselect_b32 s28, s33, s37
	s_add_i32 s46, 0, 0x14000
	ds_read_b128 v[150:153], v0
	ds_read_b128 v[154:157], v0 offset:1024
	ds_read_b128 v[158:161], v0 offset:2048
	ds_read_b128 v[186:189], v0 offset:3072
	v_add_u32_e32 v0, s46, v149
	ds_read_b128 v[190:193], v0
	ds_read_b128 v[194:197], v0 offset:1024
	ds_read_b128 v[198:201], v0 offset:2048
	ds_read_b128 v[212:215], v0 offset:3072
	ds_read_b128 v[216:219], v184
	ds_read_b128 v[220:223], v184 offset:1024
	ds_read_b128 v[224:227], v184 offset:2048
	ds_read_b128 v[228:231], v184 offset:3072
	ds_read_b128 v[232:235], v184 offset:4096
	ds_read_b128 v[236:239], v184 offset:5120
	ds_read_b128 v[240:243], v184 offset:6144
	ds_read_b128 v[244:247], v184 offset:7168
	s_waitcnt vmcnt(8)
	s_waitcnt lgkmcnt(0)
	s_barrier
	s_setprio 1
	s_waitcnt lgkmcnt(0)
	v_mfma_f32_16x16x32_bf16 v[126:129], v[150:153], v[216:219], v[126:129]
	v_mfma_f32_16x16x32_bf16 v[122:125], v[158:161], v[216:219], v[122:125]
	v_mfma_f32_16x16x32_bf16 v[110:113], v[150:153], v[224:227], v[110:113]
	v_mfma_f32_16x16x32_bf16 v[106:109], v[158:161], v[224:227], v[106:109]
	v_mfma_f32_16x16x32_bf16 v[94:97], v[150:153], v[232:235], v[94:97]
	v_mfma_f32_16x16x32_bf16 v[90:93], v[158:161], v[232:235], v[90:93]
	v_mfma_f32_16x16x32_bf16 v[78:81], v[150:153], v[240:243], v[78:81]
	v_mfma_f32_16x16x32_bf16 v[74:77], v[158:161], v[240:243], v[74:77]
	v_mfma_f32_16x16x32_bf16 v[126:129], v[154:157], v[220:223], v[126:129]
	v_mfma_f32_16x16x32_bf16 v[122:125], v[186:189], v[220:223], v[122:125]
	v_mfma_f32_16x16x32_bf16 v[110:113], v[154:157], v[228:231], v[110:113]
	v_mfma_f32_16x16x32_bf16 v[106:109], v[186:189], v[228:231], v[106:109]
	v_mfma_f32_16x16x32_bf16 v[94:97], v[154:157], v[236:239], v[94:97]
	v_mfma_f32_16x16x32_bf16 v[90:93], v[186:189], v[236:239], v[90:93]
	v_mfma_f32_16x16x32_bf16 v[78:81], v[154:157], v[244:247], v[78:81]
	v_mfma_f32_16x16x32_bf16 v[74:77], v[186:189], v[244:247], v[74:77]
	s_setprio 0
	s_setprio 1
	v_mfma_f32_16x16x32_bf16 v[118:121], v[190:193], v[216:219], v[118:121]
	v_mfma_f32_16x16x32_bf16 v[114:117], v[198:201], v[216:219], v[114:117]
	v_mfma_f32_16x16x32_bf16 v[102:105], v[190:193], v[224:227], v[102:105]
	v_mfma_f32_16x16x32_bf16 v[98:101], v[198:201], v[224:227], v[98:101]
	v_mfma_f32_16x16x32_bf16 v[86:89], v[190:193], v[232:235], v[86:89]
	v_mfma_f32_16x16x32_bf16 v[82:85], v[198:201], v[232:235], v[82:85]
	v_mfma_f32_16x16x32_bf16 v[70:73], v[190:193], v[240:243], v[70:73]
	v_mfma_f32_16x16x32_bf16 v[66:69], v[198:201], v[240:243], v[66:69]
	v_mfma_f32_16x16x32_bf16 v[118:121], v[194:197], v[220:223], v[118:121]
	v_mfma_f32_16x16x32_bf16 v[114:117], v[212:215], v[220:223], v[114:117]
	v_mfma_f32_16x16x32_bf16 v[102:105], v[194:197], v[228:231], v[102:105]
	v_mfma_f32_16x16x32_bf16 v[98:101], v[212:215], v[228:231], v[98:101]
	v_mfma_f32_16x16x32_bf16 v[86:89], v[194:197], v[236:239], v[86:89]
	v_mfma_f32_16x16x32_bf16 v[82:85], v[212:215], v[236:239], v[82:85]
	v_mfma_f32_16x16x32_bf16 v[70:73], v[194:197], v[244:247], v[70:73]
	v_mfma_f32_16x16x32_bf16 v[66:69], v[212:215], v[244:247], v[66:69]
	s_setprio 0
	s_barrier
	s_add_i32 s44, s44, s56
	v_lshl_add_u64 v[162:163], s[28:29], 0, v[132:133]
	s_mov_b32 m0, s44
	ds_read_b128 v[216:219], v184 offset:16384
	global_load_lds_dwordx4 v[162:163], off
	ds_read_b128 v[220:223], v184 offset:17408
	ds_read_b128 v[224:227], v184 offset:18432
	s_add_i32 m0, s44, 0x2000
	s_add_u32 s44, s28, 0x8000
	v_lshl_add_u64 v[248:249], s[28:29], 0, v[136:137]
	s_addc_u32 s45, s29, 0
	s_add_i32 s46, s46, s56
	global_load_lds_dwordx4 v[248:249], off
	ds_read_b128 v[228:231], v184 offset:19456
	ds_read_b128 v[232:235], v184 offset:20480
	v_lshl_add_u64 v[172:173], s[44:45], 0, v[132:133]
	s_mov_b32 m0, s46
	v_lshl_add_u64 v[174:175], s[34:35], 0, v[134:135]
	global_load_lds_dwordx4 v[172:173], off
	ds_read_b128 v[236:239], v184 offset:21504
	ds_read_b128 v[240:243], v184 offset:22528
	v_lshl_add_u64 v[172:173], s[44:45], 0, v[136:137]
	s_add_i32 m0, s46, 0x2000
	s_nop 0
	global_load_lds_dwordx4 v[172:173], off
	ds_read_b128 v[244:247], v184 offset:23552
	v_lshl_add_u64 v[172:173], s[34:35], 0, v[130:131]
	s_mov_b32 m0, s57
	s_nop 0
	global_load_lds_dwordx4 v[172:173], off
	s_mov_b32 m0, s58
	s_nop 0
	global_load_lds_dwordx4 v[174:175], off
	s_waitcnt vmcnt(8)
	s_waitcnt lgkmcnt(0)
	s_barrier
; #define PG8_STAGE(bufoff, gbase, voff) do { _Pragma("unroll") for (int _i = 0; _i < 2; ++_i) \
;         __builtin_amdgcn_global_load_lds((const unsigned*)((const char*)(gbase) + (voff)[_i]), (LAS unsigned*)(lds + (bufoff) + ldsw + _i * 8192), 16, 0, 0); } while (0)
; #define PG8_LDA(dst, b, h) do { _Pragma("unroll") for (int m = 0; m < 4; ++m) _Pragma("unroll") for (int k = 0; k < 2; ++k) dst[m][k] = *(const LAS bf16x8*)(lds + PG8_SA(b, h) + aoff + m * 2048 + k * 1024); } while (0)
; #define PG8_LDB(dst, b, h) do { _Pragma("unroll") for (int n = 0; n < 2; ++n) _Pragma("unroll") for (int k = 0; k < 2; ++k) dst[n][k] = *(const LAS bf16x8*)(lds + PG8_SB(b, h) + boff + n * 2048 + k * 1024); } while (0)
; #define PG8_MMA(ai, bj, At, Bt) do { __builtin_amdgcn_s_setprio(1); _Pragma("unroll") for (int m = 0; m < 4; ++m) _Pragma("unroll") for (int n = 0; n < 2; ++n) _Pragma("unroll") for (int k = 0; k < 2; ++k) \
;         acc[ai][bj][m][n] = __builtin_amdgcn_mfma_f32_16x16x32_bf16(Bt[n][k], At[m][k], acc[ai][bj][m][n], 0, 0, 0); __builtin_amdgcn_s_setprio(0); } while (0)
; #define PG8_WAIT_V(n) asm volatile("s_waitcnt vmcnt(" #n ")" ::: "memory")
; #define PG8_WAIT_L(n) asm volatile("s_waitcnt lgkmcnt(" #n ")" ::: "memory")
; #define PG8_BAR __builtin_amdgcn_s_barrier()
; #define PG8_SCHED __builtin_amdgcn_sched_barrier(0)
; template <class Epi>
; __device__ __forceinline__ void gemm_phase(LAS unsigned char* lds, const Gemm g, const StaticOrder& S, const Epi& E, const int tid) {
;     ...
;             PG8_WAIT_V(8); PG8_WAIT_L(0); PG8_BAR; PG8_MMA(1, 0, At, B0); PG8_MMA(1, 1, At, B1); PG8_BAR; PG8_SCHED;
;             PG8_LDB(B0, 1, 0); PG8_LDB(B1, 1, 1); PG8_SCHED; PG8_LDA(At, 1, 0); PG8_STAGE(PG8_SA(0, 1), a2 + hstep, voffA);
;             PG8_WAIT_V(8); PG8_WAIT_L(0); PG8_BAR; PG8_MMA(0, 0, At, B0); PG8_MMA(0, 1, At, B1); PG8_BAR; PG8_SCHED;
	s_setprio 1
	s_waitcnt lgkmcnt(0)
	v_mfma_f32_16x16x32_bf16 v[62:65], v[150:153], v[216:219], v[62:65]
	v_mfma_f32_16x16x32_bf16 v[58:61], v[158:161], v[216:219], v[58:61]
	v_mfma_f32_16x16x32_bf16 v[46:49], v[150:153], v[224:227], v[46:49]
	v_mfma_f32_16x16x32_bf16 v[42:45], v[158:161], v[224:227], v[42:45]
	v_mfma_f32_16x16x32_bf16 v[30:33], v[150:153], v[232:235], v[30:33]
	v_mfma_f32_16x16x32_bf16 v[26:29], v[158:161], v[232:235], v[26:29]
	v_mfma_f32_16x16x32_bf16 v[14:17], v[150:153], v[240:243], v[14:17]
	v_mfma_f32_16x16x32_bf16 v[10:13], v[158:161], v[240:243], v[10:13]
	v_mfma_f32_16x16x32_bf16 v[62:65], v[154:157], v[220:223], v[62:65]
	v_mfma_f32_16x16x32_bf16 v[58:61], v[186:189], v[220:223], v[58:61]
	v_mfma_f32_16x16x32_bf16 v[46:49], v[154:157], v[228:231], v[46:49]
	v_mfma_f32_16x16x32_bf16 v[42:45], v[186:189], v[228:231], v[42:45]
	v_mfma_f32_16x16x32_bf16 v[30:33], v[154:157], v[236:239], v[30:33]
	v_mfma_f32_16x16x32_bf16 v[26:29], v[186:189], v[236:239], v[26:29]
	v_mfma_f32_16x16x32_bf16 v[14:17], v[154:157], v[244:247], v[14:17]
	v_mfma_f32_16x16x32_bf16 v[10:13], v[186:189], v[244:247], v[10:13]
	s_setprio 0
	s_setprio 1
	v_mfma_f32_16x16x32_bf16 v[54:57], v[190:193], v[216:219], v[54:57]
	v_mfma_f32_16x16x32_bf16 v[50:53], v[198:201], v[216:219], v[50:53]
	v_mfma_f32_16x16x32_bf16 v[38:41], v[190:193], v[224:227], v[38:41]
	v_mfma_f32_16x16x32_bf16 v[34:37], v[198:201], v[224:227], v[34:37]
	v_mfma_f32_16x16x32_bf16 v[22:25], v[190:193], v[232:235], v[22:25]
	v_mfma_f32_16x16x32_bf16 v[18:21], v[198:201], v[232:235], v[18:21]
	v_mfma_f32_16x16x32_bf16 v[6:9], v[190:193], v[240:243], v[6:9]
	v_mfma_f32_16x16x32_bf16 v[2:5], v[198:201], v[240:243], v[2:5]
	v_mfma_f32_16x16x32_bf16 v[54:57], v[194:197], v[220:223], v[54:57]
	v_mfma_f32_16x16x32_bf16 v[50:53], v[212:215], v[220:223], v[50:53]
	v_mfma_f32_16x16x32_bf16 v[38:41], v[194:197], v[228:231], v[38:41]
	v_mfma_f32_16x16x32_bf16 v[34:37], v[212:215], v[228:231], v[34:37]
	v_mfma_f32_16x16x32_bf16 v[22:25], v[194:197], v[236:239], v[22:25]
	v_mfma_f32_16x16x32_bf16 v[18:21], v[212:215], v[236:239], v[18:21]
	v_mfma_f32_16x16x32_bf16 v[6:9], v[194:197], v[244:247], v[6:9]
	v_mfma_f32_16x16x32_bf16 v[2:5], v[212:215], v[244:247], v[2:5]
	s_setprio 0
	s_barrier
	s_add_u32 s34, s34, 0x80000
	s_addc_u32 s35, s35, 0
	s_mov_b32 m0, s59
	s_nop 0
	global_load_lds_dwordx4 v130, s[34:35]
	s_mov_b32 m0, s60
	s_nop 0
	global_load_lds_dwordx4 v134, s[34:35]
	s_add_i32 s44, 0, 0x18000
	v_add_u32_e32 v0, s44, v149
	s_add_i32 s45, 0, 0x1c000
	ds_read_b128 v[150:153], v0
	ds_read_b128 v[154:157], v0 offset:1024
	ds_read_b128 v[158:161], v0 offset:2048
	ds_read_b128 v[186:189], v0 offset:3072
	v_add_u32_e32 v0, s45, v149
	ds_read_b128 v[190:193], v0
	ds_read_b128 v[194:197], v0 offset:1024
	ds_read_b128 v[198:201], v0 offset:2048
	ds_read_b128 v[212:215], v0 offset:3072
	ds_read_b128 v[216:219], v184 offset:32768
	ds_read_b128 v[220:223], v184 offset:33792
	ds_read_b128 v[224:227], v184 offset:34816
	ds_read_b128 v[228:231], v184 offset:35840
	ds_read_b128 v[232:235], v184 offset:36864
	ds_read_b128 v[236:239], v184 offset:37888
	ds_read_b128 v[240:243], v184 offset:38912
	ds_read_b128 v[244:247], v184 offset:39936
	s_waitcnt vmcnt(8)
	s_waitcnt lgkmcnt(0)
	s_barrier
	s_setprio 1
	s_waitcnt lgkmcnt(0)
	v_mfma_f32_16x16x32_bf16 v[126:129], v[150:153], v[216:219], v[126:129]
	v_mfma_f32_16x16x32_bf16 v[122:125], v[158:161], v[216:219], v[122:125]
	v_mfma_f32_16x16x32_bf16 v[110:113], v[150:153], v[224:227], v[110:113]
	v_mfma_f32_16x16x32_bf16 v[106:109], v[158:161], v[224:227], v[106:109]
	v_mfma_f32_16x16x32_bf16 v[94:97], v[150:153], v[232:235], v[94:97]
	v_mfma_f32_16x16x32_bf16 v[90:93], v[158:161], v[232:235], v[90:93]
	v_mfma_f32_16x16x32_bf16 v[78:81], v[150:153], v[240:243], v[78:81]
	v_mfma_f32_16x16x32_bf16 v[74:77], v[158:161], v[240:243], v[74:77]
	v_mfma_f32_16x16x32_bf16 v[126:129], v[154:157], v[220:223], v[126:129]
	v_mfma_f32_16x16x32_bf16 v[122:125], v[186:189], v[220:223], v[122:125]
	v_mfma_f32_16x16x32_bf16 v[110:113], v[154:157], v[228:231], v[110:113]
	v_mfma_f32_16x16x32_bf16 v[106:109], v[186:189], v[228:231], v[106:109]
	v_mfma_f32_16x16x32_bf16 v[94:97], v[154:157], v[236:239], v[94:97]
	v_mfma_f32_16x16x32_bf16 v[90:93], v[186:189], v[236:239], v[90:93]
	v_mfma_f32_16x16x32_bf16 v[78:81], v[154:157], v[244:247], v[78:81]
	v_mfma_f32_16x16x32_bf16 v[74:77], v[186:189], v[244:247], v[74:77]
	s_setprio 0
	s_setprio 1
	v_mfma_f32_16x16x32_bf16 v[118:121], v[190:193], v[216:219], v[118:121]
	v_mfma_f32_16x16x32_bf16 v[114:117], v[198:201], v[216:219], v[114:117]
	v_mfma_f32_16x16x32_bf16 v[102:105], v[190:193], v[224:227], v[102:105]
	v_mfma_f32_16x16x32_bf16 v[98:101], v[198:201], v[224:227], v[98:101]
	v_mfma_f32_16x16x32_bf16 v[86:89], v[190:193], v[232:235], v[86:89]
	v_mfma_f32_16x16x32_bf16 v[82:85], v[198:201], v[232:235], v[82:85]
	v_mfma_f32_16x16x32_bf16 v[70:73], v[190:193], v[240:243], v[70:73]
	v_mfma_f32_16x16x32_bf16 v[66:69], v[198:201], v[240:243], v[66:69]
	v_mfma_f32_16x16x32_bf16 v[118:121], v[194:197], v[220:223], v[118:121]
	v_mfma_f32_16x16x32_bf16 v[114:117], v[212:215], v[220:223], v[114:117]
	v_mfma_f32_16x16x32_bf16 v[102:105], v[194:197], v[228:231], v[102:105]
	v_mfma_f32_16x16x32_bf16 v[98:101], v[212:215], v[228:231], v[98:101]
	v_mfma_f32_16x16x32_bf16 v[86:89], v[194:197], v[236:239], v[86:89]
	v_mfma_f32_16x16x32_bf16 v[82:85], v[212:215], v[236:239], v[82:85]
	v_mfma_f32_16x16x32_bf16 v[70:73], v[194:197], v[244:247], v[70:73]
	v_mfma_f32_16x16x32_bf16 v[66:69], v[212:215], v[244:247], v[66:69]
	s_setprio 0
	s_barrier
; #define PG8_STAGE(bufoff, gbase, voff) do { _Pragma("unroll") for (int _i = 0; _i < 2; ++_i) \
;         __builtin_amdgcn_global_load_lds((const unsigned*)((const char*)(gbase) + (voff)[_i]), (LAS unsigned*)(lds + (bufoff) + ldsw + _i * 8192), 16, 0, 0); } while (0)
; #define PG8_LDA(dst, b, h) do { _Pragma("unroll") for (int m = 0; m < 4; ++m) _Pragma("unroll") for (int k = 0; k < 2; ++k) dst[m][k] = *(const LAS bf16x8*)(lds + PG8_SA(b, h) + aoff + m * 2048 + k * 1024); } while (0)
; #define PG8_MMA(ai, bj, At, Bt) do { __builtin_amdgcn_s_setprio(1); _Pragma("unroll") for (int m = 0; m < 4; ++m) _Pragma("unroll") for (int n = 0; n < 2; ++n) _Pragma("unroll") for (int k = 0; k < 2; ++k) \
;         acc[ai][bj][m][n] = __builtin_amdgcn_mfma_f32_16x16x32_bf16(Bt[n][k], At[m][k], acc[ai][bj][m][n], 0, 0, 0); __builtin_amdgcn_s_setprio(0); } while (0)
; #define PG8_WAIT_V(n) asm volatile("s_waitcnt vmcnt(" #n ")" ::: "memory")
; #define PG8_WAIT_L(n) asm volatile("s_waitcnt lgkmcnt(" #n ")" ::: "memory")
; #define PG8_BAR __builtin_amdgcn_s_barrier()
; #define PG8_SCHED __builtin_amdgcn_sched_barrier(0)
; template <class Epi>
; __device__ __forceinline__ void gemm_phase(LAS unsigned char* lds, const Gemm g, const StaticOrder& S, const Epi& E, const int tid) {
;     ...
;             const char* a1 = (s1 ? cA2 + (size_t)(t - nt + 1) * kstep : cA + (size_t)(t + 1) * kstep);
;             const char* a2 = last ? nA : (s2 ? cA2 + (size_t)(t + 2 - nt) * kstep : cA + (size_t)(t + 2) * kstep);
;             const char* b2 = last ? nB : (s2 ? cB2 + (size_t)(t + 2 - nt) * kstep : cB + (size_t)(t + 2) * kstep);
;             const char* a3 = a2 + kstep; const char* b3 = b2 + kstep;
;     ...
;             PG8_LDA(At, 1, 1); PG8_STAGE(PG8_SB(1, 0), b3, voffB); PG8_STAGE(PG8_SB(1, 1), b3 + bhs, voffB); PG8_STAGE(PG8_SA(1, 0), a3, voffA);
;             PG8_WAIT_V(8); PG8_WAIT_L(0); PG8_BAR; PG8_MMA(1, 0, At, B0); PG8_MMA(1, 1, At, B1); PG8_BAR; PG8_SCHED;
	s_add_i32 s34, s44, s56
	v_lshl_add_u64 v[162:163], v[162:163], 0, s[70:71]
	s_mov_b32 m0, s34
	ds_read_b128 v[216:219], v184 offset:49152
	global_load_lds_dwordx4 v[162:163], off
	ds_read_b128 v[220:223], v184 offset:50176
	ds_read_b128 v[224:227], v184 offset:51200
	s_add_i32 m0, s34, 0x2000
	s_add_u32 s28, s28, 0x8080
	v_lshl_add_u64 v[162:163], v[248:249], 0, s[70:71]
	s_addc_u32 s29, s29, 0
	s_add_i32 s34, s45, s56
	global_load_lds_dwordx4 v[162:163], off
	ds_read_b128 v[228:231], v184 offset:52224
	ds_read_b128 v[232:235], v184 offset:53248
	v_lshl_add_u64 v[162:163], s[28:29], 0, v[132:133]
	s_mov_b32 m0, s34
	s_nop 0
	global_load_lds_dwordx4 v[162:163], off
	ds_read_b128 v[236:239], v184 offset:54272
	ds_read_b128 v[240:243], v184 offset:55296
	v_lshl_add_u64 v[162:163], s[28:29], 0, v[136:137]
	s_add_i32 m0, s34, 0x2000
	s_nop 0
	global_load_lds_dwordx4 v[162:163], off
	ds_read_b128 v[244:247], v184 offset:56320
	v_lshl_add_u64 v[162:163], v[172:173], 0, s[70:71]
	s_mov_b32 m0, s61
	s_nop 0
	global_load_lds_dwordx4 v[162:163], off
	v_lshl_add_u64 v[162:163], v[174:175], 0, s[70:71]
	s_mov_b32 m0, s62
	s_nop 0
	global_load_lds_dwordx4 v[162:163], off
	s_waitcnt vmcnt(8)
	s_waitcnt lgkmcnt(0)
	s_barrier
	s_setprio 1
	s_waitcnt lgkmcnt(0)
	v_mfma_f32_16x16x32_bf16 v[62:65], v[150:153], v[216:219], v[62:65]
	v_mfma_f32_16x16x32_bf16 v[58:61], v[158:161], v[216:219], v[58:61]
	v_mfma_f32_16x16x32_bf16 v[46:49], v[150:153], v[224:227], v[46:49]
	v_mfma_f32_16x16x32_bf16 v[42:45], v[158:161], v[224:227], v[42:45]
	v_mfma_f32_16x16x32_bf16 v[30:33], v[150:153], v[232:235], v[30:33]
	v_mfma_f32_16x16x32_bf16 v[26:29], v[158:161], v[232:235], v[26:29]
	v_mfma_f32_16x16x32_bf16 v[14:17], v[150:153], v[240:243], v[14:17]
	v_mfma_f32_16x16x32_bf16 v[10:13], v[158:161], v[240:243], v[10:13]
	v_mfma_f32_16x16x32_bf16 v[62:65], v[154:157], v[220:223], v[62:65]
	v_mfma_f32_16x16x32_bf16 v[58:61], v[186:189], v[220:223], v[58:61]
	v_mfma_f32_16x16x32_bf16 v[46:49], v[154:157], v[228:231], v[46:49]
	v_mfma_f32_16x16x32_bf16 v[42:45], v[186:189], v[228:231], v[42:45]
	v_mfma_f32_16x16x32_bf16 v[30:33], v[154:157], v[236:239], v[30:33]
	v_mfma_f32_16x16x32_bf16 v[26:29], v[186:189], v[236:239], v[26:29]
	v_mfma_f32_16x16x32_bf16 v[14:17], v[154:157], v[244:247], v[14:17]
	v_mfma_f32_16x16x32_bf16 v[10:13], v[186:189], v[244:247], v[10:13]
	s_setprio 0
	s_setprio 1
	v_mfma_f32_16x16x32_bf16 v[54:57], v[190:193], v[216:219], v[54:57]
	v_mfma_f32_16x16x32_bf16 v[50:53], v[198:201], v[216:219], v[50:53]
	v_mfma_f32_16x16x32_bf16 v[38:41], v[190:193], v[224:227], v[38:41]
	v_mfma_f32_16x16x32_bf16 v[34:37], v[198:201], v[224:227], v[34:37]
	v_mfma_f32_16x16x32_bf16 v[22:25], v[190:193], v[232:235], v[22:25]
	v_mfma_f32_16x16x32_bf16 v[18:21], v[198:201], v[232:235], v[18:21]
	v_mfma_f32_16x16x32_bf16 v[6:9], v[190:193], v[240:243], v[6:9]
	v_mfma_f32_16x16x32_bf16 v[2:5], v[198:201], v[240:243], v[2:5]
	v_mfma_f32_16x16x32_bf16 v[54:57], v[194:197], v[220:223], v[54:57]
	v_mfma_f32_16x16x32_bf16 v[50:53], v[212:215], v[220:223], v[50:53]
	v_mfma_f32_16x16x32_bf16 v[38:41], v[194:197], v[228:231], v[38:41]
	v_mfma_f32_16x16x32_bf16 v[34:37], v[212:215], v[228:231], v[34:37]
	v_mfma_f32_16x16x32_bf16 v[22:25], v[194:197], v[236:239], v[22:25]
	v_mfma_f32_16x16x32_bf16 v[18:21], v[212:215], v[236:239], v[18:21]
	v_mfma_f32_16x16x32_bf16 v[6:9], v[194:197], v[244:247], v[6:9]
	v_mfma_f32_16x16x32_bf16 v[2:5], v[212:215], v[244:247], v[2:5]
	s_setprio 0
	s_barrier
	s_add_i32 s39, s39, 2
	s_add_u32 s37, s37, 0x100
	s_addc_u32 s38, s38, 0
	s_add_u32 s26, s26, 0x100
	s_addc_u32 s27, s27, 0
	s_cmp_gt_u32 s39, 29
	s_cbranch_scc0 .LBB0_546
	s_and_b64 vcc, exec, s[14:15]
	s_cbranch_vccz .LBB0_549
	s_barrier

; #define PG8_STAGE(bufoff, gbase, voff) do { _Pragma("unroll") for (int _i = 0; _i < 2; ++_i) \
;         __builtin_amdgcn_global_load_lds((const unsigned*)((const char*)(gbase) + (voff)[_i]), (LAS unsigned*)(lds + (bufoff) + ldsw + _i * 8192), 16, 0, 0); } while (0)
; #define PG8_LDA(dst, b, h) do { _Pragma("unroll") for (int m = 0; m < 4; ++m) _Pragma("unroll") for (int k = 0; k < 2; ++k) dst[m][k] = *(const LAS bf16x8*)(lds + PG8_SA(b, h) + aoff + m * 2048 + k * 1024); } while (0)
; #define PG8_LDB(dst, b, h) do { _Pragma("unroll") for (int n = 0; n < 2; ++n) _Pragma("unroll") for (int k = 0; k < 2; ++k) dst[n][k] = *(const LAS bf16x8*)(lds + PG8_SB(b, h) + boff + n * 2048 + k * 1024); } while (0)
; #define PG8_MMA(ai, bj, At, Bt) do { __builtin_amdgcn_s_setprio(1); _Pragma("unroll") for (int m = 0; m < 4; ++m) _Pragma("unroll") for (int n = 0; n < 2; ++n) _Pragma("unroll") for (int k = 0; k < 2; ++k) \
;         acc[ai][bj][m][n] = __builtin_amdgcn_mfma_f32_16x16x32_bf16(Bt[n][k], At[m][k], acc[ai][bj][m][n], 0, 0, 0); __builtin_amdgcn_s_setprio(0); } while (0)
; #define PG8_WAIT_V(n) asm volatile("s_waitcnt vmcnt(" #n ")" ::: "memory")
; #define PG8_WAIT_L(n) asm volatile("s_waitcnt lgkmcnt(" #n ")" ::: "memory")
; #define PG8_BAR __builtin_amdgcn_s_barrier()
; #define PG8_SCHED __builtin_amdgcn_sched_barrier(0)
; template <class Epi>
; __device__ __forceinline__ void gemm_phase(LAS unsigned char* lds, const Gemm g, const StaticOrder& S, const Epi& E, const int tid) {
;     ...
;             PG8_LDB(B0, 0, 0); PG8_LDB(B1, 0, 1); PG8_SCHED; PG8_LDA(At, 0, 0); PG8_STAGE(PG8_SA(1, 1), a1 + hstep, voffA);
;             PG8_WAIT_V(8); PG8_WAIT_L(0); PG8_BAR; PG8_MMA(0, 0, At, B0); PG8_MMA(0, 1, At, B1); PG8_BAR; PG8_SCHED;
;             PG8_LDA(At, 0, 1); PG8_STAGE(PG8_SB(0, 0), b2, voffB); PG8_STAGE(PG8_SB(0, 1), b2 + bhs, voffB); PG8_STAGE(PG8_SA(0, 0), a2, voffA);
;             PG8_WAIT_V(8); PG8_WAIT_L(0); PG8_BAR; PG8_MMA(1, 0, At, B0); PG8_MMA(1, 1, At, B1); PG8_BAR; PG8_SCHED;
.LBB0_844:
	s_add_i32 m0, s23, 0xc000
	s_nop 0
	global_load_lds_dwordx4 v138, s[26:27]
	s_add_i32 m0, s23, 0xe000
	s_nop 0
	global_load_lds_dwordx4 v136, s[26:27]
	s_add_u32 s28, s26, 0xfff80080
	s_addc_u32 s29, s27, -1
	s_add_i32 s48, 0, 0x10000
	s_cmp_eq_u32 s47, 28
	s_cselect_b32 s31, s15, s29
	s_cselect_b32 s30, s43, s28
	v_add_u32_e32 v145, s48, v142
	s_cselect_b32 s29, s13, s46
	s_cselect_b32 s28, s44, s45
	s_add_i32 s50, 0, 0x14000
	ds_read_b128 v[146:149], v145
	ds_read_b128 v[150:153], v145 offset:1024
	ds_read_b128 v[154:157], v145 offset:2048
	ds_read_b128 v[158:161], v145 offset:3072
	v_add_u32_e32 v145, s50, v142
	ds_read_b128 v[162:165], v145
	ds_read_b128 v[166:169], v145 offset:1024
	ds_read_b128 v[178:181], v145 offset:2048
	ds_read_b128 v[182:185], v145 offset:3072
	ds_read_b128 v[186:189], v144
	ds_read_b128 v[190:193], v144 offset:1024
	ds_read_b128 v[194:197], v144 offset:2048
	ds_read_b128 v[198:201], v144 offset:3072
	ds_read_b128 v[212:215], v144 offset:4096
	ds_read_b128 v[216:219], v144 offset:5120
	ds_read_b128 v[220:223], v144 offset:6144
	ds_read_b128 v[224:227], v144 offset:7168
	s_waitcnt vmcnt(8)
	s_waitcnt lgkmcnt(0)
	s_barrier
	s_setprio 1
	s_waitcnt lgkmcnt(0)
	v_mfma_f32_16x16x32_bf16 v[126:129], v[146:149], v[186:189], v[126:129]
	v_mfma_f32_16x16x32_bf16 v[122:125], v[154:157], v[186:189], v[122:125]
	v_mfma_f32_16x16x32_bf16 v[118:121], v[146:149], v[194:197], v[118:121]
	v_mfma_f32_16x16x32_bf16 v[110:113], v[154:157], v[194:197], v[110:113]
	v_mfma_f32_16x16x32_bf16 v[102:105], v[146:149], v[212:215], v[102:105]
	v_mfma_f32_16x16x32_bf16 v[94:97], v[154:157], v[212:215], v[94:97]
	v_mfma_f32_16x16x32_bf16 v[86:89], v[146:149], v[220:223], v[86:89]
	v_mfma_f32_16x16x32_bf16 v[78:81], v[154:157], v[220:223], v[78:81]
	v_mfma_f32_16x16x32_bf16 v[126:129], v[150:153], v[190:193], v[126:129]
	v_mfma_f32_16x16x32_bf16 v[122:125], v[158:161], v[190:193], v[122:125]
	v_mfma_f32_16x16x32_bf16 v[118:121], v[150:153], v[198:201], v[118:121]
	v_mfma_f32_16x16x32_bf16 v[110:113], v[158:161], v[198:201], v[110:113]
	v_mfma_f32_16x16x32_bf16 v[102:105], v[150:153], v[216:219], v[102:105]
	v_mfma_f32_16x16x32_bf16 v[94:97], v[158:161], v[216:219], v[94:97]
	v_mfma_f32_16x16x32_bf16 v[86:89], v[150:153], v[224:227], v[86:89]
	v_mfma_f32_16x16x32_bf16 v[78:81], v[158:161], v[224:227], v[78:81]
	s_setprio 0
	s_setprio 1
	v_mfma_f32_16x16x32_bf16 v[114:117], v[162:165], v[186:189], v[114:117]
	v_mfma_f32_16x16x32_bf16 v[106:109], v[178:181], v[186:189], v[106:109]
	v_mfma_f32_16x16x32_bf16 v[98:101], v[162:165], v[194:197], v[98:101]
	v_mfma_f32_16x16x32_bf16 v[90:93], v[178:181], v[194:197], v[90:93]
	v_mfma_f32_16x16x32_bf16 v[82:85], v[162:165], v[212:215], v[82:85]
	v_mfma_f32_16x16x32_bf16 v[74:77], v[178:181], v[212:215], v[74:77]
	v_mfma_f32_16x16x32_bf16 v[70:73], v[162:165], v[220:223], v[70:73]
	v_mfma_f32_16x16x32_bf16 v[66:69], v[178:181], v[220:223], v[66:69]
	v_mfma_f32_16x16x32_bf16 v[114:117], v[166:169], v[190:193], v[114:117]
	v_mfma_f32_16x16x32_bf16 v[106:109], v[182:185], v[190:193], v[106:109]
	v_mfma_f32_16x16x32_bf16 v[98:101], v[166:169], v[198:201], v[98:101]
	v_mfma_f32_16x16x32_bf16 v[90:93], v[182:185], v[198:201], v[90:93]
	v_mfma_f32_16x16x32_bf16 v[82:85], v[166:169], v[216:219], v[82:85]
	v_mfma_f32_16x16x32_bf16 v[74:77], v[182:185], v[216:219], v[74:77]
	v_mfma_f32_16x16x32_bf16 v[70:73], v[166:169], v[224:227], v[70:73]
	v_mfma_f32_16x16x32_bf16 v[66:69], v[182:185], v[224:227], v[66:69]
	s_setprio 0
	s_barrier
	s_add_i32 s48, s48, s37
	v_lshl_add_u64 v[172:173], s[28:29], 0, v[0:1]
	s_mov_b32 m0, s48
	ds_read_b128 v[186:189], v144 offset:16384
	global_load_lds_dwordx4 v[172:173], off
	ds_read_b128 v[190:193], v144 offset:17408
	ds_read_b128 v[194:197], v144 offset:18432
	s_add_i32 m0, s48, 0x2000
	s_add_u32 s48, s28, 0x8000
	v_lshl_add_u64 v[174:175], s[28:29], 0, v[134:135]
	s_addc_u32 s49, s29, 0
	s_add_i32 s50, s50, s37
	global_load_lds_dwordx4 v[174:175], off
	ds_read_b128 v[198:201], v144 offset:19456
	ds_read_b128 v[212:215], v144 offset:20480
	v_lshl_add_u64 v[176:177], s[48:49], 0, v[0:1]
	s_mov_b32 m0, s50
	v_lshl_add_u64 v[228:229], s[30:31], 0, v[132:133]
	global_load_lds_dwordx4 v[176:177], off
	ds_read_b128 v[216:219], v144 offset:21504
	ds_read_b128 v[220:223], v144 offset:22528
	v_lshl_add_u64 v[176:177], s[48:49], 0, v[134:135]
	s_add_i32 m0, s50, 0x2000
	s_nop 0
	global_load_lds_dwordx4 v[176:177], off
	ds_read_b128 v[224:227], v144 offset:23552
	v_lshl_add_u64 v[176:177], s[30:31], 0, v[130:131]
	s_mov_b32 m0, s23
	s_nop 0
	global_load_lds_dwordx4 v[176:177], off
	s_mov_b32 m0, s25
	s_nop 0
	global_load_lds_dwordx4 v[228:229], off
	s_waitcnt vmcnt(8)
	s_waitcnt lgkmcnt(0)
	s_barrier
; #define PG8_STAGE(bufoff, gbase, voff) do { _Pragma("unroll") for (int _i = 0; _i < 2; ++_i) \
;         __builtin_amdgcn_global_load_lds((const unsigned*)((const char*)(gbase) + (voff)[_i]), (LAS unsigned*)(lds + (bufoff) + ldsw + _i * 8192), 16, 0, 0); } while (0)
; #define PG8_LDA(dst, b, h) do { _Pragma("unroll") for (int m = 0; m < 4; ++m) _Pragma("unroll") for (int k = 0; k < 2; ++k) dst[m][k] = *(const LAS bf16x8*)(lds + PG8_SA(b, h) + aoff + m * 2048 + k * 1024); } while (0)
; #define PG8_LDB(dst, b, h) do { _Pragma("unroll") for (int n = 0; n < 2; ++n) _Pragma("unroll") for (int k = 0; k < 2; ++k) dst[n][k] = *(const LAS bf16x8*)(lds + PG8_SB(b, h) + boff + n * 2048 + k * 1024); } while (0)
; #define PG8_MMA(ai, bj, At, Bt) do { __builtin_amdgcn_s_setprio(1); _Pragma("unroll") for (int m = 0; m < 4; ++m) _Pragma("unroll") for (int n = 0; n < 2; ++n) _Pragma("unroll") for (int k = 0; k < 2; ++k) \
;         acc[ai][bj][m][n] = __builtin_amdgcn_mfma_f32_16x16x32_bf16(Bt[n][k], At[m][k], acc[ai][bj][m][n], 0, 0, 0); __builtin_amdgcn_s_setprio(0); } while (0)
; #define PG8_WAIT_V(n) asm volatile("s_waitcnt vmcnt(" #n ")" ::: "memory")
; #define PG8_WAIT_L(n) asm volatile("s_waitcnt lgkmcnt(" #n ")" ::: "memory")
; #define PG8_BAR __builtin_amdgcn_s_barrier()
; #define PG8_SCHED __builtin_amdgcn_sched_barrier(0)
; template <class Epi>
; __device__ __forceinline__ void gemm_phase(LAS unsigned char* lds, const Gemm g, const StaticOrder& S, const Epi& E, const int tid) {
;     ...
;             PG8_WAIT_V(8); PG8_WAIT_L(0); PG8_BAR; PG8_MMA(1, 0, At, B0); PG8_MMA(1, 1, At, B1); PG8_BAR; PG8_SCHED;
;             PG8_LDB(B0, 1, 0); PG8_LDB(B1, 1, 1); PG8_SCHED; PG8_LDA(At, 1, 0); PG8_STAGE(PG8_SA(0, 1), a2 + hstep, voffA);
;             PG8_WAIT_V(8); PG8_WAIT_L(0); PG8_BAR; PG8_MMA(0, 0, At, B0); PG8_MMA(0, 1, At, B1); PG8_BAR; PG8_SCHED;
	s_setprio 1
	s_waitcnt lgkmcnt(0)
	v_mfma_f32_16x16x32_bf16 v[62:65], v[146:149], v[186:189], v[62:65]
	v_mfma_f32_16x16x32_bf16 v[58:61], v[154:157], v[186:189], v[58:61]
	v_mfma_f32_16x16x32_bf16 v[54:57], v[146:149], v[194:197], v[54:57]
	v_mfma_f32_16x16x32_bf16 v[46:49], v[154:157], v[194:197], v[46:49]
	v_mfma_f32_16x16x32_bf16 v[38:41], v[146:149], v[212:215], v[38:41]
	v_mfma_f32_16x16x32_bf16 v[30:33], v[154:157], v[212:215], v[30:33]
	v_mfma_f32_16x16x32_bf16 v[22:25], v[146:149], v[220:223], v[22:25]
	v_mfma_f32_16x16x32_bf16 v[14:17], v[154:157], v[220:223], v[14:17]
	v_mfma_f32_16x16x32_bf16 v[62:65], v[150:153], v[190:193], v[62:65]
	v_mfma_f32_16x16x32_bf16 v[58:61], v[158:161], v[190:193], v[58:61]
	v_mfma_f32_16x16x32_bf16 v[54:57], v[150:153], v[198:201], v[54:57]
	v_mfma_f32_16x16x32_bf16 v[46:49], v[158:161], v[198:201], v[46:49]
	v_mfma_f32_16x16x32_bf16 v[38:41], v[150:153], v[216:219], v[38:41]
	v_mfma_f32_16x16x32_bf16 v[30:33], v[158:161], v[216:219], v[30:33]
	v_mfma_f32_16x16x32_bf16 v[22:25], v[150:153], v[224:227], v[22:25]
	v_mfma_f32_16x16x32_bf16 v[14:17], v[158:161], v[224:227], v[14:17]
	s_setprio 0
	s_setprio 1
	v_mfma_f32_16x16x32_bf16 v[50:53], v[162:165], v[186:189], v[50:53]
	v_mfma_f32_16x16x32_bf16 v[42:45], v[178:181], v[186:189], v[42:45]
	v_mfma_f32_16x16x32_bf16 v[34:37], v[162:165], v[194:197], v[34:37]
	v_mfma_f32_16x16x32_bf16 v[26:29], v[178:181], v[194:197], v[26:29]
	v_mfma_f32_16x16x32_bf16 v[18:21], v[162:165], v[212:215], v[18:21]
	v_mfma_f32_16x16x32_bf16 v[10:13], v[178:181], v[212:215], v[10:13]
	v_mfma_f32_16x16x32_bf16 v[6:9], v[162:165], v[220:223], v[6:9]
	v_mfma_f32_16x16x32_bf16 v[2:5], v[178:181], v[220:223], v[2:5]
	v_mfma_f32_16x16x32_bf16 v[50:53], v[166:169], v[190:193], v[50:53]
	v_mfma_f32_16x16x32_bf16 v[42:45], v[182:185], v[190:193], v[42:45]
	v_mfma_f32_16x16x32_bf16 v[34:37], v[166:169], v[198:201], v[34:37]
	v_mfma_f32_16x16x32_bf16 v[26:29], v[182:185], v[198:201], v[26:29]
	v_mfma_f32_16x16x32_bf16 v[18:21], v[166:169], v[216:219], v[18:21]
	v_mfma_f32_16x16x32_bf16 v[10:13], v[182:185], v[216:219], v[10:13]
	v_mfma_f32_16x16x32_bf16 v[6:9], v[166:169], v[224:227], v[6:9]
	v_mfma_f32_16x16x32_bf16 v[2:5], v[182:185], v[224:227], v[2:5]
	s_setprio 0
	s_barrier
	s_add_u32 s30, s30, 0x80000
	s_addc_u32 s31, s31, 0
	s_mov_b32 m0, s38
	s_nop 0
	global_load_lds_dwordx4 v130, s[30:31]
	s_mov_b32 m0, s39
	s_nop 0
	global_load_lds_dwordx4 v132, s[30:31]
	s_add_i32 s48, 0, 0x18000
	v_add_u32_e32 v145, s48, v142
	s_add_i32 s49, 0, 0x1c000
	ds_read_b128 v[146:149], v145
	ds_read_b128 v[150:153], v145 offset:1024
	ds_read_b128 v[154:157], v145 offset:2048
	ds_read_b128 v[158:161], v145 offset:3072
	v_add_u32_e32 v145, s49, v142
	ds_read_b128 v[162:165], v145
	ds_read_b128 v[166:169], v145 offset:1024
	ds_read_b128 v[178:181], v145 offset:2048
	ds_read_b128 v[182:185], v145 offset:3072
	ds_read_b128 v[186:189], v144 offset:32768
	ds_read_b128 v[190:193], v144 offset:33792
	ds_read_b128 v[194:197], v144 offset:34816
	ds_read_b128 v[198:201], v144 offset:35840
	ds_read_b128 v[212:215], v144 offset:36864
	ds_read_b128 v[216:219], v144 offset:37888
	ds_read_b128 v[220:223], v144 offset:38912
	ds_read_b128 v[224:227], v144 offset:39936
	s_waitcnt vmcnt(8)
	s_waitcnt lgkmcnt(0)
	s_barrier
	s_setprio 1
	s_waitcnt lgkmcnt(0)
	v_mfma_f32_16x16x32_bf16 v[126:129], v[146:149], v[186:189], v[126:129]
	v_mfma_f32_16x16x32_bf16 v[122:125], v[154:157], v[186:189], v[122:125]
	v_mfma_f32_16x16x32_bf16 v[118:121], v[146:149], v[194:197], v[118:121]
	v_mfma_f32_16x16x32_bf16 v[110:113], v[154:157], v[194:197], v[110:113]
	v_mfma_f32_16x16x32_bf16 v[102:105], v[146:149], v[212:215], v[102:105]
	v_mfma_f32_16x16x32_bf16 v[94:97], v[154:157], v[212:215], v[94:97]
	v_mfma_f32_16x16x32_bf16 v[86:89], v[146:149], v[220:223], v[86:89]
	v_mfma_f32_16x16x32_bf16 v[78:81], v[154:157], v[220:223], v[78:81]
	v_mfma_f32_16x16x32_bf16 v[126:129], v[150:153], v[190:193], v[126:129]
	v_mfma_f32_16x16x32_bf16 v[122:125], v[158:161], v[190:193], v[122:125]
	v_mfma_f32_16x16x32_bf16 v[118:121], v[150:153], v[198:201], v[118:121]
	v_mfma_f32_16x16x32_bf16 v[110:113], v[158:161], v[198:201], v[110:113]
	v_mfma_f32_16x16x32_bf16 v[102:105], v[150:153], v[216:219], v[102:105]
	v_mfma_f32_16x16x32_bf16 v[94:97], v[158:161], v[216:219], v[94:97]
	v_mfma_f32_16x16x32_bf16 v[86:89], v[150:153], v[224:227], v[86:89]
	v_mfma_f32_16x16x32_bf16 v[78:81], v[158:161], v[224:227], v[78:81]
	s_setprio 0
	s_setprio 1
	v_mfma_f32_16x16x32_bf16 v[114:117], v[162:165], v[186:189], v[114:117]
	v_mfma_f32_16x16x32_bf16 v[106:109], v[178:181], v[186:189], v[106:109]
	v_mfma_f32_16x16x32_bf16 v[98:101], v[162:165], v[194:197], v[98:101]
	v_mfma_f32_16x16x32_bf16 v[90:93], v[178:181], v[194:197], v[90:93]
	v_mfma_f32_16x16x32_bf16 v[82:85], v[162:165], v[212:215], v[82:85]
	v_mfma_f32_16x16x32_bf16 v[74:77], v[178:181], v[212:215], v[74:77]
	v_mfma_f32_16x16x32_bf16 v[70:73], v[162:165], v[220:223], v[70:73]
	v_mfma_f32_16x16x32_bf16 v[66:69], v[178:181], v[220:223], v[66:69]
	v_mfma_f32_16x16x32_bf16 v[114:117], v[166:169], v[190:193], v[114:117]
	v_mfma_f32_16x16x32_bf16 v[106:109], v[182:185], v[190:193], v[106:109]
	v_mfma_f32_16x16x32_bf16 v[98:101], v[166:169], v[198:201], v[98:101]
	v_mfma_f32_16x16x32_bf16 v[90:93], v[182:185], v[198:201], v[90:93]
	v_mfma_f32_16x16x32_bf16 v[82:85], v[166:169], v[216:219], v[82:85]
	v_mfma_f32_16x16x32_bf16 v[74:77], v[182:185], v[216:219], v[74:77]
	v_mfma_f32_16x16x32_bf16 v[70:73], v[166:169], v[224:227], v[70:73]
	v_mfma_f32_16x16x32_bf16 v[66:69], v[182:185], v[224:227], v[66:69]
	s_setprio 0
	s_barrier
; #define PG8_STAGE(bufoff, gbase, voff) do { _Pragma("unroll") for (int _i = 0; _i < 2; ++_i) \
;         __builtin_amdgcn_global_load_lds((const unsigned*)((const char*)(gbase) + (voff)[_i]), (LAS unsigned*)(lds + (bufoff) + ldsw + _i * 8192), 16, 0, 0); } while (0)
; #define PG8_LDA(dst, b, h) do { _Pragma("unroll") for (int m = 0; m < 4; ++m) _Pragma("unroll") for (int k = 0; k < 2; ++k) dst[m][k] = *(const LAS bf16x8*)(lds + PG8_SA(b, h) + aoff + m * 2048 + k * 1024); } while (0)
; #define PG8_MMA(ai, bj, At, Bt) do { __builtin_amdgcn_s_setprio(1); _Pragma("unroll") for (int m = 0; m < 4; ++m) _Pragma("unroll") for (int n = 0; n < 2; ++n) _Pragma("unroll") for (int k = 0; k < 2; ++k) \
;         acc[ai][bj][m][n] = __builtin_amdgcn_mfma_f32_16x16x32_bf16(Bt[n][k], At[m][k], acc[ai][bj][m][n], 0, 0, 0); __builtin_amdgcn_s_setprio(0); } while (0)
; #define PG8_WAIT_V(n) asm volatile("s_waitcnt vmcnt(" #n ")" ::: "memory")
; #define PG8_WAIT_L(n) asm volatile("s_waitcnt lgkmcnt(" #n ")" ::: "memory")
; #define PG8_BAR __builtin_amdgcn_s_barrier()
; #define PG8_SCHED __builtin_amdgcn_sched_barrier(0)
; template <class Epi>
; __device__ __forceinline__ void gemm_phase(LAS unsigned char* lds, const Gemm g, const StaticOrder& S, const Epi& E, const int tid) {
;     ...
;             PG8_LDA(At, 1, 1); PG8_STAGE(PG8_SB(1, 0), b3, voffB); PG8_STAGE(PG8_SB(1, 1), b3 + bhs, voffB); PG8_STAGE(PG8_SA(1, 0), a3, voffA);
;             PG8_WAIT_V(8); PG8_WAIT_L(0); PG8_BAR; PG8_MMA(1, 0, At, B0); PG8_MMA(1, 1, At, B1); PG8_BAR; PG8_SCHED;
	s_add_i32 s30, s48, s37
	v_lshl_add_u64 v[172:173], v[172:173], 0, s[70:71]
	s_mov_b32 m0, s30
	ds_read_b128 v[186:189], v144 offset:49152
	global_load_lds_dwordx4 v[172:173], off
	ds_read_b128 v[190:193], v144 offset:50176
	ds_read_b128 v[194:197], v144 offset:51200
	s_add_i32 m0, s30, 0x2000
	s_add_u32 s28, s28, 0x8080
	v_lshl_add_u64 v[172:173], v[174:175], 0, s[70:71]
	s_addc_u32 s29, s29, 0
	s_add_i32 s30, s49, s37
	global_load_lds_dwordx4 v[172:173], off
	ds_read_b128 v[198:201], v144 offset:52224
	ds_read_b128 v[212:215], v144 offset:53248
	v_lshl_add_u64 v[172:173], s[28:29], 0, v[0:1]
	s_mov_b32 m0, s30
	s_nop 0
	global_load_lds_dwordx4 v[172:173], off
	ds_read_b128 v[216:219], v144 offset:54272
	ds_read_b128 v[220:223], v144 offset:55296
	v_lshl_add_u64 v[172:173], s[28:29], 0, v[134:135]
	s_add_i32 m0, s30, 0x2000
	s_nop 0
	global_load_lds_dwordx4 v[172:173], off
	ds_read_b128 v[224:227], v144 offset:56320
	v_lshl_add_u64 v[172:173], v[176:177], 0, s[70:71]
	s_mov_b32 m0, s40
	s_nop 0
	global_load_lds_dwordx4 v[172:173], off
	v_lshl_add_u64 v[172:173], v[228:229], 0, s[70:71]
	s_mov_b32 m0, s41
	s_nop 0
	global_load_lds_dwordx4 v[172:173], off
	s_waitcnt vmcnt(8)
	s_waitcnt lgkmcnt(0)
	s_barrier
	s_setprio 1
	s_waitcnt lgkmcnt(0)
	v_mfma_f32_16x16x32_bf16 v[62:65], v[146:149], v[186:189], v[62:65]
	v_mfma_f32_16x16x32_bf16 v[58:61], v[154:157], v[186:189], v[58:61]
	v_mfma_f32_16x16x32_bf16 v[54:57], v[146:149], v[194:197], v[54:57]
	v_mfma_f32_16x16x32_bf16 v[46:49], v[154:157], v[194:197], v[46:49]
	v_mfma_f32_16x16x32_bf16 v[38:41], v[146:149], v[212:215], v[38:41]
	v_mfma_f32_16x16x32_bf16 v[30:33], v[154:157], v[212:215], v[30:33]
	v_mfma_f32_16x16x32_bf16 v[22:25], v[146:149], v[220:223], v[22:25]
	v_mfma_f32_16x16x32_bf16 v[14:17], v[154:157], v[220:223], v[14:17]
	v_mfma_f32_16x16x32_bf16 v[62:65], v[150:153], v[190:193], v[62:65]
	v_mfma_f32_16x16x32_bf16 v[58:61], v[158:161], v[190:193], v[58:61]
	v_mfma_f32_16x16x32_bf16 v[54:57], v[150:153], v[198:201], v[54:57]
	v_mfma_f32_16x16x32_bf16 v[46:49], v[158:161], v[198:201], v[46:49]
	v_mfma_f32_16x16x32_bf16 v[38:41], v[150:153], v[216:219], v[38:41]
	v_mfma_f32_16x16x32_bf16 v[30:33], v[158:161], v[216:219], v[30:33]
	v_mfma_f32_16x16x32_bf16 v[22:25], v[150:153], v[224:227], v[22:25]
	v_mfma_f32_16x16x32_bf16 v[14:17], v[158:161], v[224:227], v[14:17]
	s_setprio 0
	s_setprio 1
	v_mfma_f32_16x16x32_bf16 v[50:53], v[162:165], v[186:189], v[50:53]
	v_mfma_f32_16x16x32_bf16 v[42:45], v[178:181], v[186:189], v[42:45]
	v_mfma_f32_16x16x32_bf16 v[34:37], v[162:165], v[194:197], v[34:37]
	v_mfma_f32_16x16x32_bf16 v[26:29], v[178:181], v[194:197], v[26:29]
	v_mfma_f32_16x16x32_bf16 v[18:21], v[162:165], v[212:215], v[18:21]
	v_mfma_f32_16x16x32_bf16 v[10:13], v[178:181], v[212:215], v[10:13]
	v_mfma_f32_16x16x32_bf16 v[6:9], v[162:165], v[220:223], v[6:9]
	v_mfma_f32_16x16x32_bf16 v[2:5], v[178:181], v[220:223], v[2:5]
	v_mfma_f32_16x16x32_bf16 v[50:53], v[166:169], v[190:193], v[50:53]
	v_mfma_f32_16x16x32_bf16 v[42:45], v[182:185], v[190:193], v[42:45]
	v_mfma_f32_16x16x32_bf16 v[34:37], v[166:169], v[198:201], v[34:37]
	v_mfma_f32_16x16x32_bf16 v[26:29], v[182:185], v[198:201], v[26:29]
	v_mfma_f32_16x16x32_bf16 v[18:21], v[166:169], v[216:219], v[18:21]
	v_mfma_f32_16x16x32_bf16 v[10:13], v[182:185], v[216:219], v[10:13]
	v_mfma_f32_16x16x32_bf16 v[6:9], v[166:169], v[224:227], v[6:9]
	v_mfma_f32_16x16x32_bf16 v[2:5], v[182:185], v[224:227], v[2:5]
	s_setprio 0
	s_barrier
	s_add_i32 s47, s47, 2
	s_add_u32 s45, s45, 0x100
	s_addc_u32 s46, s46, 0
	s_add_u32 s26, s26, 0x100
	s_addc_u32 s27, s27, 0
	s_cmp_gt_u32 s47, 29
	s_cbranch_scc0 .LBB0_844
	s_and_b64 vcc, exec, s[10:11]
	s_cbranch_vccz .LBB0_847
	s_barrier

; #define PG8_STAGE(bufoff, gbase, voff) do { _Pragma("unroll") for (int _i = 0; _i < 2; ++_i) \
;         __builtin_amdgcn_global_load_lds((const unsigned*)((const char*)(gbase) + (voff)[_i]), (LAS unsigned*)(lds + (bufoff) + ldsw + _i * 8192), 16, 0, 0); } while (0)
; #define PG8_LDA(dst, b, h) do { _Pragma("unroll") for (int m = 0; m < 4; ++m) _Pragma("unroll") for (int k = 0; k < 2; ++k) dst[m][k] = *(const LAS bf16x8*)(lds + PG8_SA(b, h) + aoff + m * 2048 + k * 1024); } while (0)
; #define PG8_LDB(dst, b, h) do { _Pragma("unroll") for (int n = 0; n < 2; ++n) _Pragma("unroll") for (int k = 0; k < 2; ++k) dst[n][k] = *(const LAS bf16x8*)(lds + PG8_SB(b, h) + boff + n * 2048 + k * 1024); } while (0)
; #define PG8_MMA(ai, bj, At, Bt) do { __builtin_amdgcn_s_setprio(1); _Pragma("unroll") for (int m = 0; m < 4; ++m) _Pragma("unroll") for (int n = 0; n < 2; ++n) _Pragma("unroll") for (int k = 0; k < 2; ++k) \
;         acc[ai][bj][m][n] = __builtin_amdgcn_mfma_f32_16x16x32_bf16(Bt[n][k], At[m][k], acc[ai][bj][m][n], 0, 0, 0); __builtin_amdgcn_s_setprio(0); } while (0)
; #define PG8_WAIT_V(n) asm volatile("s_waitcnt vmcnt(" #n ")" ::: "memory")
; #define PG8_WAIT_L(n) asm volatile("s_waitcnt lgkmcnt(" #n ")" ::: "memory")
; #define PG8_BAR __builtin_amdgcn_s_barrier()
; #define PG8_SCHED __builtin_amdgcn_sched_barrier(0)
; template <class Epi>
; __device__ __forceinline__ void gemm_phase(LAS unsigned char* lds, const Gemm g, const StaticOrder& S, const Epi& E, const int tid) {
;     ...
;             PG8_LDB(B0, 0, 0); PG8_LDB(B1, 0, 1); PG8_SCHED; PG8_LDA(At, 0, 0); PG8_STAGE(PG8_SA(1, 1), a1 + hstep, voffA);
;             PG8_WAIT_V(8); PG8_WAIT_L(0); PG8_BAR; PG8_MMA(0, 0, At, B0); PG8_MMA(0, 1, At, B1); PG8_BAR; PG8_SCHED;
;             PG8_LDA(At, 0, 1); PG8_STAGE(PG8_SB(0, 0), b2, voffB); PG8_STAGE(PG8_SB(0, 1), b2 + bhs, voffB); PG8_STAGE(PG8_SA(0, 0), a2, voffA);
;             PG8_WAIT_V(8); PG8_WAIT_L(0); PG8_BAR; PG8_MMA(1, 0, At, B0); PG8_MMA(1, 1, At, B1); PG8_BAR; PG8_SCHED;
.LBB0_861:
	s_add_i32 m0, s25, 0xc000
	s_nop 0
	global_load_lds_dwordx4 v138, s[28:29]
	s_add_i32 m0, s25, 0xe000
	s_nop 0
	global_load_lds_dwordx4 v136, s[28:29]
	s_add_u32 s30, s28, 0xfff80080
	s_addc_u32 s31, s29, -1
	s_add_i32 s51, 0, 0x10000
	s_cmp_eq_u32 s50, 28
	s_cselect_b32 s35, s17, s31
	s_cselect_b32 s34, s46, s30
	v_add_u32_e32 v145, s51, v142
	s_cselect_b32 s31, s15, s49
	s_cselect_b32 s30, s47, s48
	s_add_i32 s54, 0, 0x14000
	ds_read_b128 v[146:149], v145
	ds_read_b128 v[150:153], v145 offset:1024
	ds_read_b128 v[154:157], v145 offset:2048
	ds_read_b128 v[158:161], v145 offset:3072
	v_add_u32_e32 v145, s54, v142
	ds_read_b128 v[162:165], v145
	ds_read_b128 v[166:169], v145 offset:1024
	ds_read_b128 v[178:181], v145 offset:2048
	ds_read_b128 v[182:185], v145 offset:3072
	ds_read_b128 v[186:189], v144
	ds_read_b128 v[190:193], v144 offset:1024
	ds_read_b128 v[194:197], v144 offset:2048
	ds_read_b128 v[198:201], v144 offset:3072
	ds_read_b128 v[212:215], v144 offset:4096
	ds_read_b128 v[216:219], v144 offset:5120
	ds_read_b128 v[220:223], v144 offset:6144
	ds_read_b128 v[224:227], v144 offset:7168
	s_waitcnt vmcnt(8)
	s_waitcnt lgkmcnt(0)
	s_barrier
	s_setprio 1
	s_waitcnt lgkmcnt(0)
	v_mfma_f32_16x16x32_bf16 v[126:129], v[146:149], v[186:189], v[126:129]
	v_mfma_f32_16x16x32_bf16 v[122:125], v[154:157], v[186:189], v[122:125]
	v_mfma_f32_16x16x32_bf16 v[118:121], v[146:149], v[194:197], v[118:121]
	v_mfma_f32_16x16x32_bf16 v[110:113], v[154:157], v[194:197], v[110:113]
	v_mfma_f32_16x16x32_bf16 v[102:105], v[146:149], v[212:215], v[102:105]
	v_mfma_f32_16x16x32_bf16 v[94:97], v[154:157], v[212:215], v[94:97]
	v_mfma_f32_16x16x32_bf16 v[86:89], v[146:149], v[220:223], v[86:89]
	v_mfma_f32_16x16x32_bf16 v[78:81], v[154:157], v[220:223], v[78:81]
	v_mfma_f32_16x16x32_bf16 v[126:129], v[150:153], v[190:193], v[126:129]
	v_mfma_f32_16x16x32_bf16 v[122:125], v[158:161], v[190:193], v[122:125]
	v_mfma_f32_16x16x32_bf16 v[118:121], v[150:153], v[198:201], v[118:121]
	v_mfma_f32_16x16x32_bf16 v[110:113], v[158:161], v[198:201], v[110:113]
	v_mfma_f32_16x16x32_bf16 v[102:105], v[150:153], v[216:219], v[102:105]
	v_mfma_f32_16x16x32_bf16 v[94:97], v[158:161], v[216:219], v[94:97]
	v_mfma_f32_16x16x32_bf16 v[86:89], v[150:153], v[224:227], v[86:89]
	v_mfma_f32_16x16x32_bf16 v[78:81], v[158:161], v[224:227], v[78:81]
	s_setprio 0
	s_setprio 1
	v_mfma_f32_16x16x32_bf16 v[114:117], v[162:165], v[186:189], v[114:117]
	v_mfma_f32_16x16x32_bf16 v[106:109], v[178:181], v[186:189], v[106:109]
	v_mfma_f32_16x16x32_bf16 v[98:101], v[162:165], v[194:197], v[98:101]
	v_mfma_f32_16x16x32_bf16 v[90:93], v[178:181], v[194:197], v[90:93]
	v_mfma_f32_16x16x32_bf16 v[82:85], v[162:165], v[212:215], v[82:85]
	v_mfma_f32_16x16x32_bf16 v[74:77], v[178:181], v[212:215], v[74:77]
	v_mfma_f32_16x16x32_bf16 v[70:73], v[162:165], v[220:223], v[70:73]
	v_mfma_f32_16x16x32_bf16 v[66:69], v[178:181], v[220:223], v[66:69]
	v_mfma_f32_16x16x32_bf16 v[114:117], v[166:169], v[190:193], v[114:117]
	v_mfma_f32_16x16x32_bf16 v[106:109], v[182:185], v[190:193], v[106:109]
	v_mfma_f32_16x16x32_bf16 v[98:101], v[166:169], v[198:201], v[98:101]
	v_mfma_f32_16x16x32_bf16 v[90:93], v[182:185], v[198:201], v[90:93]
	v_mfma_f32_16x16x32_bf16 v[82:85], v[166:169], v[216:219], v[82:85]
	v_mfma_f32_16x16x32_bf16 v[74:77], v[182:185], v[216:219], v[74:77]
	v_mfma_f32_16x16x32_bf16 v[70:73], v[166:169], v[224:227], v[70:73]
	v_mfma_f32_16x16x32_bf16 v[66:69], v[182:185], v[224:227], v[66:69]
	s_setprio 0
	s_barrier
	s_add_i32 s51, s51, s40
	v_lshl_add_u64 v[172:173], s[30:31], 0, v[0:1]
	s_mov_b32 m0, s51
	ds_read_b128 v[186:189], v144 offset:16384
	global_load_lds_dwordx4 v[172:173], off
	ds_read_b128 v[190:193], v144 offset:17408
	ds_read_b128 v[194:197], v144 offset:18432
	s_add_i32 m0, s51, 0x2000
	s_add_u32 s52, s30, 0x8000
	v_lshl_add_u64 v[174:175], s[30:31], 0, v[134:135]
	s_addc_u32 s53, s31, 0
	s_add_i32 s51, s54, s40
	global_load_lds_dwordx4 v[174:175], off
	ds_read_b128 v[198:201], v144 offset:19456
	ds_read_b128 v[212:215], v144 offset:20480
	v_lshl_add_u64 v[176:177], s[52:53], 0, v[0:1]
	s_mov_b32 m0, s51
	v_lshl_add_u64 v[228:229], s[34:35], 0, v[132:133]
	global_load_lds_dwordx4 v[176:177], off
	ds_read_b128 v[216:219], v144 offset:21504
	ds_read_b128 v[220:223], v144 offset:22528
	v_lshl_add_u64 v[176:177], s[52:53], 0, v[134:135]
	s_add_i32 m0, s51, 0x2000
	s_nop 0
	global_load_lds_dwordx4 v[176:177], off
	ds_read_b128 v[224:227], v144 offset:23552
	v_lshl_add_u64 v[176:177], s[34:35], 0, v[130:131]
	s_mov_b32 m0, s25
	s_nop 0
	global_load_lds_dwordx4 v[176:177], off
	s_mov_b32 m0, s27
	s_nop 0
	global_load_lds_dwordx4 v[228:229], off
	s_waitcnt vmcnt(8)
	s_waitcnt lgkmcnt(0)
	s_barrier
; #define PG8_STAGE(bufoff, gbase, voff) do { _Pragma("unroll") for (int _i = 0; _i < 2; ++_i) \
;         __builtin_amdgcn_global_load_lds((const unsigned*)((const char*)(gbase) + (voff)[_i]), (LAS unsigned*)(lds + (bufoff) + ldsw + _i * 8192), 16, 0, 0); } while (0)
; #define PG8_LDA(dst, b, h) do { _Pragma("unroll") for (int m = 0; m < 4; ++m) _Pragma("unroll") for (int k = 0; k < 2; ++k) dst[m][k] = *(const LAS bf16x8*)(lds + PG8_SA(b, h) + aoff + m * 2048 + k * 1024); } while (0)
; #define PG8_LDB(dst, b, h) do { _Pragma("unroll") for (int n = 0; n < 2; ++n) _Pragma("unroll") for (int k = 0; k < 2; ++k) dst[n][k] = *(const LAS bf16x8*)(lds + PG8_SB(b, h) + boff + n * 2048 + k * 1024); } while (0)
; #define PG8_MMA(ai, bj, At, Bt) do { __builtin_amdgcn_s_setprio(1); _Pragma("unroll") for (int m = 0; m < 4; ++m) _Pragma("unroll") for (int n = 0; n < 2; ++n) _Pragma("unroll") for (int k = 0; k < 2; ++k) \
;         acc[ai][bj][m][n] = __builtin_amdgcn_mfma_f32_16x16x32_bf16(Bt[n][k], At[m][k], acc[ai][bj][m][n], 0, 0, 0); __builtin_amdgcn_s_setprio(0); } while (0)
; #define PG8_WAIT_V(n) asm volatile("s_waitcnt vmcnt(" #n ")" ::: "memory")
; #define PG8_WAIT_L(n) asm volatile("s_waitcnt lgkmcnt(" #n ")" ::: "memory")
; #define PG8_BAR __builtin_amdgcn_s_barrier()
; #define PG8_SCHED __builtin_amdgcn_sched_barrier(0)
; template <class Epi>
; __device__ __forceinline__ void gemm_phase(LAS unsigned char* lds, const Gemm g, const StaticOrder& S, const Epi& E, const int tid) {
;     ...
;             PG8_WAIT_V(8); PG8_WAIT_L(0); PG8_BAR; PG8_MMA(1, 0, At, B0); PG8_MMA(1, 1, At, B1); PG8_BAR; PG8_SCHED;
;             PG8_LDB(B0, 1, 0); PG8_LDB(B1, 1, 1); PG8_SCHED; PG8_LDA(At, 1, 0); PG8_STAGE(PG8_SA(0, 1), a2 + hstep, voffA);
;             PG8_WAIT_V(8); PG8_WAIT_L(0); PG8_BAR; PG8_MMA(0, 0, At, B0); PG8_MMA(0, 1, At, B1); PG8_BAR; PG8_SCHED;
	s_setprio 1
	s_waitcnt lgkmcnt(0)
	v_mfma_f32_16x16x32_bf16 v[62:65], v[146:149], v[186:189], v[62:65]
	v_mfma_f32_16x16x32_bf16 v[58:61], v[154:157], v[186:189], v[58:61]
	v_mfma_f32_16x16x32_bf16 v[54:57], v[146:149], v[194:197], v[54:57]
	v_mfma_f32_16x16x32_bf16 v[46:49], v[154:157], v[194:197], v[46:49]
	v_mfma_f32_16x16x32_bf16 v[38:41], v[146:149], v[212:215], v[38:41]
	v_mfma_f32_16x16x32_bf16 v[30:33], v[154:157], v[212:215], v[30:33]
	v_mfma_f32_16x16x32_bf16 v[22:25], v[146:149], v[220:223], v[22:25]
	v_mfma_f32_16x16x32_bf16 v[14:17], v[154:157], v[220:223], v[14:17]
	v_mfma_f32_16x16x32_bf16 v[62:65], v[150:153], v[190:193], v[62:65]
	v_mfma_f32_16x16x32_bf16 v[58:61], v[158:161], v[190:193], v[58:61]
	v_mfma_f32_16x16x32_bf16 v[54:57], v[150:153], v[198:201], v[54:57]
	v_mfma_f32_16x16x32_bf16 v[46:49], v[158:161], v[198:201], v[46:49]
	v_mfma_f32_16x16x32_bf16 v[38:41], v[150:153], v[216:219], v[38:41]
	v_mfma_f32_16x16x32_bf16 v[30:33], v[158:161], v[216:219], v[30:33]
	v_mfma_f32_16x16x32_bf16 v[22:25], v[150:153], v[224:227], v[22:25]
	v_mfma_f32_16x16x32_bf16 v[14:17], v[158:161], v[224:227], v[14:17]
	s_setprio 0
	s_setprio 1
	v_mfma_f32_16x16x32_bf16 v[50:53], v[162:165], v[186:189], v[50:53]
	v_mfma_f32_16x16x32_bf16 v[42:45], v[178:181], v[186:189], v[42:45]
	v_mfma_f32_16x16x32_bf16 v[34:37], v[162:165], v[194:197], v[34:37]
	v_mfma_f32_16x16x32_bf16 v[26:29], v[178:181], v[194:197], v[26:29]
	v_mfma_f32_16x16x32_bf16 v[18:21], v[162:165], v[212:215], v[18:21]
	v_mfma_f32_16x16x32_bf16 v[10:13], v[178:181], v[212:215], v[10:13]
	v_mfma_f32_16x16x32_bf16 v[6:9], v[162:165], v[220:223], v[6:9]
	v_mfma_f32_16x16x32_bf16 v[2:5], v[178:181], v[220:223], v[2:5]
	v_mfma_f32_16x16x32_bf16 v[50:53], v[166:169], v[190:193], v[50:53]
	v_mfma_f32_16x16x32_bf16 v[42:45], v[182:185], v[190:193], v[42:45]
	v_mfma_f32_16x16x32_bf16 v[34:37], v[166:169], v[198:201], v[34:37]
	v_mfma_f32_16x16x32_bf16 v[26:29], v[182:185], v[198:201], v[26:29]
	v_mfma_f32_16x16x32_bf16 v[18:21], v[166:169], v[216:219], v[18:21]
	v_mfma_f32_16x16x32_bf16 v[10:13], v[182:185], v[216:219], v[10:13]
	v_mfma_f32_16x16x32_bf16 v[6:9], v[166:169], v[224:227], v[6:9]
	v_mfma_f32_16x16x32_bf16 v[2:5], v[182:185], v[224:227], v[2:5]
	s_setprio 0
	s_barrier
	s_add_u32 s34, s34, 0x80000
	s_addc_u32 s35, s35, 0
	s_mov_b32 m0, s41
	s_nop 0
	global_load_lds_dwordx4 v130, s[34:35]
	s_mov_b32 m0, s42
	s_nop 0
	global_load_lds_dwordx4 v132, s[34:35]
	s_add_i32 s51, 0, 0x18000
	v_add_u32_e32 v145, s51, v142
	s_add_i32 s52, 0, 0x1c000
	ds_read_b128 v[146:149], v145
	ds_read_b128 v[150:153], v145 offset:1024
	ds_read_b128 v[154:157], v145 offset:2048
	ds_read_b128 v[158:161], v145 offset:3072
	v_add_u32_e32 v145, s52, v142
	ds_read_b128 v[162:165], v145
	ds_read_b128 v[166:169], v145 offset:1024
	ds_read_b128 v[178:181], v145 offset:2048
	ds_read_b128 v[182:185], v145 offset:3072
	ds_read_b128 v[186:189], v144 offset:32768
	ds_read_b128 v[190:193], v144 offset:33792
	ds_read_b128 v[194:197], v144 offset:34816
	ds_read_b128 v[198:201], v144 offset:35840
	ds_read_b128 v[212:215], v144 offset:36864
	ds_read_b128 v[216:219], v144 offset:37888
	ds_read_b128 v[220:223], v144 offset:38912
	ds_read_b128 v[224:227], v144 offset:39936
	s_waitcnt vmcnt(8)
	s_waitcnt lgkmcnt(0)
	s_barrier
	s_setprio 1
	s_waitcnt lgkmcnt(0)
	v_mfma_f32_16x16x32_bf16 v[126:129], v[146:149], v[186:189], v[126:129]
	v_mfma_f32_16x16x32_bf16 v[122:125], v[154:157], v[186:189], v[122:125]
	v_mfma_f32_16x16x32_bf16 v[118:121], v[146:149], v[194:197], v[118:121]
	v_mfma_f32_16x16x32_bf16 v[110:113], v[154:157], v[194:197], v[110:113]
	v_mfma_f32_16x16x32_bf16 v[102:105], v[146:149], v[212:215], v[102:105]
	v_mfma_f32_16x16x32_bf16 v[94:97], v[154:157], v[212:215], v[94:97]
	v_mfma_f32_16x16x32_bf16 v[86:89], v[146:149], v[220:223], v[86:89]
	v_mfma_f32_16x16x32_bf16 v[78:81], v[154:157], v[220:223], v[78:81]
	v_mfma_f32_16x16x32_bf16 v[126:129], v[150:153], v[190:193], v[126:129]
	v_mfma_f32_16x16x32_bf16 v[122:125], v[158:161], v[190:193], v[122:125]
	v_mfma_f32_16x16x32_bf16 v[118:121], v[150:153], v[198:201], v[118:121]
	v_mfma_f32_16x16x32_bf16 v[110:113], v[158:161], v[198:201], v[110:113]
	v_mfma_f32_16x16x32_bf16 v[102:105], v[150:153], v[216:219], v[102:105]
	v_mfma_f32_16x16x32_bf16 v[94:97], v[158:161], v[216:219], v[94:97]
	v_mfma_f32_16x16x32_bf16 v[86:89], v[150:153], v[224:227], v[86:89]
	v_mfma_f32_16x16x32_bf16 v[78:81], v[158:161], v[224:227], v[78:81]
	s_setprio 0
	s_setprio 1
	v_mfma_f32_16x16x32_bf16 v[114:117], v[162:165], v[186:189], v[114:117]
	v_mfma_f32_16x16x32_bf16 v[106:109], v[178:181], v[186:189], v[106:109]
	v_mfma_f32_16x16x32_bf16 v[98:101], v[162:165], v[194:197], v[98:101]
	v_mfma_f32_16x16x32_bf16 v[90:93], v[178:181], v[194:197], v[90:93]
	v_mfma_f32_16x16x32_bf16 v[82:85], v[162:165], v[212:215], v[82:85]
	v_mfma_f32_16x16x32_bf16 v[74:77], v[178:181], v[212:215], v[74:77]
	v_mfma_f32_16x16x32_bf16 v[70:73], v[162:165], v[220:223], v[70:73]
	v_mfma_f32_16x16x32_bf16 v[66:69], v[178:181], v[220:223], v[66:69]
	v_mfma_f32_16x16x32_bf16 v[114:117], v[166:169], v[190:193], v[114:117]
	v_mfma_f32_16x16x32_bf16 v[106:109], v[182:185], v[190:193], v[106:109]
	v_mfma_f32_16x16x32_bf16 v[98:101], v[166:169], v[198:201], v[98:101]
	v_mfma_f32_16x16x32_bf16 v[90:93], v[182:185], v[198:201], v[90:93]
	v_mfma_f32_16x16x32_bf16 v[82:85], v[166:169], v[216:219], v[82:85]
	v_mfma_f32_16x16x32_bf16 v[74:77], v[182:185], v[216:219], v[74:77]
	v_mfma_f32_16x16x32_bf16 v[70:73], v[166:169], v[224:227], v[70:73]
	v_mfma_f32_16x16x32_bf16 v[66:69], v[182:185], v[224:227], v[66:69]
	s_setprio 0
	s_barrier
; #define PG8_STAGE(bufoff, gbase, voff) do { _Pragma("unroll") for (int _i = 0; _i < 2; ++_i) \
;         __builtin_amdgcn_global_load_lds((const unsigned*)((const char*)(gbase) + (voff)[_i]), (LAS unsigned*)(lds + (bufoff) + ldsw + _i * 8192), 16, 0, 0); } while (0)
; #define PG8_LDA(dst, b, h) do { _Pragma("unroll") for (int m = 0; m < 4; ++m) _Pragma("unroll") for (int k = 0; k < 2; ++k) dst[m][k] = *(const LAS bf16x8*)(lds + PG8_SA(b, h) + aoff + m * 2048 + k * 1024); } while (0)
; #define PG8_MMA(ai, bj, At, Bt) do { __builtin_amdgcn_s_setprio(1); _Pragma("unroll") for (int m = 0; m < 4; ++m) _Pragma("unroll") for (int n = 0; n < 2; ++n) _Pragma("unroll") for (int k = 0; k < 2; ++k) \
;         acc[ai][bj][m][n] = __builtin_amdgcn_mfma_f32_16x16x32_bf16(Bt[n][k], At[m][k], acc[ai][bj][m][n], 0, 0, 0); __builtin_amdgcn_s_setprio(0); } while (0)
; #define PG8_WAIT_V(n) asm volatile("s_waitcnt vmcnt(" #n ")" ::: "memory")
; #define PG8_WAIT_L(n) asm volatile("s_waitcnt lgkmcnt(" #n ")" ::: "memory")
; #define PG8_BAR __builtin_amdgcn_s_barrier()
; #define PG8_SCHED __builtin_amdgcn_sched_barrier(0)
; template <class Epi>
; __device__ __forceinline__ void gemm_phase(LAS unsigned char* lds, const Gemm g, const StaticOrder& S, const Epi& E, const int tid) {
;     ...
;             PG8_LDA(At, 1, 1); PG8_STAGE(PG8_SB(1, 0), b3, voffB); PG8_STAGE(PG8_SB(1, 1), b3 + bhs, voffB); PG8_STAGE(PG8_SA(1, 0), a3, voffA);
;             PG8_WAIT_V(8); PG8_WAIT_L(0); PG8_BAR; PG8_MMA(1, 0, At, B0); PG8_MMA(1, 1, At, B1); PG8_BAR; PG8_SCHED;
	s_add_i32 s34, s51, s40
	v_lshl_add_u64 v[172:173], v[172:173], 0, s[70:71]
	s_mov_b32 m0, s34
	ds_read_b128 v[186:189], v144 offset:49152
	global_load_lds_dwordx4 v[172:173], off
	ds_read_b128 v[190:193], v144 offset:50176
	ds_read_b128 v[194:197], v144 offset:51200
	s_add_i32 m0, s34, 0x2000
	s_add_u32 s30, s30, 0x8080
	v_lshl_add_u64 v[172:173], v[174:175], 0, s[70:71]
	s_addc_u32 s31, s31, 0
	s_add_i32 s34, s52, s40
	global_load_lds_dwordx4 v[172:173], off
	ds_read_b128 v[198:201], v144 offset:52224
	ds_read_b128 v[212:215], v144 offset:53248
	v_lshl_add_u64 v[172:173], s[30:31], 0, v[0:1]
	s_mov_b32 m0, s34
	s_nop 0
	global_load_lds_dwordx4 v[172:173], off
	ds_read_b128 v[216:219], v144 offset:54272
	ds_read_b128 v[220:223], v144 offset:55296
	v_lshl_add_u64 v[172:173], s[30:31], 0, v[134:135]
	s_add_i32 m0, s34, 0x2000
	s_nop 0
	global_load_lds_dwordx4 v[172:173], off
	ds_read_b128 v[224:227], v144 offset:56320
	v_lshl_add_u64 v[172:173], v[176:177], 0, s[70:71]
	s_mov_b32 m0, s43
	s_nop 0
	global_load_lds_dwordx4 v[172:173], off
	v_lshl_add_u64 v[172:173], v[228:229], 0, s[70:71]
	s_mov_b32 m0, s44
	s_nop 0
	global_load_lds_dwordx4 v[172:173], off
	s_waitcnt vmcnt(8)
	s_waitcnt lgkmcnt(0)
	s_barrier
	s_setprio 1
	s_waitcnt lgkmcnt(0)
	v_mfma_f32_16x16x32_bf16 v[62:65], v[146:149], v[186:189], v[62:65]
	v_mfma_f32_16x16x32_bf16 v[58:61], v[154:157], v[186:189], v[58:61]
	v_mfma_f32_16x16x32_bf16 v[54:57], v[146:149], v[194:197], v[54:57]
	v_mfma_f32_16x16x32_bf16 v[46:49], v[154:157], v[194:197], v[46:49]
	v_mfma_f32_16x16x32_bf16 v[38:41], v[146:149], v[212:215], v[38:41]
	v_mfma_f32_16x16x32_bf16 v[30:33], v[154:157], v[212:215], v[30:33]
	v_mfma_f32_16x16x32_bf16 v[22:25], v[146:149], v[220:223], v[22:25]
	v_mfma_f32_16x16x32_bf16 v[14:17], v[154:157], v[220:223], v[14:17]
	v_mfma_f32_16x16x32_bf16 v[62:65], v[150:153], v[190:193], v[62:65]
	v_mfma_f32_16x16x32_bf16 v[58:61], v[158:161], v[190:193], v[58:61]
	v_mfma_f32_16x16x32_bf16 v[54:57], v[150:153], v[198:201], v[54:57]
	v_mfma_f32_16x16x32_bf16 v[46:49], v[158:161], v[198:201], v[46:49]
	v_mfma_f32_16x16x32_bf16 v[38:41], v[150:153], v[216:219], v[38:41]
	v_mfma_f32_16x16x32_bf16 v[30:33], v[158:161], v[216:219], v[30:33]
	v_mfma_f32_16x16x32_bf16 v[22:25], v[150:153], v[224:227], v[22:25]
	v_mfma_f32_16x16x32_bf16 v[14:17], v[158:161], v[224:227], v[14:17]
	s_setprio 0
	s_setprio 1
	v_mfma_f32_16x16x32_bf16 v[50:53], v[162:165], v[186:189], v[50:53]
	v_mfma_f32_16x16x32_bf16 v[42:45], v[178:181], v[186:189], v[42:45]
	v_mfma_f32_16x16x32_bf16 v[34:37], v[162:165], v[194:197], v[34:37]
	v_mfma_f32_16x16x32_bf16 v[26:29], v[178:181], v[194:197], v[26:29]
	v_mfma_f32_16x16x32_bf16 v[18:21], v[162:165], v[212:215], v[18:21]
	v_mfma_f32_16x16x32_bf16 v[10:13], v[178:181], v[212:215], v[10:13]
	v_mfma_f32_16x16x32_bf16 v[6:9], v[162:165], v[220:223], v[6:9]
	v_mfma_f32_16x16x32_bf16 v[2:5], v[178:181], v[220:223], v[2:5]
	v_mfma_f32_16x16x32_bf16 v[50:53], v[166:169], v[190:193], v[50:53]
	v_mfma_f32_16x16x32_bf16 v[42:45], v[182:185], v[190:193], v[42:45]
	v_mfma_f32_16x16x32_bf16 v[34:37], v[166:169], v[198:201], v[34:37]
	v_mfma_f32_16x16x32_bf16 v[26:29], v[182:185], v[198:201], v[26:29]
	v_mfma_f32_16x16x32_bf16 v[18:21], v[166:169], v[216:219], v[18:21]
	v_mfma_f32_16x16x32_bf16 v[10:13], v[182:185], v[216:219], v[10:13]
	v_mfma_f32_16x16x32_bf16 v[6:9], v[166:169], v[224:227], v[6:9]
	v_mfma_f32_16x16x32_bf16 v[2:5], v[182:185], v[224:227], v[2:5]
	s_setprio 0
	s_barrier
	s_add_i32 s50, s50, 2
	s_add_u32 s48, s48, 0x100
	s_addc_u32 s49, s49, 0
	s_add_u32 s28, s28, 0x100
	s_addc_u32 s29, s29, 0
	s_cmp_gt_u32 s50, 29
	s_cbranch_scc0 .LBB0_861
	s_and_b64 vcc, exec, s[12:13]
	s_cbranch_vccz .LBB0_864
	s_barrier
